# mfmasnake: MFMAs inside each 8-MFMA half-group of the 9 GEMM K-loops reordered so consecutive MFMAs share a source fragment (bit-identical)
# speedup vs baseline: 1.0044x; 1.0044x over previous
; #define PG8_STAGE(bufoff, gbase, voff) do { _Pragma("unroll") for (int _i = 0; _i < 2; ++_i) \
;         __builtin_amdgcn_global_load_lds((const unsigned*)((const char*)(gbase) + (voff)[_i]), (PG8_LAS unsigned*)(lds + (bufoff) + ldsw + _i * 8192), 16, 0, 0); } while (0)
; #define PG8_LDA(dst, b, h) do { _Pragma("unroll") for (int m = 0; m < 4; ++m) _Pragma("unroll") for (int k = 0; k < 2; ++k) dst[m][k] = *(const PG8_LAS bf16x8*)(lds + PG8_SA(b, h) + aoff + m * 2048 + k * 1024); } while (0)
; #define PG8_LDB(dst, b, h) do { _Pragma("unroll") for (int n = 0; n < 2; ++n) _Pragma("unroll") for (int k = 0; k < 2; ++k) dst[n][k] = *(const PG8_LAS bf16x8*)(lds + PG8_SB(b, h) + boff + n * 2048 + k * 1024); } while (0)
; #define PG8_MMA(ai, bj, At, Bt) do { __builtin_amdgcn_s_setprio(1); _Pragma("unroll") for (int m = 0; m < 4; ++m) _Pragma("unroll") for (int n = 0; n < 2; ++n) _Pragma("unroll") for (int k = 0; k < 2; ++k) \
;         acc[ai][bj][m][n] = __builtin_amdgcn_mfma_f32_16x16x32_bf16(Bt[n][k], At[m][k], acc[ai][bj][m][n], 0, 0, 0); __builtin_amdgcn_s_setprio(0); } while (0)
; #define PG8_WAIT_V(n) asm volatile("s_waitcnt vmcnt(" #n ")" ::: "memory")
; #define PG8_WAIT_L(n) asm volatile("s_waitcnt lgkmcnt(" #n ")" ::: "memory")
; #define PG8_BAR __builtin_amdgcn_s_barrier()
; #define PG8_SCHED __builtin_amdgcn_sched_barrier(0)
; template <class Epi, class Sched, bool ALIGN_EPI = false, bool SP2 = false>
; __device__ __forceinline__ void gemm_phase(PG8_LAS unsigned char* lds, const Gemm g, const Sched& S, const Epi& E) {
;     ...
;             PG8_LDB(B0, 0, 0); PG8_LDB(B1, 0, 1); PG8_SCHED; PG8_LDA(At, 0, 0); PG8_STAGE(PG8_SA(1, 1), a1 + hstep, voffA);
;             PG8_WAIT_V(8); PG8_WAIT_L(0); PG8_BAR; PG8_MMA(0, 0, At, B0); PG8_MMA(0, 1, At, B1); PG8_BAR; PG8_SCHED;
;             PG8_LDA(At, 0, 1); PG8_STAGE(PG8_SB(0, 0), b2, voffB); PG8_STAGE(PG8_SB(0, 1), b2 + hstep, voffB); PG8_STAGE(PG8_SA(0, 0), a2, voffA);
;             PG8_WAIT_V(8); PG8_WAIT_L(0); PG8_BAR; PG8_MMA(1, 0, At, B0); PG8_MMA(1, 1, At, B1); PG8_BAR; PG8_SCHED;
.Lrw0_b0:
	s_waitcnt lgkmcnt(0)
	s_barrier
	s_setprio 1
	s_waitcnt lgkmcnt(0)
	v_mfma_f32_16x16x32_bf16 v[124:127], v[144:147], v[182:185], v[124:127]
	v_mfma_f32_16x16x32_bf16 v[108:111], v[144:147], v[190:193], v[108:111]
	v_mfma_f32_16x16x32_bf16 v[92:95], v[144:147], v[202:205], v[92:95]
	v_mfma_f32_16x16x32_bf16 v[76:79], v[144:147], v[210:213], v[76:79]
	v_mfma_f32_16x16x32_bf16 v[72:75], v[158:161], v[210:213], v[72:75]
	v_mfma_f32_16x16x32_bf16 v[88:91], v[158:161], v[202:205], v[88:91]
	v_mfma_f32_16x16x32_bf16 v[104:107], v[158:161], v[190:193], v[104:107]
	v_mfma_f32_16x16x32_bf16 v[120:123], v[158:161], v[182:185], v[120:123]
	v_mfma_f32_16x16x32_bf16 v[124:127], v[154:157], v[186:189], v[124:127]
	v_mfma_f32_16x16x32_bf16 v[108:111], v[154:157], v[198:201], v[108:111]
	v_mfma_f32_16x16x32_bf16 v[92:95], v[154:157], v[206:209], v[92:95]
	v_mfma_f32_16x16x32_bf16 v[76:79], v[154:157], v[214:217], v[76:79]
	v_mfma_f32_16x16x32_bf16 v[72:75], v[162:165], v[214:217], v[72:75]
	v_mfma_f32_16x16x32_bf16 v[88:91], v[162:165], v[206:209], v[88:91]
	v_mfma_f32_16x16x32_bf16 v[104:107], v[162:165], v[198:201], v[104:107]
	v_mfma_f32_16x16x32_bf16 v[120:123], v[162:165], v[186:189], v[120:123]
	s_setprio 0
	s_setprio 1
	v_mfma_f32_16x16x32_bf16 v[116:119], v[166:169], v[182:185], v[116:119]
	v_mfma_f32_16x16x32_bf16 v[100:103], v[166:169], v[190:193], v[100:103]
	v_mfma_f32_16x16x32_bf16 v[84:87], v[166:169], v[202:205], v[84:87]
	v_mfma_f32_16x16x32_bf16 v[68:71], v[166:169], v[210:213], v[68:71]
	v_mfma_f32_16x16x32_bf16 v[64:67], v[174:177], v[210:213], v[64:67]
	v_mfma_f32_16x16x32_bf16 v[80:83], v[174:177], v[202:205], v[80:83]
	v_mfma_f32_16x16x32_bf16 v[96:99], v[174:177], v[190:193], v[96:99]
	v_mfma_f32_16x16x32_bf16 v[112:115], v[174:177], v[182:185], v[112:115]
	v_mfma_f32_16x16x32_bf16 v[116:119], v[170:173], v[186:189], v[116:119]
	v_mfma_f32_16x16x32_bf16 v[100:103], v[170:173], v[198:201], v[100:103]
	v_mfma_f32_16x16x32_bf16 v[84:87], v[170:173], v[206:209], v[84:87]
	v_mfma_f32_16x16x32_bf16 v[68:71], v[170:173], v[214:217], v[68:71]
	v_mfma_f32_16x16x32_bf16 v[64:67], v[178:181], v[214:217], v[64:67]
	v_mfma_f32_16x16x32_bf16 v[80:83], v[178:181], v[206:209], v[80:83]
	v_mfma_f32_16x16x32_bf16 v[96:99], v[178:181], v[198:201], v[96:99]
	v_mfma_f32_16x16x32_bf16 v[112:115], v[178:181], v[186:189], v[112:115]
	s_setprio 0
	s_barrier
	s_add_i32 s51, s42, s30
	v_lshl_add_u64 v[194:195], s[26:27], 0, v[130:131]
	s_mov_b32 m0, s51
	ds_read_b128 v[182:185], v153 offset:16384
	ds_read_b128 v[186:189], v153 offset:17408
	ds_read_b128 v[190:193], v153 offset:18432
	ds_read_b128 v[198:201], v153 offset:19456
	ds_read_b128 v[202:205], v153 offset:20480
	ds_read_b128 v[206:209], v153 offset:21504
	ds_read_b128 v[210:213], v153 offset:22528
	ds_read_b128 v[214:217], v153 offset:23552
	global_load_lds_dwordx4 v[194:195], off
	s_add_i32 m0, s51, 0x2000
	s_add_u32 s52, s26, 0x40000
	v_lshl_add_u64 v[218:219], s[26:27], 0, v[134:135]
	s_addc_u32 s53, s27, 0
	s_add_i32 s51, s43, s30
	global_load_lds_dwordx4 v[218:219], off
	v_lshl_add_u64 v[220:221], s[52:53], 0, v[130:131]
	s_mov_b32 m0, s51
	v_lshl_add_u64 v[222:223], s[28:29], 0, v[132:133]
	global_load_lds_dwordx4 v[220:221], off
	v_lshl_add_u64 v[220:221], s[52:53], 0, v[134:135]
	s_add_i32 m0, s51, 0x2000
	s_nop 0
	global_load_lds_dwordx4 v[220:221], off
	v_lshl_add_u64 v[220:221], s[28:29], 0, v[128:129]
	s_mov_b32 m0, s23
	s_nop 0
	global_load_lds_dwordx4 v[220:221], off
	s_mov_b32 m0, s34
	s_nop 0
	global_load_lds_dwordx4 v[222:223], off
	s_cmp_eq_u32 s50, s101
	s_cbranch_scc1 .Lrw0_r1
	s_waitcnt vmcnt(8)
.Lrw0_b1:
	s_waitcnt lgkmcnt(0)
	s_barrier
	s_setprio 1
	s_waitcnt lgkmcnt(0)
	v_mfma_f32_16x16x32_bf16 v[60:63], v[144:147], v[182:185], v[60:63]
	v_mfma_f32_16x16x32_bf16 v[44:47], v[144:147], v[190:193], v[44:47]
	v_mfma_f32_16x16x32_bf16 v[28:31], v[144:147], v[202:205], v[28:31]
	v_mfma_f32_16x16x32_bf16 v[12:15], v[144:147], v[210:213], v[12:15]
	v_mfma_f32_16x16x32_bf16 v[8:11], v[158:161], v[210:213], v[8:11]
	v_mfma_f32_16x16x32_bf16 v[24:27], v[158:161], v[202:205], v[24:27]
	v_mfma_f32_16x16x32_bf16 v[40:43], v[158:161], v[190:193], v[40:43]
	v_mfma_f32_16x16x32_bf16 v[56:59], v[158:161], v[182:185], v[56:59]
	v_mfma_f32_16x16x32_bf16 v[60:63], v[154:157], v[186:189], v[60:63]
	v_mfma_f32_16x16x32_bf16 v[44:47], v[154:157], v[198:201], v[44:47]
	v_mfma_f32_16x16x32_bf16 v[28:31], v[154:157], v[206:209], v[28:31]
	v_mfma_f32_16x16x32_bf16 v[12:15], v[154:157], v[214:217], v[12:15]
	v_mfma_f32_16x16x32_bf16 v[8:11], v[162:165], v[214:217], v[8:11]
	v_mfma_f32_16x16x32_bf16 v[24:27], v[162:165], v[206:209], v[24:27]
	v_mfma_f32_16x16x32_bf16 v[40:43], v[162:165], v[198:201], v[40:43]
	v_mfma_f32_16x16x32_bf16 v[56:59], v[162:165], v[186:189], v[56:59]
	s_setprio 0
	s_setprio 1
	v_mfma_f32_16x16x32_bf16 v[52:55], v[166:169], v[182:185], v[52:55]
	v_mfma_f32_16x16x32_bf16 v[36:39], v[166:169], v[190:193], v[36:39]
	v_mfma_f32_16x16x32_bf16 v[20:23], v[166:169], v[202:205], v[20:23]
	v_mfma_f32_16x16x32_bf16 v[4:7], v[166:169], v[210:213], v[4:7]
	v_mfma_f32_16x16x32_bf16 v[0:3], v[174:177], v[210:213], v[0:3]
	v_mfma_f32_16x16x32_bf16 v[16:19], v[174:177], v[202:205], v[16:19]
	v_mfma_f32_16x16x32_bf16 v[32:35], v[174:177], v[190:193], v[32:35]
	v_mfma_f32_16x16x32_bf16 v[48:51], v[174:177], v[182:185], v[48:51]
	v_mfma_f32_16x16x32_bf16 v[52:55], v[170:173], v[186:189], v[52:55]
	v_mfma_f32_16x16x32_bf16 v[36:39], v[170:173], v[198:201], v[36:39]
	v_mfma_f32_16x16x32_bf16 v[20:23], v[170:173], v[206:209], v[20:23]
	v_mfma_f32_16x16x32_bf16 v[4:7], v[170:173], v[214:217], v[4:7]
	v_mfma_f32_16x16x32_bf16 v[0:3], v[178:181], v[214:217], v[0:3]
	v_mfma_f32_16x16x32_bf16 v[16:19], v[178:181], v[206:209], v[16:19]
	v_mfma_f32_16x16x32_bf16 v[32:35], v[178:181], v[198:201], v[32:35]
	v_mfma_f32_16x16x32_bf16 v[48:51], v[178:181], v[186:189], v[48:51]
	s_setprio 0
	s_barrier
; #define PG8_STAGE(bufoff, gbase, voff) do { _Pragma("unroll") for (int _i = 0; _i < 2; ++_i) \
;         __builtin_amdgcn_global_load_lds((const unsigned*)((const char*)(gbase) + (voff)[_i]), (PG8_LAS unsigned*)(lds + (bufoff) + ldsw + _i * 8192), 16, 0, 0); } while (0)
; #define PG8_LDA(dst, b, h) do { _Pragma("unroll") for (int m = 0; m < 4; ++m) _Pragma("unroll") for (int k = 0; k < 2; ++k) dst[m][k] = *(const PG8_LAS bf16x8*)(lds + PG8_SA(b, h) + aoff + m * 2048 + k * 1024); } while (0)
; #define PG8_LDB(dst, b, h) do { _Pragma("unroll") for (int n = 0; n < 2; ++n) _Pragma("unroll") for (int k = 0; k < 2; ++k) dst[n][k] = *(const PG8_LAS bf16x8*)(lds + PG8_SB(b, h) + boff + n * 2048 + k * 1024); } while (0)
; #define PG8_MMA(ai, bj, At, Bt) do { __builtin_amdgcn_s_setprio(1); _Pragma("unroll") for (int m = 0; m < 4; ++m) _Pragma("unroll") for (int n = 0; n < 2; ++n) _Pragma("unroll") for (int k = 0; k < 2; ++k) \
;         acc[ai][bj][m][n] = __builtin_amdgcn_mfma_f32_16x16x32_bf16(Bt[n][k], At[m][k], acc[ai][bj][m][n], 0, 0, 0); __builtin_amdgcn_s_setprio(0); } while (0)
; #define PG8_WAIT_V(n) asm volatile("s_waitcnt vmcnt(" #n ")" ::: "memory")
; #define PG8_WAIT_L(n) asm volatile("s_waitcnt lgkmcnt(" #n ")" ::: "memory")
; #define PG8_BAR __builtin_amdgcn_s_barrier()
; #define PG8_SCHED __builtin_amdgcn_sched_barrier(0)
; template <class Epi, class Sched, bool ALIGN_EPI = false, bool SP2 = false>
; __device__ __forceinline__ void gemm_phase(PG8_LAS unsigned char* lds, const Gemm g, const Sched& S, const Epi& E) {
;     ...
;             PG8_LDB(B0, 1, 0); PG8_LDB(B1, 1, 1); PG8_SCHED; PG8_LDA(At, 1, 0); PG8_STAGE(PG8_SA(0, 1), a2 + hstep, voffA);
;             PG8_WAIT_V(8); PG8_WAIT_L(0); PG8_BAR; PG8_MMA(0, 0, At, B0); PG8_MMA(0, 1, At, B1); PG8_BAR; PG8_SCHED;
	s_add_i32 s51, 0, 0x18000
	s_add_i32 s52, 0, 0x1c000
	v_add_u32_e32 v162, s51, v149
	v_add_u32_e32 v178, s52, v149
	ds_read_b128 v[144:147], v162
	ds_read_b128 v[154:157], v162 offset:1024
	ds_read_b128 v[158:161], v162 offset:2048
	ds_read_b128 v[162:165], v162 offset:3072
	ds_read_b128 v[166:169], v178
	ds_read_b128 v[170:173], v178 offset:1024
	ds_read_b128 v[174:177], v178 offset:2048
	ds_read_b128 v[178:181], v178 offset:3072
	s_add_u32 s28, s28, 0x40000
	s_addc_u32 s29, s29, 0
	s_mov_b32 m0, s35
	v_lshl_add_u64 v[224:225], s[28:29], 0, v[128:129]
	ds_read_b128 v[182:185], v153 offset:32768
	ds_read_b128 v[186:189], v153 offset:33792
	ds_read_b128 v[190:193], v153 offset:34816
	ds_read_b128 v[198:201], v153 offset:35840
	ds_read_b128 v[202:205], v153 offset:36864
	ds_read_b128 v[206:209], v153 offset:37888
	ds_read_b128 v[210:213], v153 offset:38912
	ds_read_b128 v[214:217], v153 offset:39936
	global_load_lds_dwordx4 v[224:225], off
	v_lshl_add_u64 v[224:225], s[28:29], 0, v[132:133]
	s_mov_b32 m0, s36
	s_nop 0
	global_load_lds_dwordx4 v[224:225], off
	s_waitcnt vmcnt(8)
	s_waitcnt lgkmcnt(0)
	s_barrier
	s_setprio 1
	s_waitcnt lgkmcnt(0)
	v_mfma_f32_16x16x32_bf16 v[124:127], v[144:147], v[182:185], v[124:127]
	v_mfma_f32_16x16x32_bf16 v[108:111], v[144:147], v[190:193], v[108:111]
	v_mfma_f32_16x16x32_bf16 v[92:95], v[144:147], v[202:205], v[92:95]
	v_mfma_f32_16x16x32_bf16 v[76:79], v[144:147], v[210:213], v[76:79]
	v_mfma_f32_16x16x32_bf16 v[72:75], v[158:161], v[210:213], v[72:75]
	v_mfma_f32_16x16x32_bf16 v[88:91], v[158:161], v[202:205], v[88:91]
	v_mfma_f32_16x16x32_bf16 v[104:107], v[158:161], v[190:193], v[104:107]
	v_mfma_f32_16x16x32_bf16 v[120:123], v[158:161], v[182:185], v[120:123]
	v_mfma_f32_16x16x32_bf16 v[124:127], v[154:157], v[186:189], v[124:127]
	v_mfma_f32_16x16x32_bf16 v[108:111], v[154:157], v[198:201], v[108:111]
	v_mfma_f32_16x16x32_bf16 v[92:95], v[154:157], v[206:209], v[92:95]
	v_mfma_f32_16x16x32_bf16 v[76:79], v[154:157], v[214:217], v[76:79]
	v_mfma_f32_16x16x32_bf16 v[72:75], v[162:165], v[214:217], v[72:75]
	v_mfma_f32_16x16x32_bf16 v[88:91], v[162:165], v[206:209], v[88:91]
	v_mfma_f32_16x16x32_bf16 v[104:107], v[162:165], v[198:201], v[104:107]
	v_mfma_f32_16x16x32_bf16 v[120:123], v[162:165], v[186:189], v[120:123]
	s_setprio 0
	s_setprio 1
	v_mfma_f32_16x16x32_bf16 v[116:119], v[166:169], v[182:185], v[116:119]
	v_mfma_f32_16x16x32_bf16 v[100:103], v[166:169], v[190:193], v[100:103]
	v_mfma_f32_16x16x32_bf16 v[84:87], v[166:169], v[202:205], v[84:87]
	v_mfma_f32_16x16x32_bf16 v[68:71], v[166:169], v[210:213], v[68:71]
	v_mfma_f32_16x16x32_bf16 v[64:67], v[174:177], v[210:213], v[64:67]
	v_mfma_f32_16x16x32_bf16 v[80:83], v[174:177], v[202:205], v[80:83]
	v_mfma_f32_16x16x32_bf16 v[96:99], v[174:177], v[190:193], v[96:99]
	v_mfma_f32_16x16x32_bf16 v[112:115], v[174:177], v[182:185], v[112:115]
	v_mfma_f32_16x16x32_bf16 v[116:119], v[170:173], v[186:189], v[116:119]
	v_mfma_f32_16x16x32_bf16 v[100:103], v[170:173], v[198:201], v[100:103]
	v_mfma_f32_16x16x32_bf16 v[84:87], v[170:173], v[206:209], v[84:87]
	v_mfma_f32_16x16x32_bf16 v[68:71], v[170:173], v[214:217], v[68:71]
	v_mfma_f32_16x16x32_bf16 v[64:67], v[178:181], v[214:217], v[64:67]
	v_mfma_f32_16x16x32_bf16 v[80:83], v[178:181], v[206:209], v[80:83]
	v_mfma_f32_16x16x32_bf16 v[96:99], v[178:181], v[198:201], v[96:99]
	v_mfma_f32_16x16x32_bf16 v[112:115], v[178:181], v[186:189], v[112:115]
	s_setprio 0
	s_barrier
; #define PG8_STAGE(bufoff, gbase, voff) do { _Pragma("unroll") for (int _i = 0; _i < 2; ++_i) \
;         __builtin_amdgcn_global_load_lds((const unsigned*)((const char*)(gbase) + (voff)[_i]), (PG8_LAS unsigned*)(lds + (bufoff) + ldsw + _i * 8192), 16, 0, 0); } while (0)
; #define PG8_LDA(dst, b, h) do { _Pragma("unroll") for (int m = 0; m < 4; ++m) _Pragma("unroll") for (int k = 0; k < 2; ++k) dst[m][k] = *(const PG8_LAS bf16x8*)(lds + PG8_SA(b, h) + aoff + m * 2048 + k * 1024); } while (0)
; #define PG8_MMA(ai, bj, At, Bt) do { __builtin_amdgcn_s_setprio(1); _Pragma("unroll") for (int m = 0; m < 4; ++m) _Pragma("unroll") for (int n = 0; n < 2; ++n) _Pragma("unroll") for (int k = 0; k < 2; ++k) \
;         acc[ai][bj][m][n] = __builtin_amdgcn_mfma_f32_16x16x32_bf16(Bt[n][k], At[m][k], acc[ai][bj][m][n], 0, 0, 0); __builtin_amdgcn_s_setprio(0); } while (0)
; #define PG8_WAIT_V(n) asm volatile("s_waitcnt vmcnt(" #n ")" ::: "memory")
; #define PG8_WAIT_L(n) asm volatile("s_waitcnt lgkmcnt(" #n ")" ::: "memory")
; #define PG8_BAR __builtin_amdgcn_s_barrier()
; #define PG8_SCHED __builtin_amdgcn_sched_barrier(0)
; template <class Epi, class Sched, bool ALIGN_EPI = false, bool SP2 = false>
; __device__ __forceinline__ void gemm_phase(PG8_LAS unsigned char* lds, const Gemm g, const Sched& S, const Epi& E) {
;     ...
;             PG8_LDA(At, 1, 1); PG8_STAGE(PG8_SB(1, 0), b3, voffB); PG8_STAGE(PG8_SB(1, 1), b3 + hstep, voffB); PG8_STAGE(PG8_SA(1, 0), a3, voffA);
;             PG8_WAIT_V(8); PG8_WAIT_L(0); PG8_BAR; PG8_MMA(1, 0, At, B0); PG8_MMA(1, 1, At, B1); PG8_BAR; PG8_SCHED;
	s_add_i32 s28, s51, s30
	v_lshl_add_u64 v[194:195], v[194:195], 0, s[10:11]
	s_mov_b32 m0, s28
	ds_read_b128 v[182:185], v153 offset:49152
	ds_read_b128 v[186:189], v153 offset:50176
	ds_read_b128 v[190:193], v153 offset:51200
	ds_read_b128 v[198:201], v153 offset:52224
	ds_read_b128 v[202:205], v153 offset:53248
	ds_read_b128 v[206:209], v153 offset:54272
	ds_read_b128 v[210:213], v153 offset:55296
	ds_read_b128 v[214:217], v153 offset:56320
	global_load_lds_dwordx4 v[194:195], off
	s_add_i32 m0, s28, 0x2000
	s_add_u32 s26, s26, 0x40080
	v_lshl_add_u64 v[194:195], v[218:219], 0, s[10:11]
	s_addc_u32 s27, s27, 0
	s_add_i32 s28, s52, s30
	global_load_lds_dwordx4 v[194:195], off
	v_lshl_add_u64 v[194:195], s[26:27], 0, v[130:131]
	s_mov_b32 m0, s28
	s_nop 0
	global_load_lds_dwordx4 v[194:195], off
	v_lshl_add_u64 v[194:195], s[26:27], 0, v[134:135]
	s_add_i32 m0, s28, 0x2000
	s_nop 0
	global_load_lds_dwordx4 v[194:195], off
	v_lshl_add_u64 v[194:195], v[220:221], 0, s[10:11]
	s_mov_b32 m0, s39
	s_nop 0
	global_load_lds_dwordx4 v[194:195], off
	v_lshl_add_u64 v[194:195], v[222:223], 0, s[10:11]
	s_mov_b32 m0, s40
	s_nop 0
	global_load_lds_dwordx4 v[194:195], off
	s_waitcnt vmcnt(8)
	s_waitcnt lgkmcnt(0)
	s_barrier
	s_setprio 1
	s_waitcnt lgkmcnt(0)
	v_mfma_f32_16x16x32_bf16 v[60:63], v[144:147], v[182:185], v[60:63]
	v_mfma_f32_16x16x32_bf16 v[44:47], v[144:147], v[190:193], v[44:47]
	v_mfma_f32_16x16x32_bf16 v[28:31], v[144:147], v[202:205], v[28:31]
	v_mfma_f32_16x16x32_bf16 v[12:15], v[144:147], v[210:213], v[12:15]
	v_mfma_f32_16x16x32_bf16 v[8:11], v[158:161], v[210:213], v[8:11]
	v_mfma_f32_16x16x32_bf16 v[24:27], v[158:161], v[202:205], v[24:27]
	v_mfma_f32_16x16x32_bf16 v[40:43], v[158:161], v[190:193], v[40:43]
	v_mfma_f32_16x16x32_bf16 v[56:59], v[158:161], v[182:185], v[56:59]
	v_mfma_f32_16x16x32_bf16 v[60:63], v[154:157], v[186:189], v[60:63]
	v_mfma_f32_16x16x32_bf16 v[44:47], v[154:157], v[198:201], v[44:47]
	v_mfma_f32_16x16x32_bf16 v[28:31], v[154:157], v[206:209], v[28:31]
	v_mfma_f32_16x16x32_bf16 v[12:15], v[154:157], v[214:217], v[12:15]
	v_mfma_f32_16x16x32_bf16 v[8:11], v[162:165], v[214:217], v[8:11]
	v_mfma_f32_16x16x32_bf16 v[24:27], v[162:165], v[206:209], v[24:27]
	v_mfma_f32_16x16x32_bf16 v[40:43], v[162:165], v[198:201], v[40:43]
	v_mfma_f32_16x16x32_bf16 v[56:59], v[162:165], v[186:189], v[56:59]
	s_setprio 0
	s_setprio 1
	v_mfma_f32_16x16x32_bf16 v[52:55], v[166:169], v[182:185], v[52:55]
	v_mfma_f32_16x16x32_bf16 v[36:39], v[166:169], v[190:193], v[36:39]
	v_mfma_f32_16x16x32_bf16 v[20:23], v[166:169], v[202:205], v[20:23]
	v_mfma_f32_16x16x32_bf16 v[4:7], v[166:169], v[210:213], v[4:7]
	v_mfma_f32_16x16x32_bf16 v[0:3], v[174:177], v[210:213], v[0:3]
	v_mfma_f32_16x16x32_bf16 v[16:19], v[174:177], v[202:205], v[16:19]
	v_mfma_f32_16x16x32_bf16 v[32:35], v[174:177], v[190:193], v[32:35]
	v_mfma_f32_16x16x32_bf16 v[48:51], v[174:177], v[182:185], v[48:51]
	v_mfma_f32_16x16x32_bf16 v[52:55], v[170:173], v[186:189], v[52:55]
	v_mfma_f32_16x16x32_bf16 v[36:39], v[170:173], v[198:201], v[36:39]
	v_mfma_f32_16x16x32_bf16 v[20:23], v[170:173], v[206:209], v[20:23]
	v_mfma_f32_16x16x32_bf16 v[4:7], v[170:173], v[214:217], v[4:7]
	v_mfma_f32_16x16x32_bf16 v[0:3], v[178:181], v[214:217], v[0:3]
	v_mfma_f32_16x16x32_bf16 v[16:19], v[178:181], v[206:209], v[16:19]
	v_mfma_f32_16x16x32_bf16 v[32:35], v[178:181], v[198:201], v[32:35]
	v_mfma_f32_16x16x32_bf16 v[48:51], v[178:181], v[186:189], v[48:51]
	s_setprio 0
	s_barrier
	s_add_i32 s50, s50, 2
	s_add_u32 s24, s24, 0x100
	s_addc_u32 s25, s25, 0
	s_add_u32 s48, s48, 0x100
	s_addc_u32 s49, s49, 0
	s_cmp_gt_u32 s50, 13
	s_cbranch_scc0 .LBB0_293
	s_branch .Lrw0_x

; #define PG8_STAGE(bufoff, gbase, voff) do { _Pragma("unroll") for (int _i = 0; _i < 2; ++_i) \
;         __builtin_amdgcn_global_load_lds((const unsigned*)((const char*)(gbase) + (voff)[_i]), (PG8_LAS unsigned*)(lds + (bufoff) + ldsw + _i * 8192), 16, 0, 0); } while (0)
; #define PG8_LDA(dst, b, h) do { _Pragma("unroll") for (int m = 0; m < 4; ++m) _Pragma("unroll") for (int k = 0; k < 2; ++k) dst[m][k] = *(const PG8_LAS bf16x8*)(lds + PG8_SA(b, h) + aoff + m * 2048 + k * 1024); } while (0)
; #define PG8_LDB(dst, b, h) do { _Pragma("unroll") for (int n = 0; n < 2; ++n) _Pragma("unroll") for (int k = 0; k < 2; ++k) dst[n][k] = *(const PG8_LAS bf16x8*)(lds + PG8_SB(b, h) + boff + n * 2048 + k * 1024); } while (0)
; #define PG8_MMA(ai, bj, At, Bt) do { __builtin_amdgcn_s_setprio(1); _Pragma("unroll") for (int m = 0; m < 4; ++m) _Pragma("unroll") for (int n = 0; n < 2; ++n) _Pragma("unroll") for (int k = 0; k < 2; ++k) \
;         acc[ai][bj][m][n] = __builtin_amdgcn_mfma_f32_16x16x32_bf16(Bt[n][k], At[m][k], acc[ai][bj][m][n], 0, 0, 0); __builtin_amdgcn_s_setprio(0); } while (0)
; #define PG8_WAIT_V(n) asm volatile("s_waitcnt vmcnt(" #n ")" ::: "memory")
; #define PG8_WAIT_L(n) asm volatile("s_waitcnt lgkmcnt(" #n ")" ::: "memory")
; #define PG8_BAR __builtin_amdgcn_s_barrier()
; #define PG8_SCHED __builtin_amdgcn_sched_barrier(0)
; template <class Epi, class Sched, bool ALIGN_EPI = false, bool SP2 = false>
; __device__ __forceinline__ void gemm_phase(PG8_LAS unsigned char* lds, const Gemm g, const Sched& S, const Epi& E) {
;     ...
;             PG8_LDB(B0, 0, 0); PG8_LDB(B1, 0, 1); PG8_SCHED; PG8_LDA(At, 0, 0); PG8_STAGE(PG8_SA(1, 1), a1 + hstep, voffA);
;             PG8_WAIT_V(8); PG8_WAIT_L(0); PG8_BAR; PG8_MMA(0, 0, At, B0); PG8_MMA(0, 1, At, B1); PG8_BAR; PG8_SCHED;
;             PG8_LDA(At, 0, 1); PG8_STAGE(PG8_SB(0, 0), b2, voffB); PG8_STAGE(PG8_SB(0, 1), b2 + hstep, voffB); PG8_STAGE(PG8_SA(0, 0), a2, voffA);
;             PG8_WAIT_V(8); PG8_WAIT_L(0); PG8_BAR; PG8_MMA(1, 0, At, B0); PG8_MMA(1, 1, At, B1); PG8_BAR; PG8_SCHED;
.Lrw3_b0:
	s_waitcnt lgkmcnt(0)
	s_barrier
	s_setprio 1
	s_waitcnt lgkmcnt(0)
	v_mfma_f32_16x16x32_bf16 v[124:127], v[144:147], v[184:187], v[124:127]
	v_mfma_f32_16x16x32_bf16 v[108:111], v[144:147], v[192:195], v[108:111]
	v_mfma_f32_16x16x32_bf16 v[92:95], v[144:147], v[202:205], v[92:95]
	v_mfma_f32_16x16x32_bf16 v[76:79], v[144:147], v[210:213], v[76:79]
	v_mfma_f32_16x16x32_bf16 v[72:75], v[160:163], v[210:213], v[72:75]
	v_mfma_f32_16x16x32_bf16 v[88:91], v[160:163], v[202:205], v[88:91]
	v_mfma_f32_16x16x32_bf16 v[104:107], v[160:163], v[192:195], v[104:107]
	v_mfma_f32_16x16x32_bf16 v[120:123], v[160:163], v[184:187], v[120:123]
	v_mfma_f32_16x16x32_bf16 v[124:127], v[156:159], v[188:191], v[124:127]
	v_mfma_f32_16x16x32_bf16 v[108:111], v[156:159], v[198:201], v[108:111]
	v_mfma_f32_16x16x32_bf16 v[92:95], v[156:159], v[206:209], v[92:95]
	v_mfma_f32_16x16x32_bf16 v[76:79], v[156:159], v[214:217], v[76:79]
	v_mfma_f32_16x16x32_bf16 v[72:75], v[164:167], v[214:217], v[72:75]
	v_mfma_f32_16x16x32_bf16 v[88:91], v[164:167], v[206:209], v[88:91]
	v_mfma_f32_16x16x32_bf16 v[104:107], v[164:167], v[198:201], v[104:107]
	v_mfma_f32_16x16x32_bf16 v[120:123], v[164:167], v[188:191], v[120:123]
	s_setprio 0
	s_setprio 1
	v_mfma_f32_16x16x32_bf16 v[116:119], v[168:171], v[184:187], v[116:119]
	v_mfma_f32_16x16x32_bf16 v[100:103], v[168:171], v[192:195], v[100:103]
	v_mfma_f32_16x16x32_bf16 v[84:87], v[168:171], v[202:205], v[84:87]
	v_mfma_f32_16x16x32_bf16 v[68:71], v[168:171], v[210:213], v[68:71]
	v_mfma_f32_16x16x32_bf16 v[64:67], v[176:179], v[210:213], v[64:67]
	v_mfma_f32_16x16x32_bf16 v[80:83], v[176:179], v[202:205], v[80:83]
	v_mfma_f32_16x16x32_bf16 v[96:99], v[176:179], v[192:195], v[96:99]
	v_mfma_f32_16x16x32_bf16 v[112:115], v[176:179], v[184:187], v[112:115]
	v_mfma_f32_16x16x32_bf16 v[116:119], v[172:175], v[188:191], v[116:119]
	v_mfma_f32_16x16x32_bf16 v[100:103], v[172:175], v[198:201], v[100:103]
	v_mfma_f32_16x16x32_bf16 v[84:87], v[172:175], v[206:209], v[84:87]
	v_mfma_f32_16x16x32_bf16 v[68:71], v[172:175], v[214:217], v[68:71]
	v_mfma_f32_16x16x32_bf16 v[64:67], v[180:183], v[214:217], v[64:67]
	v_mfma_f32_16x16x32_bf16 v[80:83], v[180:183], v[206:209], v[80:83]
	v_mfma_f32_16x16x32_bf16 v[96:99], v[180:183], v[198:201], v[96:99]
	v_mfma_f32_16x16x32_bf16 v[112:115], v[180:183], v[188:191], v[112:115]
	s_setprio 0
	s_barrier
	s_add_i32 s49, s40, s28
	v_lshl_add_u64 v[218:219], s[24:25], 0, v[130:131]
	s_mov_b32 m0, s49
	ds_read_b128 v[184:187], v153 offset:16384
	ds_read_b128 v[188:191], v153 offset:17408
	ds_read_b128 v[192:195], v153 offset:18432
	ds_read_b128 v[198:201], v153 offset:19456
	ds_read_b128 v[202:205], v153 offset:20480
	ds_read_b128 v[206:209], v153 offset:21504
	ds_read_b128 v[210:213], v153 offset:22528
	ds_read_b128 v[214:217], v153 offset:23552
	global_load_lds_dwordx4 v[218:219], off
	s_add_i32 m0, s49, 0x2000
	s_add_u32 s50, s24, 0xb0000
	v_lshl_add_u64 v[220:221], s[24:25], 0, v[134:135]
	s_addc_u32 s51, s25, 0
	s_add_i32 s49, s41, s28
	global_load_lds_dwordx4 v[220:221], off
	v_lshl_add_u64 v[222:223], s[50:51], 0, v[130:131]
	s_mov_b32 m0, s49
	v_lshl_add_u64 v[224:225], s[26:27], 0, v[132:133]
	global_load_lds_dwordx4 v[222:223], off
	v_lshl_add_u64 v[222:223], s[50:51], 0, v[134:135]
	s_add_i32 m0, s49, 0x2000
	s_nop 0
	global_load_lds_dwordx4 v[222:223], off
	v_lshl_add_u64 v[222:223], s[26:27], 0, v[128:129]
	s_mov_b32 m0, s29
	s_nop 0
	global_load_lds_dwordx4 v[222:223], off
	s_mov_b32 m0, s30
	s_nop 0
	global_load_lds_dwordx4 v[224:225], off
	s_cmp_eq_u32 s48, s101
	s_cbranch_scc1 .Lrw3_r1
	s_waitcnt vmcnt(8)
.Lrw3_b1:
	s_waitcnt lgkmcnt(0)
	s_barrier
	s_setprio 1
	s_waitcnt lgkmcnt(0)
	v_mfma_f32_16x16x32_bf16 v[60:63], v[144:147], v[184:187], v[60:63]
	v_mfma_f32_16x16x32_bf16 v[44:47], v[144:147], v[192:195], v[44:47]
	v_mfma_f32_16x16x32_bf16 v[28:31], v[144:147], v[202:205], v[28:31]
	v_mfma_f32_16x16x32_bf16 v[12:15], v[144:147], v[210:213], v[12:15]
	v_mfma_f32_16x16x32_bf16 v[8:11], v[160:163], v[210:213], v[8:11]
	v_mfma_f32_16x16x32_bf16 v[24:27], v[160:163], v[202:205], v[24:27]
	v_mfma_f32_16x16x32_bf16 v[40:43], v[160:163], v[192:195], v[40:43]
	v_mfma_f32_16x16x32_bf16 v[56:59], v[160:163], v[184:187], v[56:59]
	v_mfma_f32_16x16x32_bf16 v[60:63], v[156:159], v[188:191], v[60:63]
	v_mfma_f32_16x16x32_bf16 v[44:47], v[156:159], v[198:201], v[44:47]
	v_mfma_f32_16x16x32_bf16 v[28:31], v[156:159], v[206:209], v[28:31]
	v_mfma_f32_16x16x32_bf16 v[12:15], v[156:159], v[214:217], v[12:15]
	v_mfma_f32_16x16x32_bf16 v[8:11], v[164:167], v[214:217], v[8:11]
	v_mfma_f32_16x16x32_bf16 v[24:27], v[164:167], v[206:209], v[24:27]
	v_mfma_f32_16x16x32_bf16 v[40:43], v[164:167], v[198:201], v[40:43]
	v_mfma_f32_16x16x32_bf16 v[56:59], v[164:167], v[188:191], v[56:59]
	s_setprio 0
	s_setprio 1
	v_mfma_f32_16x16x32_bf16 v[52:55], v[168:171], v[184:187], v[52:55]
	v_mfma_f32_16x16x32_bf16 v[36:39], v[168:171], v[192:195], v[36:39]
	v_mfma_f32_16x16x32_bf16 v[20:23], v[168:171], v[202:205], v[20:23]
	v_mfma_f32_16x16x32_bf16 v[4:7], v[168:171], v[210:213], v[4:7]
	v_mfma_f32_16x16x32_bf16 v[0:3], v[176:179], v[210:213], v[0:3]
	v_mfma_f32_16x16x32_bf16 v[16:19], v[176:179], v[202:205], v[16:19]
	v_mfma_f32_16x16x32_bf16 v[32:35], v[176:179], v[192:195], v[32:35]
	v_mfma_f32_16x16x32_bf16 v[48:51], v[176:179], v[184:187], v[48:51]
	v_mfma_f32_16x16x32_bf16 v[52:55], v[172:175], v[188:191], v[52:55]
	v_mfma_f32_16x16x32_bf16 v[36:39], v[172:175], v[198:201], v[36:39]
	v_mfma_f32_16x16x32_bf16 v[20:23], v[172:175], v[206:209], v[20:23]
	v_mfma_f32_16x16x32_bf16 v[4:7], v[172:175], v[214:217], v[4:7]
	v_mfma_f32_16x16x32_bf16 v[0:3], v[180:183], v[214:217], v[0:3]
	v_mfma_f32_16x16x32_bf16 v[16:19], v[180:183], v[206:209], v[16:19]
	v_mfma_f32_16x16x32_bf16 v[32:35], v[180:183], v[198:201], v[32:35]
	v_mfma_f32_16x16x32_bf16 v[48:51], v[180:183], v[188:191], v[48:51]
	s_setprio 0
	s_barrier
; #define PG8_STAGE(bufoff, gbase, voff) do { _Pragma("unroll") for (int _i = 0; _i < 2; ++_i) \
;         __builtin_amdgcn_global_load_lds((const unsigned*)((const char*)(gbase) + (voff)[_i]), (PG8_LAS unsigned*)(lds + (bufoff) + ldsw + _i * 8192), 16, 0, 0); } while (0)
; #define PG8_LDA(dst, b, h) do { _Pragma("unroll") for (int m = 0; m < 4; ++m) _Pragma("unroll") for (int k = 0; k < 2; ++k) dst[m][k] = *(const PG8_LAS bf16x8*)(lds + PG8_SA(b, h) + aoff + m * 2048 + k * 1024); } while (0)
; #define PG8_LDB(dst, b, h) do { _Pragma("unroll") for (int n = 0; n < 2; ++n) _Pragma("unroll") for (int k = 0; k < 2; ++k) dst[n][k] = *(const PG8_LAS bf16x8*)(lds + PG8_SB(b, h) + boff + n * 2048 + k * 1024); } while (0)
; #define PG8_MMA(ai, bj, At, Bt) do { __builtin_amdgcn_s_setprio(1); _Pragma("unroll") for (int m = 0; m < 4; ++m) _Pragma("unroll") for (int n = 0; n < 2; ++n) _Pragma("unroll") for (int k = 0; k < 2; ++k) \
;         acc[ai][bj][m][n] = __builtin_amdgcn_mfma_f32_16x16x32_bf16(Bt[n][k], At[m][k], acc[ai][bj][m][n], 0, 0, 0); __builtin_amdgcn_s_setprio(0); } while (0)
; #define PG8_WAIT_V(n) asm volatile("s_waitcnt vmcnt(" #n ")" ::: "memory")
; #define PG8_WAIT_L(n) asm volatile("s_waitcnt lgkmcnt(" #n ")" ::: "memory")
; #define PG8_BAR __builtin_amdgcn_s_barrier()
; #define PG8_SCHED __builtin_amdgcn_sched_barrier(0)
; template <class Epi, class Sched, bool ALIGN_EPI = false, bool SP2 = false>
; __device__ __forceinline__ void gemm_phase(PG8_LAS unsigned char* lds, const Gemm g, const Sched& S, const Epi& E) {
;     ...
;             PG8_LDB(B0, 1, 0); PG8_LDB(B1, 1, 1); PG8_SCHED; PG8_LDA(At, 1, 0); PG8_STAGE(PG8_SA(0, 1), a2 + hstep, voffA);
;             PG8_WAIT_V(8); PG8_WAIT_L(0); PG8_BAR; PG8_MMA(0, 0, At, B0); PG8_MMA(0, 1, At, B1); PG8_BAR; PG8_SCHED;
	s_add_i32 s49, 0, 0x18000
	v_add_u32_e32 v155, s49, v149
	s_add_i32 s50, 0, 0x1c000
	ds_read_b128 v[144:147], v155
	ds_read_b128 v[156:159], v155 offset:1024
	ds_read_b128 v[160:163], v155 offset:2048
	ds_read_b128 v[164:167], v155 offset:3072
	v_add_u32_e32 v155, s50, v149
	ds_read_b128 v[168:171], v155
	ds_read_b128 v[172:175], v155 offset:1024
	ds_read_b128 v[176:179], v155 offset:2048
	ds_read_b128 v[180:183], v155 offset:3072
	s_add_u32 s26, s26, 0xb0000
	s_addc_u32 s27, s27, 0
	s_mov_b32 m0, s31
	v_lshl_add_u64 v[226:227], s[26:27], 0, v[128:129]
	ds_read_b128 v[184:187], v153 offset:32768
	ds_read_b128 v[188:191], v153 offset:33792
	ds_read_b128 v[192:195], v153 offset:34816
	ds_read_b128 v[198:201], v153 offset:35840
	ds_read_b128 v[202:205], v153 offset:36864
	ds_read_b128 v[206:209], v153 offset:37888
	ds_read_b128 v[210:213], v153 offset:38912
	ds_read_b128 v[214:217], v153 offset:39936
	global_load_lds_dwordx4 v[226:227], off
	v_lshl_add_u64 v[226:227], s[26:27], 0, v[132:133]
	s_mov_b32 m0, s33
	s_nop 0
	global_load_lds_dwordx4 v[226:227], off
	s_waitcnt vmcnt(8)
	s_waitcnt lgkmcnt(0)
	s_barrier
	s_setprio 1
	s_waitcnt lgkmcnt(0)
	v_mfma_f32_16x16x32_bf16 v[124:127], v[144:147], v[184:187], v[124:127]
	v_mfma_f32_16x16x32_bf16 v[108:111], v[144:147], v[192:195], v[108:111]
	v_mfma_f32_16x16x32_bf16 v[92:95], v[144:147], v[202:205], v[92:95]
	v_mfma_f32_16x16x32_bf16 v[76:79], v[144:147], v[210:213], v[76:79]
	v_mfma_f32_16x16x32_bf16 v[72:75], v[160:163], v[210:213], v[72:75]
	v_mfma_f32_16x16x32_bf16 v[88:91], v[160:163], v[202:205], v[88:91]
	v_mfma_f32_16x16x32_bf16 v[104:107], v[160:163], v[192:195], v[104:107]
	v_mfma_f32_16x16x32_bf16 v[120:123], v[160:163], v[184:187], v[120:123]
	v_mfma_f32_16x16x32_bf16 v[124:127], v[156:159], v[188:191], v[124:127]
	v_mfma_f32_16x16x32_bf16 v[108:111], v[156:159], v[198:201], v[108:111]
	v_mfma_f32_16x16x32_bf16 v[92:95], v[156:159], v[206:209], v[92:95]
	v_mfma_f32_16x16x32_bf16 v[76:79], v[156:159], v[214:217], v[76:79]
	v_mfma_f32_16x16x32_bf16 v[72:75], v[164:167], v[214:217], v[72:75]
	v_mfma_f32_16x16x32_bf16 v[88:91], v[164:167], v[206:209], v[88:91]
	v_mfma_f32_16x16x32_bf16 v[104:107], v[164:167], v[198:201], v[104:107]
	v_mfma_f32_16x16x32_bf16 v[120:123], v[164:167], v[188:191], v[120:123]
	s_setprio 0
	s_setprio 1
	v_mfma_f32_16x16x32_bf16 v[116:119], v[168:171], v[184:187], v[116:119]
	v_mfma_f32_16x16x32_bf16 v[100:103], v[168:171], v[192:195], v[100:103]
	v_mfma_f32_16x16x32_bf16 v[84:87], v[168:171], v[202:205], v[84:87]
	v_mfma_f32_16x16x32_bf16 v[68:71], v[168:171], v[210:213], v[68:71]
	v_mfma_f32_16x16x32_bf16 v[64:67], v[176:179], v[210:213], v[64:67]
	v_mfma_f32_16x16x32_bf16 v[80:83], v[176:179], v[202:205], v[80:83]
	v_mfma_f32_16x16x32_bf16 v[96:99], v[176:179], v[192:195], v[96:99]
	v_mfma_f32_16x16x32_bf16 v[112:115], v[176:179], v[184:187], v[112:115]
	v_mfma_f32_16x16x32_bf16 v[116:119], v[172:175], v[188:191], v[116:119]
	v_mfma_f32_16x16x32_bf16 v[100:103], v[172:175], v[198:201], v[100:103]
	v_mfma_f32_16x16x32_bf16 v[84:87], v[172:175], v[206:209], v[84:87]
	v_mfma_f32_16x16x32_bf16 v[68:71], v[172:175], v[214:217], v[68:71]
	v_mfma_f32_16x16x32_bf16 v[64:67], v[180:183], v[214:217], v[64:67]
	v_mfma_f32_16x16x32_bf16 v[80:83], v[180:183], v[206:209], v[80:83]
	v_mfma_f32_16x16x32_bf16 v[96:99], v[180:183], v[198:201], v[96:99]
	v_mfma_f32_16x16x32_bf16 v[112:115], v[180:183], v[188:191], v[112:115]
	s_setprio 0
	s_barrier
; #define PG8_STAGE(bufoff, gbase, voff) do { _Pragma("unroll") for (int _i = 0; _i < 2; ++_i) \
;         __builtin_amdgcn_global_load_lds((const unsigned*)((const char*)(gbase) + (voff)[_i]), (PG8_LAS unsigned*)(lds + (bufoff) + ldsw + _i * 8192), 16, 0, 0); } while (0)
; #define PG8_LDA(dst, b, h) do { _Pragma("unroll") for (int m = 0; m < 4; ++m) _Pragma("unroll") for (int k = 0; k < 2; ++k) dst[m][k] = *(const PG8_LAS bf16x8*)(lds + PG8_SA(b, h) + aoff + m * 2048 + k * 1024); } while (0)
; #define PG8_MMA(ai, bj, At, Bt) do { __builtin_amdgcn_s_setprio(1); _Pragma("unroll") for (int m = 0; m < 4; ++m) _Pragma("unroll") for (int n = 0; n < 2; ++n) _Pragma("unroll") for (int k = 0; k < 2; ++k) \
;         acc[ai][bj][m][n] = __builtin_amdgcn_mfma_f32_16x16x32_bf16(Bt[n][k], At[m][k], acc[ai][bj][m][n], 0, 0, 0); __builtin_amdgcn_s_setprio(0); } while (0)
; #define PG8_WAIT_V(n) asm volatile("s_waitcnt vmcnt(" #n ")" ::: "memory")
; #define PG8_WAIT_L(n) asm volatile("s_waitcnt lgkmcnt(" #n ")" ::: "memory")
; #define PG8_BAR __builtin_amdgcn_s_barrier()
; #define PG8_SCHED __builtin_amdgcn_sched_barrier(0)
; template <class Epi, class Sched, bool ALIGN_EPI = false, bool SP2 = false>
; __device__ __forceinline__ void gemm_phase(PG8_LAS unsigned char* lds, const Gemm g, const Sched& S, const Epi& E) {
;     ...
;             PG8_LDA(At, 1, 1); PG8_STAGE(PG8_SB(1, 0), b3, voffB); PG8_STAGE(PG8_SB(1, 1), b3 + hstep, voffB); PG8_STAGE(PG8_SA(1, 0), a3, voffA);
;             PG8_WAIT_V(8); PG8_WAIT_L(0); PG8_BAR; PG8_MMA(1, 0, At, B0); PG8_MMA(1, 1, At, B1); PG8_BAR; PG8_SCHED;
	s_add_i32 s26, s49, s28
	v_lshl_add_u64 v[218:219], v[218:219], 0, s[16:17]
	s_mov_b32 m0, s26
	ds_read_b128 v[184:187], v153 offset:49152
	ds_read_b128 v[188:191], v153 offset:50176
	ds_read_b128 v[192:195], v153 offset:51200
	ds_read_b128 v[198:201], v153 offset:52224
	ds_read_b128 v[202:205], v153 offset:53248
	ds_read_b128 v[206:209], v153 offset:54272
	ds_read_b128 v[210:213], v153 offset:55296
	ds_read_b128 v[214:217], v153 offset:56320
	global_load_lds_dwordx4 v[218:219], off
	s_add_i32 m0, s26, 0x2000
	s_add_u32 s24, s24, 0xb0080
	v_lshl_add_u64 v[218:219], v[220:221], 0, s[16:17]
	s_addc_u32 s25, s25, 0
	s_add_i32 s26, s50, s28
	global_load_lds_dwordx4 v[218:219], off
	v_lshl_add_u64 v[218:219], s[24:25], 0, v[130:131]
	s_mov_b32 m0, s26
	s_nop 0
	global_load_lds_dwordx4 v[218:219], off
	v_lshl_add_u64 v[218:219], s[24:25], 0, v[134:135]
	s_add_i32 m0, s26, 0x2000
	s_nop 0
	global_load_lds_dwordx4 v[218:219], off
	v_lshl_add_u64 v[218:219], v[222:223], 0, s[16:17]
	s_mov_b32 m0, s37
	s_nop 0
	global_load_lds_dwordx4 v[218:219], off
	v_lshl_add_u64 v[218:219], v[224:225], 0, s[16:17]
	s_mov_b32 m0, s38
	s_nop 0
	global_load_lds_dwordx4 v[218:219], off
	s_waitcnt vmcnt(8)
	s_waitcnt lgkmcnt(0)
	s_barrier
	s_setprio 1
	s_waitcnt lgkmcnt(0)
	v_mfma_f32_16x16x32_bf16 v[60:63], v[144:147], v[184:187], v[60:63]
	v_mfma_f32_16x16x32_bf16 v[44:47], v[144:147], v[192:195], v[44:47]
	v_mfma_f32_16x16x32_bf16 v[28:31], v[144:147], v[202:205], v[28:31]
	v_mfma_f32_16x16x32_bf16 v[12:15], v[144:147], v[210:213], v[12:15]
	v_mfma_f32_16x16x32_bf16 v[8:11], v[160:163], v[210:213], v[8:11]
	v_mfma_f32_16x16x32_bf16 v[24:27], v[160:163], v[202:205], v[24:27]
	v_mfma_f32_16x16x32_bf16 v[40:43], v[160:163], v[192:195], v[40:43]
	v_mfma_f32_16x16x32_bf16 v[56:59], v[160:163], v[184:187], v[56:59]
	v_mfma_f32_16x16x32_bf16 v[60:63], v[156:159], v[188:191], v[60:63]
	v_mfma_f32_16x16x32_bf16 v[44:47], v[156:159], v[198:201], v[44:47]
	v_mfma_f32_16x16x32_bf16 v[28:31], v[156:159], v[206:209], v[28:31]
	v_mfma_f32_16x16x32_bf16 v[12:15], v[156:159], v[214:217], v[12:15]
	v_mfma_f32_16x16x32_bf16 v[8:11], v[164:167], v[214:217], v[8:11]
	v_mfma_f32_16x16x32_bf16 v[24:27], v[164:167], v[206:209], v[24:27]
	v_mfma_f32_16x16x32_bf16 v[40:43], v[164:167], v[198:201], v[40:43]
	v_mfma_f32_16x16x32_bf16 v[56:59], v[164:167], v[188:191], v[56:59]
	s_setprio 0
	s_setprio 1
	v_mfma_f32_16x16x32_bf16 v[52:55], v[168:171], v[184:187], v[52:55]
	v_mfma_f32_16x16x32_bf16 v[36:39], v[168:171], v[192:195], v[36:39]
	v_mfma_f32_16x16x32_bf16 v[20:23], v[168:171], v[202:205], v[20:23]
	v_mfma_f32_16x16x32_bf16 v[4:7], v[168:171], v[210:213], v[4:7]
	v_mfma_f32_16x16x32_bf16 v[0:3], v[176:179], v[210:213], v[0:3]
	v_mfma_f32_16x16x32_bf16 v[16:19], v[176:179], v[202:205], v[16:19]
	v_mfma_f32_16x16x32_bf16 v[32:35], v[176:179], v[192:195], v[32:35]
	v_mfma_f32_16x16x32_bf16 v[48:51], v[176:179], v[184:187], v[48:51]
	v_mfma_f32_16x16x32_bf16 v[52:55], v[172:175], v[188:191], v[52:55]
	v_mfma_f32_16x16x32_bf16 v[36:39], v[172:175], v[198:201], v[36:39]
	v_mfma_f32_16x16x32_bf16 v[20:23], v[172:175], v[206:209], v[20:23]
	v_mfma_f32_16x16x32_bf16 v[4:7], v[172:175], v[214:217], v[4:7]
	v_mfma_f32_16x16x32_bf16 v[0:3], v[180:183], v[214:217], v[0:3]
	v_mfma_f32_16x16x32_bf16 v[16:19], v[180:183], v[206:209], v[16:19]
	v_mfma_f32_16x16x32_bf16 v[32:35], v[180:183], v[198:201], v[32:35]
	v_mfma_f32_16x16x32_bf16 v[48:51], v[180:183], v[188:191], v[48:51]
	s_setprio 0
	s_barrier
	s_add_i32 s48, s48, 2
	s_add_u32 s22, s22, 0x100
	s_addc_u32 s23, s23, 0
	s_add_u32 s46, s46, 0x100
	s_addc_u32 s47, s47, 0
	s_cmp_gt_u32 s48, 41
	s_cbranch_scc0 .LBB0_370
	s_branch .Lrw3_x

; #define PG8_STAGE(bufoff, gbase, voff) do { _Pragma("unroll") for (int _i = 0; _i < 2; ++_i) \
;         __builtin_amdgcn_global_load_lds((const unsigned*)((const char*)(gbase) + (voff)[_i]), (PG8_LAS unsigned*)(lds + (bufoff) + ldsw + _i * 8192), 16, 0, 0); } while (0)
; #define PG8_LDA(dst, b, h) do { _Pragma("unroll") for (int m = 0; m < 4; ++m) _Pragma("unroll") for (int k = 0; k < 2; ++k) dst[m][k] = *(const PG8_LAS bf16x8*)(lds + PG8_SA(b, h) + aoff + m * 2048 + k * 1024); } while (0)
; #define PG8_LDB(dst, b, h) do { _Pragma("unroll") for (int n = 0; n < 2; ++n) _Pragma("unroll") for (int k = 0; k < 2; ++k) dst[n][k] = *(const PG8_LAS bf16x8*)(lds + PG8_SB(b, h) + boff + n * 2048 + k * 1024); } while (0)
; #define PG8_MMA(ai, bj, At, Bt) do { __builtin_amdgcn_s_setprio(1); _Pragma("unroll") for (int m = 0; m < 4; ++m) _Pragma("unroll") for (int n = 0; n < 2; ++n) _Pragma("unroll") for (int k = 0; k < 2; ++k) \
;         acc[ai][bj][m][n] = __builtin_amdgcn_mfma_f32_16x16x32_bf16(Bt[n][k], At[m][k], acc[ai][bj][m][n], 0, 0, 0); __builtin_amdgcn_s_setprio(0); } while (0)
; #define PG8_WAIT_V(n) asm volatile("s_waitcnt vmcnt(" #n ")" ::: "memory")
; #define PG8_WAIT_L(n) asm volatile("s_waitcnt lgkmcnt(" #n ")" ::: "memory")
; #define PG8_BAR __builtin_amdgcn_s_barrier()
; #define PG8_SCHED __builtin_amdgcn_sched_barrier(0)
; template <class Epi, class Sched, bool ALIGN_EPI = false, bool SP2 = false>
; __device__ __forceinline__ void gemm_phase(PG8_LAS unsigned char* lds, const Gemm g, const Sched& S, const Epi& E) {
;     ...
;             PG8_LDB(B0, 0, 0); PG8_LDB(B1, 0, 1); PG8_SCHED; PG8_LDA(At, 0, 0); PG8_STAGE(PG8_SA(1, 1), a1 + hstep, voffA);
;             PG8_WAIT_V(8); PG8_WAIT_L(0); PG8_BAR; PG8_MMA(0, 0, At, B0); PG8_MMA(0, 1, At, B1); PG8_BAR; PG8_SCHED;
;             PG8_LDA(At, 0, 1); PG8_STAGE(PG8_SB(0, 0), b2, voffB); PG8_STAGE(PG8_SB(0, 1), b2 + hstep, voffB); PG8_STAGE(PG8_SA(0, 0), a2, voffA);
;             PG8_WAIT_V(8); PG8_WAIT_L(0); PG8_BAR; PG8_MMA(1, 0, At, B0); PG8_MMA(1, 1, At, B1); PG8_BAR; PG8_SCHED;
.Lrw1_b0:
	s_waitcnt lgkmcnt(0)
	s_barrier
	s_setprio 1
	s_waitcnt lgkmcnt(0)
	v_mfma_f32_16x16x32_bf16 v[124:127], v[144:147], v[186:189], v[124:127]
	v_mfma_f32_16x16x32_bf16 v[116:119], v[144:147], v[198:201], v[116:119]
	v_mfma_f32_16x16x32_bf16 v[108:111], v[144:147], v[206:209], v[108:111]
	v_mfma_f32_16x16x32_bf16 v[100:103], v[144:147], v[214:217], v[100:103]
	v_mfma_f32_16x16x32_bf16 v[96:99], v[162:165], v[214:217], v[96:99]
	v_mfma_f32_16x16x32_bf16 v[104:107], v[162:165], v[206:209], v[104:107]
	v_mfma_f32_16x16x32_bf16 v[112:115], v[162:165], v[198:201], v[112:115]
	v_mfma_f32_16x16x32_bf16 v[120:123], v[162:165], v[186:189], v[120:123]
	v_mfma_f32_16x16x32_bf16 v[124:127], v[148:151], v[190:193], v[124:127]
	v_mfma_f32_16x16x32_bf16 v[116:119], v[148:151], v[202:205], v[116:119]
	v_mfma_f32_16x16x32_bf16 v[108:111], v[148:151], v[210:213], v[108:111]
	v_mfma_f32_16x16x32_bf16 v[100:103], v[148:151], v[218:221], v[100:103]
	v_mfma_f32_16x16x32_bf16 v[96:99], v[166:169], v[218:221], v[96:99]
	v_mfma_f32_16x16x32_bf16 v[104:107], v[166:169], v[210:213], v[104:107]
	v_mfma_f32_16x16x32_bf16 v[112:115], v[166:169], v[202:205], v[112:115]
	v_mfma_f32_16x16x32_bf16 v[120:123], v[166:169], v[190:193], v[120:123]
	s_setprio 0
	s_setprio 1
	v_mfma_f32_16x16x32_bf16 v[64:67], v[170:173], v[186:189], v[64:67]
	v_mfma_f32_16x16x32_bf16 v[52:55], v[170:173], v[198:201], v[52:55]
	v_mfma_f32_16x16x32_bf16 v[44:47], v[170:173], v[206:209], v[44:47]
	v_mfma_f32_16x16x32_bf16 v[36:39], v[170:173], v[214:217], v[36:39]
	v_mfma_f32_16x16x32_bf16 v[32:35], v[178:181], v[214:217], v[32:35]
	v_mfma_f32_16x16x32_bf16 v[40:43], v[178:181], v[206:209], v[40:43]
	v_mfma_f32_16x16x32_bf16 v[48:51], v[178:181], v[198:201], v[48:51]
	v_mfma_f32_16x16x32_bf16 v[56:59], v[178:181], v[186:189], v[56:59]
	v_mfma_f32_16x16x32_bf16 v[64:67], v[174:177], v[190:193], v[64:67]
	v_mfma_f32_16x16x32_bf16 v[52:55], v[174:177], v[202:205], v[52:55]
	v_mfma_f32_16x16x32_bf16 v[44:47], v[174:177], v[210:213], v[44:47]
	v_mfma_f32_16x16x32_bf16 v[36:39], v[174:177], v[218:221], v[36:39]
	v_mfma_f32_16x16x32_bf16 v[32:35], v[182:185], v[218:221], v[32:35]
	v_mfma_f32_16x16x32_bf16 v[40:43], v[182:185], v[210:213], v[40:43]
	v_mfma_f32_16x16x32_bf16 v[48:51], v[182:185], v[202:205], v[48:51]
	v_mfma_f32_16x16x32_bf16 v[56:59], v[182:185], v[190:193], v[56:59]
	s_setprio 0
	s_barrier
	s_add_i32 s54, s47, s33
	v_lshl_add_u64 v[194:195], s[34:35], 0, v[130:131]
	s_mov_b32 m0, s54
	ds_read_b128 v[186:189], v159 offset:16384
	ds_read_b128 v[190:193], v159 offset:17408
	ds_read_b128 v[198:201], v159 offset:18432
	ds_read_b128 v[202:205], v159 offset:19456
	ds_read_b128 v[206:209], v159 offset:20480
	ds_read_b128 v[210:213], v159 offset:21504
	ds_read_b128 v[214:217], v159 offset:22528
	ds_read_b128 v[218:221], v159 offset:23552
	global_load_lds_dwordx4 v[194:195], off
	s_add_i32 m0, s54, 0x2000
	s_add_u32 s54, s34, 0x40000
	v_lshl_add_u64 v[222:223], s[34:35], 0, v[134:135]
	s_addc_u32 s55, s35, 0
	s_add_i32 s56, s48, s33
	global_load_lds_dwordx4 v[222:223], off
	v_lshl_add_u64 v[224:225], s[54:55], 0, v[130:131]
	s_mov_b32 m0, s56
	v_lshl_add_u64 v[226:227], s[36:37], 0, v[132:133]
	global_load_lds_dwordx4 v[224:225], off
	v_lshl_add_u64 v[224:225], s[54:55], 0, v[134:135]
	s_add_i32 m0, s56, 0x2000
	s_nop 0
	global_load_lds_dwordx4 v[224:225], off
	v_lshl_add_u64 v[224:225], s[36:37], 0, v[128:129]
	s_mov_b32 m0, s29
	s_nop 0
	global_load_lds_dwordx4 v[224:225], off
	s_mov_b32 m0, s38
	s_nop 0
	global_load_lds_dwordx4 v[226:227], off
	s_cmp_eq_u32 s53, s101
	s_cbranch_scc1 .Lrw1_r1
	s_waitcnt vmcnt(8)
.Lrw1_b1:
	s_waitcnt lgkmcnt(0)
	s_barrier
	s_setprio 1
	s_waitcnt lgkmcnt(0)
	v_mfma_f32_16x16x32_bf16 v[92:95], v[144:147], v[186:189], v[92:95]
	v_mfma_f32_16x16x32_bf16 v[84:87], v[144:147], v[198:201], v[84:87]
	v_mfma_f32_16x16x32_bf16 v[76:79], v[144:147], v[206:209], v[76:79]
	v_mfma_f32_16x16x32_bf16 v[68:71], v[144:147], v[214:217], v[68:71]
	v_mfma_f32_16x16x32_bf16 v[60:63], v[162:165], v[214:217], v[60:63]
	v_mfma_f32_16x16x32_bf16 v[72:75], v[162:165], v[206:209], v[72:75]
	v_mfma_f32_16x16x32_bf16 v[80:83], v[162:165], v[198:201], v[80:83]
	v_mfma_f32_16x16x32_bf16 v[88:91], v[162:165], v[186:189], v[88:91]
	v_mfma_f32_16x16x32_bf16 v[92:95], v[148:151], v[190:193], v[92:95]
	v_mfma_f32_16x16x32_bf16 v[84:87], v[148:151], v[202:205], v[84:87]
	v_mfma_f32_16x16x32_bf16 v[76:79], v[148:151], v[210:213], v[76:79]
	v_mfma_f32_16x16x32_bf16 v[68:71], v[148:151], v[218:221], v[68:71]
	v_mfma_f32_16x16x32_bf16 v[60:63], v[166:169], v[218:221], v[60:63]
	v_mfma_f32_16x16x32_bf16 v[72:75], v[166:169], v[210:213], v[72:75]
	v_mfma_f32_16x16x32_bf16 v[80:83], v[166:169], v[202:205], v[80:83]
	v_mfma_f32_16x16x32_bf16 v[88:91], v[166:169], v[190:193], v[88:91]
	s_setprio 0
	s_setprio 1
	v_mfma_f32_16x16x32_bf16 v[28:31], v[170:173], v[186:189], v[28:31]
	v_mfma_f32_16x16x32_bf16 v[20:23], v[170:173], v[198:201], v[20:23]
	v_mfma_f32_16x16x32_bf16 v[12:15], v[170:173], v[206:209], v[12:15]
	v_mfma_f32_16x16x32_bf16 v[4:7], v[170:173], v[214:217], v[4:7]
	v_mfma_f32_16x16x32_bf16 v[0:3], v[178:181], v[214:217], v[0:3]
	v_mfma_f32_16x16x32_bf16 v[8:11], v[178:181], v[206:209], v[8:11]
	v_mfma_f32_16x16x32_bf16 v[16:19], v[178:181], v[198:201], v[16:19]
	v_mfma_f32_16x16x32_bf16 v[24:27], v[178:181], v[186:189], v[24:27]
	v_mfma_f32_16x16x32_bf16 v[28:31], v[174:177], v[190:193], v[28:31]
	v_mfma_f32_16x16x32_bf16 v[20:23], v[174:177], v[202:205], v[20:23]
	v_mfma_f32_16x16x32_bf16 v[12:15], v[174:177], v[210:213], v[12:15]
	v_mfma_f32_16x16x32_bf16 v[4:7], v[174:177], v[218:221], v[4:7]
	v_mfma_f32_16x16x32_bf16 v[0:3], v[182:185], v[218:221], v[0:3]
	v_mfma_f32_16x16x32_bf16 v[8:11], v[182:185], v[210:213], v[8:11]
	v_mfma_f32_16x16x32_bf16 v[16:19], v[182:185], v[202:205], v[16:19]
	v_mfma_f32_16x16x32_bf16 v[24:27], v[182:185], v[190:193], v[24:27]
	s_setprio 0
	s_barrier
; #define PG8_STAGE(bufoff, gbase, voff) do { _Pragma("unroll") for (int _i = 0; _i < 2; ++_i) \
;         __builtin_amdgcn_global_load_lds((const unsigned*)((const char*)(gbase) + (voff)[_i]), (PG8_LAS unsigned*)(lds + (bufoff) + ldsw + _i * 8192), 16, 0, 0); } while (0)
; #define PG8_LDA(dst, b, h) do { _Pragma("unroll") for (int m = 0; m < 4; ++m) _Pragma("unroll") for (int k = 0; k < 2; ++k) dst[m][k] = *(const PG8_LAS bf16x8*)(lds + PG8_SA(b, h) + aoff + m * 2048 + k * 1024); } while (0)
; #define PG8_LDB(dst, b, h) do { _Pragma("unroll") for (int n = 0; n < 2; ++n) _Pragma("unroll") for (int k = 0; k < 2; ++k) dst[n][k] = *(const PG8_LAS bf16x8*)(lds + PG8_SB(b, h) + boff + n * 2048 + k * 1024); } while (0)
; #define PG8_MMA(ai, bj, At, Bt) do { __builtin_amdgcn_s_setprio(1); _Pragma("unroll") for (int m = 0; m < 4; ++m) _Pragma("unroll") for (int n = 0; n < 2; ++n) _Pragma("unroll") for (int k = 0; k < 2; ++k) \
;         acc[ai][bj][m][n] = __builtin_amdgcn_mfma_f32_16x16x32_bf16(Bt[n][k], At[m][k], acc[ai][bj][m][n], 0, 0, 0); __builtin_amdgcn_s_setprio(0); } while (0)
; #define PG8_WAIT_V(n) asm volatile("s_waitcnt vmcnt(" #n ")" ::: "memory")
; #define PG8_WAIT_L(n) asm volatile("s_waitcnt lgkmcnt(" #n ")" ::: "memory")
; #define PG8_BAR __builtin_amdgcn_s_barrier()
; #define PG8_SCHED __builtin_amdgcn_sched_barrier(0)
; template <class Epi, class Sched, bool ALIGN_EPI = false, bool SP2 = false>
; __device__ __forceinline__ void gemm_phase(PG8_LAS unsigned char* lds, const Gemm g, const Sched& S, const Epi& E) {
;     ...
;             PG8_LDB(B0, 1, 0); PG8_LDB(B1, 1, 1); PG8_SCHED; PG8_LDA(At, 1, 0); PG8_STAGE(PG8_SA(0, 1), a2 + hstep, voffA);
;             PG8_WAIT_V(8); PG8_WAIT_L(0); PG8_BAR; PG8_MMA(0, 0, At, B0); PG8_MMA(0, 1, At, B1); PG8_BAR; PG8_SCHED;
	s_add_i32 s54, 0, 0x18000
	v_add_u32_e32 v152, s54, v155
	s_add_i32 s55, 0, 0x1c000
	ds_read_b128 v[144:147], v152
	ds_read_b128 v[148:151], v152 offset:1024
	ds_read_b128 v[162:165], v152 offset:2048
	ds_read_b128 v[166:169], v152 offset:3072
	v_add_u32_e32 v152, s55, v155
	ds_read_b128 v[170:173], v152
	ds_read_b128 v[174:177], v152 offset:1024
	ds_read_b128 v[178:181], v152 offset:2048
	ds_read_b128 v[182:185], v152 offset:3072
	s_add_u32 s36, s36, 0x40000
	s_addc_u32 s37, s37, 0
	s_mov_b32 m0, s39
	v_lshl_add_u64 v[228:229], s[36:37], 0, v[128:129]
	ds_read_b128 v[186:189], v159 offset:32768
	ds_read_b128 v[190:193], v159 offset:33792
	ds_read_b128 v[198:201], v159 offset:34816
	ds_read_b128 v[202:205], v159 offset:35840
	ds_read_b128 v[206:209], v159 offset:36864
	ds_read_b128 v[210:213], v159 offset:37888
	ds_read_b128 v[214:217], v159 offset:38912
	ds_read_b128 v[218:221], v159 offset:39936
	global_load_lds_dwordx4 v[228:229], off
	v_lshl_add_u64 v[228:229], s[36:37], 0, v[132:133]
	s_mov_b32 m0, s40
	s_nop 0
	global_load_lds_dwordx4 v[228:229], off
	s_waitcnt vmcnt(8)
	s_waitcnt lgkmcnt(0)
	s_barrier
	s_setprio 1
	s_waitcnt lgkmcnt(0)
	v_mfma_f32_16x16x32_bf16 v[124:127], v[144:147], v[186:189], v[124:127]
	v_mfma_f32_16x16x32_bf16 v[116:119], v[144:147], v[198:201], v[116:119]
	v_mfma_f32_16x16x32_bf16 v[108:111], v[144:147], v[206:209], v[108:111]
	v_mfma_f32_16x16x32_bf16 v[100:103], v[144:147], v[214:217], v[100:103]
	v_mfma_f32_16x16x32_bf16 v[96:99], v[162:165], v[214:217], v[96:99]
	v_mfma_f32_16x16x32_bf16 v[104:107], v[162:165], v[206:209], v[104:107]
	v_mfma_f32_16x16x32_bf16 v[112:115], v[162:165], v[198:201], v[112:115]
	v_mfma_f32_16x16x32_bf16 v[120:123], v[162:165], v[186:189], v[120:123]
	v_mfma_f32_16x16x32_bf16 v[124:127], v[148:151], v[190:193], v[124:127]
	v_mfma_f32_16x16x32_bf16 v[116:119], v[148:151], v[202:205], v[116:119]
	v_mfma_f32_16x16x32_bf16 v[108:111], v[148:151], v[210:213], v[108:111]
	v_mfma_f32_16x16x32_bf16 v[100:103], v[148:151], v[218:221], v[100:103]
	v_mfma_f32_16x16x32_bf16 v[96:99], v[166:169], v[218:221], v[96:99]
	v_mfma_f32_16x16x32_bf16 v[104:107], v[166:169], v[210:213], v[104:107]
	v_mfma_f32_16x16x32_bf16 v[112:115], v[166:169], v[202:205], v[112:115]
	v_mfma_f32_16x16x32_bf16 v[120:123], v[166:169], v[190:193], v[120:123]
	s_setprio 0
	s_setprio 1
	v_mfma_f32_16x16x32_bf16 v[64:67], v[170:173], v[186:189], v[64:67]
	v_mfma_f32_16x16x32_bf16 v[52:55], v[170:173], v[198:201], v[52:55]
	v_mfma_f32_16x16x32_bf16 v[44:47], v[170:173], v[206:209], v[44:47]
	v_mfma_f32_16x16x32_bf16 v[36:39], v[170:173], v[214:217], v[36:39]
	v_mfma_f32_16x16x32_bf16 v[32:35], v[178:181], v[214:217], v[32:35]
	v_mfma_f32_16x16x32_bf16 v[40:43], v[178:181], v[206:209], v[40:43]
	v_mfma_f32_16x16x32_bf16 v[48:51], v[178:181], v[198:201], v[48:51]
	v_mfma_f32_16x16x32_bf16 v[56:59], v[178:181], v[186:189], v[56:59]
	v_mfma_f32_16x16x32_bf16 v[64:67], v[174:177], v[190:193], v[64:67]
	v_mfma_f32_16x16x32_bf16 v[52:55], v[174:177], v[202:205], v[52:55]
	v_mfma_f32_16x16x32_bf16 v[44:47], v[174:177], v[210:213], v[44:47]
	v_mfma_f32_16x16x32_bf16 v[36:39], v[174:177], v[218:221], v[36:39]
	v_mfma_f32_16x16x32_bf16 v[32:35], v[182:185], v[218:221], v[32:35]
	v_mfma_f32_16x16x32_bf16 v[40:43], v[182:185], v[210:213], v[40:43]
	v_mfma_f32_16x16x32_bf16 v[48:51], v[182:185], v[202:205], v[48:51]
	v_mfma_f32_16x16x32_bf16 v[56:59], v[182:185], v[190:193], v[56:59]
	s_setprio 0
	s_barrier
; #define PG8_STAGE(bufoff, gbase, voff) do { _Pragma("unroll") for (int _i = 0; _i < 2; ++_i) \
;         __builtin_amdgcn_global_load_lds((const unsigned*)((const char*)(gbase) + (voff)[_i]), (PG8_LAS unsigned*)(lds + (bufoff) + ldsw + _i * 8192), 16, 0, 0); } while (0)
; #define PG8_LDA(dst, b, h) do { _Pragma("unroll") for (int m = 0; m < 4; ++m) _Pragma("unroll") for (int k = 0; k < 2; ++k) dst[m][k] = *(const PG8_LAS bf16x8*)(lds + PG8_SA(b, h) + aoff + m * 2048 + k * 1024); } while (0)
; #define PG8_MMA(ai, bj, At, Bt) do { __builtin_amdgcn_s_setprio(1); _Pragma("unroll") for (int m = 0; m < 4; ++m) _Pragma("unroll") for (int n = 0; n < 2; ++n) _Pragma("unroll") for (int k = 0; k < 2; ++k) \
;         acc[ai][bj][m][n] = __builtin_amdgcn_mfma_f32_16x16x32_bf16(Bt[n][k], At[m][k], acc[ai][bj][m][n], 0, 0, 0); __builtin_amdgcn_s_setprio(0); } while (0)
; #define PG8_WAIT_V(n) asm volatile("s_waitcnt vmcnt(" #n ")" ::: "memory")
; #define PG8_WAIT_L(n) asm volatile("s_waitcnt lgkmcnt(" #n ")" ::: "memory")
; #define PG8_BAR __builtin_amdgcn_s_barrier()
; #define PG8_SCHED __builtin_amdgcn_sched_barrier(0)
; template <class Epi, class Sched, bool ALIGN_EPI = false, bool SP2 = false>
; __device__ __forceinline__ void gemm_phase(PG8_LAS unsigned char* lds, const Gemm g, const Sched& S, const Epi& E) {
;     ...
;             PG8_LDA(At, 1, 1); PG8_STAGE(PG8_SB(1, 0), b3, voffB); PG8_STAGE(PG8_SB(1, 1), b3 + hstep, voffB); PG8_STAGE(PG8_SA(1, 0), a3, voffA);
;             PG8_WAIT_V(8); PG8_WAIT_L(0); PG8_BAR; PG8_MMA(1, 0, At, B0); PG8_MMA(1, 1, At, B1); PG8_BAR; PG8_SCHED;
	s_add_i32 s36, s54, s33
	v_lshl_add_u64 v[194:195], v[194:195], 0, s[14:15]
	s_mov_b32 m0, s36
	ds_read_b128 v[186:189], v159 offset:49152
	ds_read_b128 v[190:193], v159 offset:50176
	ds_read_b128 v[198:201], v159 offset:51200
	ds_read_b128 v[202:205], v159 offset:52224
	ds_read_b128 v[206:209], v159 offset:53248
	ds_read_b128 v[210:213], v159 offset:54272
	ds_read_b128 v[214:217], v159 offset:55296
	ds_read_b128 v[218:221], v159 offset:56320
	global_load_lds_dwordx4 v[194:195], off
	s_add_i32 m0, s36, 0x2000
	s_add_u32 s34, s34, 0x40080
	v_lshl_add_u64 v[194:195], v[222:223], 0, s[14:15]
	s_addc_u32 s35, s35, 0
	s_add_i32 s36, s55, s33
	global_load_lds_dwordx4 v[194:195], off
	v_lshl_add_u64 v[194:195], s[34:35], 0, v[130:131]
	s_mov_b32 m0, s36
	s_nop 0
	global_load_lds_dwordx4 v[194:195], off
	v_lshl_add_u64 v[194:195], s[34:35], 0, v[134:135]
	s_add_i32 m0, s36, 0x2000
	s_nop 0
	global_load_lds_dwordx4 v[194:195], off
	v_lshl_add_u64 v[194:195], v[224:225], 0, s[14:15]
	s_mov_b32 m0, s44
	s_nop 0
	global_load_lds_dwordx4 v[194:195], off
	v_lshl_add_u64 v[194:195], v[226:227], 0, s[14:15]
	s_mov_b32 m0, s45
	s_nop 0
	global_load_lds_dwordx4 v[194:195], off
	s_waitcnt vmcnt(8)
	s_waitcnt lgkmcnt(0)
	s_barrier
	s_setprio 1
	s_waitcnt lgkmcnt(0)
	v_mfma_f32_16x16x32_bf16 v[92:95], v[144:147], v[186:189], v[92:95]
	v_mfma_f32_16x16x32_bf16 v[84:87], v[144:147], v[198:201], v[84:87]
	v_mfma_f32_16x16x32_bf16 v[76:79], v[144:147], v[206:209], v[76:79]
	v_mfma_f32_16x16x32_bf16 v[68:71], v[144:147], v[214:217], v[68:71]
	v_mfma_f32_16x16x32_bf16 v[60:63], v[162:165], v[214:217], v[60:63]
	v_mfma_f32_16x16x32_bf16 v[72:75], v[162:165], v[206:209], v[72:75]
	v_mfma_f32_16x16x32_bf16 v[80:83], v[162:165], v[198:201], v[80:83]
	v_mfma_f32_16x16x32_bf16 v[88:91], v[162:165], v[186:189], v[88:91]
	v_mfma_f32_16x16x32_bf16 v[92:95], v[148:151], v[190:193], v[92:95]
	v_mfma_f32_16x16x32_bf16 v[84:87], v[148:151], v[202:205], v[84:87]
	v_mfma_f32_16x16x32_bf16 v[76:79], v[148:151], v[210:213], v[76:79]
	v_mfma_f32_16x16x32_bf16 v[68:71], v[148:151], v[218:221], v[68:71]
	v_mfma_f32_16x16x32_bf16 v[60:63], v[166:169], v[218:221], v[60:63]
	v_mfma_f32_16x16x32_bf16 v[72:75], v[166:169], v[210:213], v[72:75]
	v_mfma_f32_16x16x32_bf16 v[80:83], v[166:169], v[202:205], v[80:83]
	v_mfma_f32_16x16x32_bf16 v[88:91], v[166:169], v[190:193], v[88:91]
	s_setprio 0
	s_setprio 1
	v_mfma_f32_16x16x32_bf16 v[28:31], v[170:173], v[186:189], v[28:31]
	v_mfma_f32_16x16x32_bf16 v[20:23], v[170:173], v[198:201], v[20:23]
	v_mfma_f32_16x16x32_bf16 v[12:15], v[170:173], v[206:209], v[12:15]
	v_mfma_f32_16x16x32_bf16 v[4:7], v[170:173], v[214:217], v[4:7]
	v_mfma_f32_16x16x32_bf16 v[0:3], v[178:181], v[214:217], v[0:3]
	v_mfma_f32_16x16x32_bf16 v[8:11], v[178:181], v[206:209], v[8:11]
	v_mfma_f32_16x16x32_bf16 v[16:19], v[178:181], v[198:201], v[16:19]
	v_mfma_f32_16x16x32_bf16 v[24:27], v[178:181], v[186:189], v[24:27]
	v_mfma_f32_16x16x32_bf16 v[28:31], v[174:177], v[190:193], v[28:31]
	v_mfma_f32_16x16x32_bf16 v[20:23], v[174:177], v[202:205], v[20:23]
	v_mfma_f32_16x16x32_bf16 v[12:15], v[174:177], v[210:213], v[12:15]
	v_mfma_f32_16x16x32_bf16 v[4:7], v[174:177], v[218:221], v[4:7]
	v_mfma_f32_16x16x32_bf16 v[0:3], v[182:185], v[218:221], v[0:3]
	v_mfma_f32_16x16x32_bf16 v[8:11], v[182:185], v[210:213], v[8:11]
	v_mfma_f32_16x16x32_bf16 v[16:19], v[182:185], v[202:205], v[16:19]
	v_mfma_f32_16x16x32_bf16 v[24:27], v[182:185], v[190:193], v[24:27]
	s_setprio 0
	s_barrier
	s_add_i32 s53, s53, 2
	s_add_u32 s30, s30, 0x100
	s_addc_u32 s31, s31, 0
	s_add_u32 s51, s51, 0x100
	s_addc_u32 s52, s52, 0
	s_cmp_gt_u32 s53, 13
	s_cbranch_scc0 .LBB0_525
	s_branch .Lrw1_x

; #define PG8_STAGE(bufoff, gbase, voff) do { _Pragma("unroll") for (int _i = 0; _i < 2; ++_i) \
;         __builtin_amdgcn_global_load_lds((const unsigned*)((const char*)(gbase) + (voff)[_i]), (PG8_LAS unsigned*)(lds + (bufoff) + ldsw + _i * 8192), 16, 0, 0); } while (0)
; #define PG8_LDA(dst, b, h) do { _Pragma("unroll") for (int m = 0; m < 4; ++m) _Pragma("unroll") for (int k = 0; k < 2; ++k) dst[m][k] = *(const PG8_LAS bf16x8*)(lds + PG8_SA(b, h) + aoff + m * 2048 + k * 1024); } while (0)
; #define PG8_LDB(dst, b, h) do { _Pragma("unroll") for (int n = 0; n < 2; ++n) _Pragma("unroll") for (int k = 0; k < 2; ++k) dst[n][k] = *(const PG8_LAS bf16x8*)(lds + PG8_SB(b, h) + boff + n * 2048 + k * 1024); } while (0)
; #define PG8_MMA(ai, bj, At, Bt) do { __builtin_amdgcn_s_setprio(1); _Pragma("unroll") for (int m = 0; m < 4; ++m) _Pragma("unroll") for (int n = 0; n < 2; ++n) _Pragma("unroll") for (int k = 0; k < 2; ++k) \
;         acc[ai][bj][m][n] = __builtin_amdgcn_mfma_f32_16x16x32_bf16(Bt[n][k], At[m][k], acc[ai][bj][m][n], 0, 0, 0); __builtin_amdgcn_s_setprio(0); } while (0)
; #define PG8_WAIT_V(n) asm volatile("s_waitcnt vmcnt(" #n ")" ::: "memory")
; #define PG8_BAR __builtin_amdgcn_s_barrier()
; template <class Epi, class Sched, bool ALIGN_EPI = false, bool SP2 = false>
; __device__ __forceinline__ void gemm_phase(PG8_LAS unsigned char* lds, const Gemm g, const Sched& S, const Epi& E) {
;     ...
;         for (int t = 0; t < nt; t += 2) {
;             const bool last = (t == nt - 2);
;             const char* a1 = cA + (size_t)(t + 1) * kstep;
;             const char* a2 = last ? nA : cA + (size_t)(t + 2) * kstep; const char* b2 = last ? nB : cB + (size_t)(t + 2) * kstep;
;             const char* a3 = a2 + kstep; const char* b3 = b2 + kstep;
;             if (last && has_next) S.a_ready(nxt);
;             if constexpr (SP2) {
;             PG8_LDB(B0, 0, 0); PG8_LDB(B1, 0, 1); PG8_SCHED; PG8_LDA(At, 0, 0); PG8_STAGE(PG8_SA(1, 1), a1 + hstep, voffA);
;             PG8_WAIT_V(8); PG8_WAIT_L(0); PG8_BAR; PG8_MMA(0, 0, At, B0); PG8_MMA(0, 1, At, B1); PG8_BAR; PG8_SCHED;
;             PG8_LDA(At, 0, 1); PG8_STAGE(PG8_SB(0, 0), b2, voffB); PG8_STAGE(PG8_SB(0, 1), b2 + hstep, voffB); PG8_STAGE(PG8_SA(0, 0), a2, voffA);
;             PG8_WAIT_V(8); PG8_WAIT_L(0); PG8_BAR; PG8_MMA(1, 0, At, B0); PG8_MMA(1, 1, At, B1); PG8_BAR; PG8_SCHED;
.LBB0_706:
	ds_read_b128 v[164:167], v161
	ds_read_b128 v[168:171], v161 offset:1024
	ds_read_b128 v[172:175], v161 offset:2048
	ds_read_b128 v[176:179], v161 offset:3072
	ds_read_b128 v[180:183], v162
	ds_read_b128 v[184:187], v162 offset:1024
	ds_read_b128 v[188:191], v162 offset:2048
	ds_read_b128 v[192:195], v162 offset:3072
	s_add_i32 s54, s26, 2
	s_add_u32 s55, s24, 0x80
	s_addc_u32 s27, s25, 0
	s_cmp_eq_u32 s43, s26
	s_cselect_b32 s26, s4, s55
	s_cselect_b32 s27, s5, s27
	s_cselect_b32 s57, s23, s53
	s_cselect_b32 s56, s22, s52
	s_mov_b32 m0, s47
	v_lshl_add_u64 v[230:231], s[24:25], 0, v[136:137]
	ds_read_b128 v[198:201], v163
	ds_read_b128 v[202:205], v163 offset:1024
	ds_read_b128 v[206:209], v163 offset:2048
	ds_read_b128 v[210:213], v163 offset:3072
	ds_read_b128 v[214:217], v163 offset:4096
	ds_read_b128 v[218:221], v163 offset:5120
	ds_read_b128 v[222:225], v163 offset:6144
	ds_read_b128 v[226:229], v163 offset:7168
	global_load_lds_dwordx4 v[230:231], off
	v_lshl_add_u64 v[230:231], s[24:25], 0, v[138:139]
	s_add_i32 m0, s35, 0xe000
	s_nop 0
	global_load_lds_dwordx4 v[230:231], off
	s_waitcnt vmcnt(8)
	s_waitcnt lgkmcnt(0)
	s_barrier
	s_setprio 1
	s_waitcnt lgkmcnt(0)
	v_mfma_f32_16x16x32_bf16 v[124:127], v[164:167], v[198:201], v[124:127]
	v_mfma_f32_16x16x32_bf16 v[116:119], v[164:167], v[206:209], v[116:119]
	v_mfma_f32_16x16x32_bf16 v[108:111], v[164:167], v[214:217], v[108:111]
	v_mfma_f32_16x16x32_bf16 v[100:103], v[164:167], v[222:225], v[100:103]
	v_mfma_f32_16x16x32_bf16 v[96:99], v[172:175], v[222:225], v[96:99]
	v_mfma_f32_16x16x32_bf16 v[104:107], v[172:175], v[214:217], v[104:107]
	v_mfma_f32_16x16x32_bf16 v[112:115], v[172:175], v[206:209], v[112:115]
	v_mfma_f32_16x16x32_bf16 v[120:123], v[172:175], v[198:201], v[120:123]
	v_mfma_f32_16x16x32_bf16 v[124:127], v[168:171], v[202:205], v[124:127]
	v_mfma_f32_16x16x32_bf16 v[116:119], v[168:171], v[210:213], v[116:119]
	v_mfma_f32_16x16x32_bf16 v[108:111], v[168:171], v[218:221], v[108:111]
	v_mfma_f32_16x16x32_bf16 v[100:103], v[168:171], v[226:229], v[100:103]
	v_mfma_f32_16x16x32_bf16 v[96:99], v[176:179], v[226:229], v[96:99]
	v_mfma_f32_16x16x32_bf16 v[104:107], v[176:179], v[218:221], v[104:107]
	v_mfma_f32_16x16x32_bf16 v[112:115], v[176:179], v[210:213], v[112:115]
	v_mfma_f32_16x16x32_bf16 v[120:123], v[176:179], v[202:205], v[120:123]
	s_setprio 0
	s_setprio 1
	v_mfma_f32_16x16x32_bf16 v[60:63], v[180:183], v[198:201], v[60:63]
	v_mfma_f32_16x16x32_bf16 v[52:55], v[180:183], v[206:209], v[52:55]
	v_mfma_f32_16x16x32_bf16 v[44:47], v[180:183], v[214:217], v[44:47]
	v_mfma_f32_16x16x32_bf16 v[36:39], v[180:183], v[222:225], v[36:39]
	v_mfma_f32_16x16x32_bf16 v[32:35], v[188:191], v[222:225], v[32:35]
	v_mfma_f32_16x16x32_bf16 v[40:43], v[188:191], v[214:217], v[40:43]
	v_mfma_f32_16x16x32_bf16 v[48:51], v[188:191], v[206:209], v[48:51]
	v_mfma_f32_16x16x32_bf16 v[56:59], v[188:191], v[198:201], v[56:59]
	v_mfma_f32_16x16x32_bf16 v[60:63], v[184:187], v[202:205], v[60:63]
	v_mfma_f32_16x16x32_bf16 v[52:55], v[184:187], v[210:213], v[52:55]
	v_mfma_f32_16x16x32_bf16 v[44:47], v[184:187], v[218:221], v[44:47]
	v_mfma_f32_16x16x32_bf16 v[36:39], v[184:187], v[226:229], v[36:39]
	v_mfma_f32_16x16x32_bf16 v[32:35], v[192:195], v[226:229], v[32:35]
	v_mfma_f32_16x16x32_bf16 v[40:43], v[192:195], v[218:221], v[40:43]
	v_mfma_f32_16x16x32_bf16 v[48:51], v[192:195], v[210:213], v[48:51]
	v_mfma_f32_16x16x32_bf16 v[56:59], v[192:195], v[202:205], v[56:59]
	s_setprio 0
	s_barrier
	s_add_i32 s55, s44, s34
	v_lshl_add_u64 v[230:231], s[56:57], 0, v[132:133]
	s_mov_b32 m0, s55
	ds_read_b128 v[198:201], v163 offset:16384
	ds_read_b128 v[202:205], v163 offset:17408
	ds_read_b128 v[206:209], v163 offset:18432
	ds_read_b128 v[210:213], v163 offset:19456
	ds_read_b128 v[214:217], v163 offset:20480
	ds_read_b128 v[218:221], v163 offset:21504
	ds_read_b128 v[222:225], v163 offset:22528
	ds_read_b128 v[226:229], v163 offset:23552
	global_load_lds_dwordx4 v[230:231], off
	s_add_i32 m0, s55, 0x2000
	v_lshl_add_u64 v[232:233], s[56:57], 0, v[128:129]
	s_add_u32 s56, s56, s10
	s_addc_u32 s57, s57, s11
	s_add_i32 s55, s45, s34
	global_load_lds_dwordx4 v[232:233], off
	v_lshl_add_u64 v[234:235], s[56:57], 0, v[132:133]
	s_mov_b32 m0, s55
	v_lshl_add_u64 v[236:237], s[56:57], 0, v[128:129]
	global_load_lds_dwordx4 v[234:235], off
	s_add_i32 m0, s55, 0x2000
	v_lshl_add_u64 v[238:239], s[26:27], 0, v[134:135]
	global_load_lds_dwordx4 v[236:237], off
	s_mov_b32 m0, s35
	v_lshl_add_u64 v[240:241], s[26:27], 0, v[130:131]
	global_load_lds_dwordx4 v[238:239], off
	s_mov_b32 m0, s36
	s_nop 0
	global_load_lds_dwordx4 v[240:241], off
	s_waitcnt vmcnt(8)
	s_waitcnt lgkmcnt(0)
	s_barrier
; #define PG8_STAGE(bufoff, gbase, voff) do { _Pragma("unroll") for (int _i = 0; _i < 2; ++_i) \
;         __builtin_amdgcn_global_load_lds((const unsigned*)((const char*)(gbase) + (voff)[_i]), (PG8_LAS unsigned*)(lds + (bufoff) + ldsw + _i * 8192), 16, 0, 0); } while (0)
; #define PG8_LDA(dst, b, h) do { _Pragma("unroll") for (int m = 0; m < 4; ++m) _Pragma("unroll") for (int k = 0; k < 2; ++k) dst[m][k] = *(const PG8_LAS bf16x8*)(lds + PG8_SA(b, h) + aoff + m * 2048 + k * 1024); } while (0)
; #define PG8_LDB(dst, b, h) do { _Pragma("unroll") for (int n = 0; n < 2; ++n) _Pragma("unroll") for (int k = 0; k < 2; ++k) dst[n][k] = *(const PG8_LAS bf16x8*)(lds + PG8_SB(b, h) + boff + n * 2048 + k * 1024); } while (0)
; #define PG8_MMA(ai, bj, At, Bt) do { __builtin_amdgcn_s_setprio(1); _Pragma("unroll") for (int m = 0; m < 4; ++m) _Pragma("unroll") for (int n = 0; n < 2; ++n) _Pragma("unroll") for (int k = 0; k < 2; ++k) \
;         acc[ai][bj][m][n] = __builtin_amdgcn_mfma_f32_16x16x32_bf16(Bt[n][k], At[m][k], acc[ai][bj][m][n], 0, 0, 0); __builtin_amdgcn_s_setprio(0); } while (0)
; #define PG8_WAIT_V(n) asm volatile("s_waitcnt vmcnt(" #n ")" ::: "memory")
; #define PG8_WAIT_L(n) asm volatile("s_waitcnt lgkmcnt(" #n ")" ::: "memory")
; #define PG8_BAR __builtin_amdgcn_s_barrier()
; #define PG8_SCHED __builtin_amdgcn_sched_barrier(0)
; template <class Epi, class Sched, bool ALIGN_EPI = false, bool SP2 = false>
; __device__ __forceinline__ void gemm_phase(PG8_LAS unsigned char* lds, const Gemm g, const Sched& S, const Epi& E) {
;     ...
;             PG8_WAIT_V(8); PG8_WAIT_L(0); PG8_BAR; PG8_MMA(1, 0, At, B0); PG8_MMA(1, 1, At, B1); PG8_BAR; PG8_SCHED;
;             PG8_LDB(B0, 1, 0); PG8_LDB(B1, 1, 1); PG8_SCHED; PG8_LDA(At, 1, 0); PG8_STAGE(PG8_SA(0, 1), a2 + hstep, voffA);
;             PG8_WAIT_V(8); PG8_WAIT_L(0); PG8_BAR; PG8_MMA(0, 0, At, B0); PG8_MMA(0, 1, At, B1); PG8_BAR; PG8_SCHED;
	s_setprio 1
	s_waitcnt lgkmcnt(0)
	v_mfma_f32_16x16x32_bf16 v[92:95], v[164:167], v[198:201], v[92:95]
	v_mfma_f32_16x16x32_bf16 v[84:87], v[164:167], v[206:209], v[84:87]
	v_mfma_f32_16x16x32_bf16 v[76:79], v[164:167], v[214:217], v[76:79]
	v_mfma_f32_16x16x32_bf16 v[68:71], v[164:167], v[222:225], v[68:71]
	v_mfma_f32_16x16x32_bf16 v[64:67], v[172:175], v[222:225], v[64:67]
	v_mfma_f32_16x16x32_bf16 v[72:75], v[172:175], v[214:217], v[72:75]
	v_mfma_f32_16x16x32_bf16 v[80:83], v[172:175], v[206:209], v[80:83]
	v_mfma_f32_16x16x32_bf16 v[88:91], v[172:175], v[198:201], v[88:91]
	v_mfma_f32_16x16x32_bf16 v[92:95], v[168:171], v[202:205], v[92:95]
	v_mfma_f32_16x16x32_bf16 v[84:87], v[168:171], v[210:213], v[84:87]
	v_mfma_f32_16x16x32_bf16 v[76:79], v[168:171], v[218:221], v[76:79]
	v_mfma_f32_16x16x32_bf16 v[68:71], v[168:171], v[226:229], v[68:71]
	v_mfma_f32_16x16x32_bf16 v[64:67], v[176:179], v[226:229], v[64:67]
	v_mfma_f32_16x16x32_bf16 v[72:75], v[176:179], v[218:221], v[72:75]
	v_mfma_f32_16x16x32_bf16 v[80:83], v[176:179], v[210:213], v[80:83]
	v_mfma_f32_16x16x32_bf16 v[88:91], v[176:179], v[202:205], v[88:91]
	s_setprio 0
	s_setprio 1
	v_mfma_f32_16x16x32_bf16 v[28:31], v[180:183], v[198:201], v[28:31]
	v_mfma_f32_16x16x32_bf16 v[20:23], v[180:183], v[206:209], v[20:23]
	v_mfma_f32_16x16x32_bf16 v[12:15], v[180:183], v[214:217], v[12:15]
	v_mfma_f32_16x16x32_bf16 v[4:7], v[180:183], v[222:225], v[4:7]
	v_mfma_f32_16x16x32_bf16 v[0:3], v[188:191], v[222:225], v[0:3]
	v_mfma_f32_16x16x32_bf16 v[8:11], v[188:191], v[214:217], v[8:11]
	v_mfma_f32_16x16x32_bf16 v[16:19], v[188:191], v[206:209], v[16:19]
	v_mfma_f32_16x16x32_bf16 v[24:27], v[188:191], v[198:201], v[24:27]
	v_mfma_f32_16x16x32_bf16 v[28:31], v[184:187], v[202:205], v[28:31]
	v_mfma_f32_16x16x32_bf16 v[20:23], v[184:187], v[210:213], v[20:23]
	v_mfma_f32_16x16x32_bf16 v[12:15], v[184:187], v[218:221], v[12:15]
	v_mfma_f32_16x16x32_bf16 v[4:7], v[184:187], v[226:229], v[4:7]
	v_mfma_f32_16x16x32_bf16 v[0:3], v[192:195], v[226:229], v[0:3]
	v_mfma_f32_16x16x32_bf16 v[8:11], v[192:195], v[218:221], v[8:11]
	v_mfma_f32_16x16x32_bf16 v[16:19], v[192:195], v[210:213], v[16:19]
	v_mfma_f32_16x16x32_bf16 v[24:27], v[192:195], v[202:205], v[24:27]
	s_setprio 0
	s_barrier
	s_add_i32 s55, 0, 0x18000
	s_add_i32 s56, 0, 0x1c000
	v_add_u32_e32 v176, s55, v145
	v_add_u32_e32 v192, s56, v145
	ds_read_b128 v[164:167], v176
	ds_read_b128 v[168:171], v176 offset:1024
	ds_read_b128 v[172:175], v176 offset:2048
	ds_read_b128 v[176:179], v176 offset:3072
	ds_read_b128 v[180:183], v192
	ds_read_b128 v[184:187], v192 offset:1024
	ds_read_b128 v[188:191], v192 offset:2048
	ds_read_b128 v[192:195], v192 offset:3072
	s_add_u32 s26, s26, s10
	s_addc_u32 s27, s27, s11
	s_mov_b32 m0, s37
	v_lshl_add_u64 v[242:243], s[26:27], 0, v[134:135]
	ds_read_b128 v[198:201], v163 offset:32768
	ds_read_b128 v[202:205], v163 offset:33792
	ds_read_b128 v[206:209], v163 offset:34816
	ds_read_b128 v[210:213], v163 offset:35840
	ds_read_b128 v[214:217], v163 offset:36864
	ds_read_b128 v[218:221], v163 offset:37888
	ds_read_b128 v[222:225], v163 offset:38912
	ds_read_b128 v[226:229], v163 offset:39936
	global_load_lds_dwordx4 v[242:243], off
	v_lshl_add_u64 v[242:243], s[26:27], 0, v[130:131]
	s_mov_b32 m0, s38
	s_nop 0
	global_load_lds_dwordx4 v[242:243], off
	s_waitcnt vmcnt(8)
	s_waitcnt lgkmcnt(0)
	s_barrier
	s_setprio 1
	s_waitcnt lgkmcnt(0)
	v_mfma_f32_16x16x32_bf16 v[124:127], v[164:167], v[198:201], v[124:127]
	v_mfma_f32_16x16x32_bf16 v[116:119], v[164:167], v[206:209], v[116:119]
	v_mfma_f32_16x16x32_bf16 v[108:111], v[164:167], v[214:217], v[108:111]
	v_mfma_f32_16x16x32_bf16 v[100:103], v[164:167], v[222:225], v[100:103]
	v_mfma_f32_16x16x32_bf16 v[96:99], v[172:175], v[222:225], v[96:99]
	v_mfma_f32_16x16x32_bf16 v[104:107], v[172:175], v[214:217], v[104:107]
	v_mfma_f32_16x16x32_bf16 v[112:115], v[172:175], v[206:209], v[112:115]
	v_mfma_f32_16x16x32_bf16 v[120:123], v[172:175], v[198:201], v[120:123]
	v_mfma_f32_16x16x32_bf16 v[124:127], v[168:171], v[202:205], v[124:127]
	v_mfma_f32_16x16x32_bf16 v[116:119], v[168:171], v[210:213], v[116:119]
	v_mfma_f32_16x16x32_bf16 v[108:111], v[168:171], v[218:221], v[108:111]
	v_mfma_f32_16x16x32_bf16 v[100:103], v[168:171], v[226:229], v[100:103]
	v_mfma_f32_16x16x32_bf16 v[96:99], v[176:179], v[226:229], v[96:99]
	v_mfma_f32_16x16x32_bf16 v[104:107], v[176:179], v[218:221], v[104:107]
	v_mfma_f32_16x16x32_bf16 v[112:115], v[176:179], v[210:213], v[112:115]
	v_mfma_f32_16x16x32_bf16 v[120:123], v[176:179], v[202:205], v[120:123]
	s_setprio 0
	s_setprio 1
	v_mfma_f32_16x16x32_bf16 v[60:63], v[180:183], v[198:201], v[60:63]
	v_mfma_f32_16x16x32_bf16 v[52:55], v[180:183], v[206:209], v[52:55]
	v_mfma_f32_16x16x32_bf16 v[44:47], v[180:183], v[214:217], v[44:47]
	v_mfma_f32_16x16x32_bf16 v[36:39], v[180:183], v[222:225], v[36:39]
	v_mfma_f32_16x16x32_bf16 v[32:35], v[188:191], v[222:225], v[32:35]
	v_mfma_f32_16x16x32_bf16 v[40:43], v[188:191], v[214:217], v[40:43]
	v_mfma_f32_16x16x32_bf16 v[48:51], v[188:191], v[206:209], v[48:51]
	v_mfma_f32_16x16x32_bf16 v[56:59], v[188:191], v[198:201], v[56:59]
	v_mfma_f32_16x16x32_bf16 v[60:63], v[184:187], v[202:205], v[60:63]
	v_mfma_f32_16x16x32_bf16 v[52:55], v[184:187], v[210:213], v[52:55]
	v_mfma_f32_16x16x32_bf16 v[44:47], v[184:187], v[218:221], v[44:47]
	v_mfma_f32_16x16x32_bf16 v[36:39], v[184:187], v[226:229], v[36:39]
	v_mfma_f32_16x16x32_bf16 v[32:35], v[192:195], v[226:229], v[32:35]
	v_mfma_f32_16x16x32_bf16 v[40:43], v[192:195], v[218:221], v[40:43]
	v_mfma_f32_16x16x32_bf16 v[48:51], v[192:195], v[210:213], v[48:51]
	v_mfma_f32_16x16x32_bf16 v[56:59], v[192:195], v[202:205], v[56:59]
	s_setprio 0
	s_barrier
; #define PG8_STAGE(bufoff, gbase, voff) do { _Pragma("unroll") for (int _i = 0; _i < 2; ++_i) \
;         __builtin_amdgcn_global_load_lds((const unsigned*)((const char*)(gbase) + (voff)[_i]), (PG8_LAS unsigned*)(lds + (bufoff) + ldsw + _i * 8192), 16, 0, 0); } while (0)
; #define PG8_LDA(dst, b, h) do { _Pragma("unroll") for (int m = 0; m < 4; ++m) _Pragma("unroll") for (int k = 0; k < 2; ++k) dst[m][k] = *(const PG8_LAS bf16x8*)(lds + PG8_SA(b, h) + aoff + m * 2048 + k * 1024); } while (0)
; #define PG8_MMA(ai, bj, At, Bt) do { __builtin_amdgcn_s_setprio(1); _Pragma("unroll") for (int m = 0; m < 4; ++m) _Pragma("unroll") for (int n = 0; n < 2; ++n) _Pragma("unroll") for (int k = 0; k < 2; ++k) \
;         acc[ai][bj][m][n] = __builtin_amdgcn_mfma_f32_16x16x32_bf16(Bt[n][k], At[m][k], acc[ai][bj][m][n], 0, 0, 0); __builtin_amdgcn_s_setprio(0); } while (0)
; #define PG8_WAIT_V(n) asm volatile("s_waitcnt vmcnt(" #n ")" ::: "memory")
; #define PG8_WAIT_L(n) asm volatile("s_waitcnt lgkmcnt(" #n ")" ::: "memory")
; #define PG8_BAR __builtin_amdgcn_s_barrier()
; #define PG8_SCHED __builtin_amdgcn_sched_barrier(0)
; template <class Epi, class Sched, bool ALIGN_EPI = false, bool SP2 = false>
; __device__ __forceinline__ void gemm_phase(PG8_LAS unsigned char* lds, const Gemm g, const Sched& S, const Epi& E) {
;     ...
;             PG8_LDA(At, 1, 1); PG8_STAGE(PG8_SB(1, 0), b3, voffB); PG8_STAGE(PG8_SB(1, 1), b3 + hstep, voffB); PG8_STAGE(PG8_SA(1, 0), a3, voffA);
;             PG8_WAIT_V(8); PG8_WAIT_L(0); PG8_BAR; PG8_MMA(1, 0, At, B0); PG8_MMA(1, 1, At, B1); PG8_BAR; PG8_SCHED;
	s_add_i32 s26, s55, s34
	v_lshl_add_u64 v[230:231], v[230:231], 0, s[18:19]
	s_mov_b32 m0, s26
	ds_read_b128 v[198:201], v163 offset:49152
	ds_read_b128 v[202:205], v163 offset:50176
	ds_read_b128 v[206:209], v163 offset:51200
	ds_read_b128 v[210:213], v163 offset:52224
	ds_read_b128 v[214:217], v163 offset:53248
	ds_read_b128 v[218:221], v163 offset:54272
	ds_read_b128 v[222:225], v163 offset:55296
	ds_read_b128 v[226:229], v163 offset:56320
	global_load_lds_dwordx4 v[230:231], off
	v_lshl_add_u64 v[230:231], v[232:233], 0, s[18:19]
	s_add_i32 m0, s26, 0x2000
	s_add_i32 s26, s56, s34
	global_load_lds_dwordx4 v[230:231], off
	v_lshl_add_u64 v[230:231], v[234:235], 0, s[18:19]
	s_mov_b32 m0, s26
	s_nop 0
	global_load_lds_dwordx4 v[230:231], off
	v_lshl_add_u64 v[230:231], v[236:237], 0, s[18:19]
	s_add_i32 m0, s26, 0x2000
	s_nop 0
	global_load_lds_dwordx4 v[230:231], off
	v_lshl_add_u64 v[230:231], v[238:239], 0, s[18:19]
	s_mov_b32 m0, s39
	s_nop 0
	global_load_lds_dwordx4 v[230:231], off
	v_lshl_add_u64 v[230:231], v[240:241], 0, s[18:19]
	s_mov_b32 m0, s40
	s_nop 0
	global_load_lds_dwordx4 v[230:231], off
	s_waitcnt vmcnt(8)
	s_waitcnt lgkmcnt(0)
	s_barrier
	s_setprio 1
	s_waitcnt lgkmcnt(0)
	v_mfma_f32_16x16x32_bf16 v[92:95], v[164:167], v[198:201], v[92:95]
	v_mfma_f32_16x16x32_bf16 v[84:87], v[164:167], v[206:209], v[84:87]
	v_mfma_f32_16x16x32_bf16 v[76:79], v[164:167], v[214:217], v[76:79]
	v_mfma_f32_16x16x32_bf16 v[68:71], v[164:167], v[222:225], v[68:71]
	v_mfma_f32_16x16x32_bf16 v[64:67], v[172:175], v[222:225], v[64:67]
	v_mfma_f32_16x16x32_bf16 v[72:75], v[172:175], v[214:217], v[72:75]
	v_mfma_f32_16x16x32_bf16 v[80:83], v[172:175], v[206:209], v[80:83]
	v_mfma_f32_16x16x32_bf16 v[88:91], v[172:175], v[198:201], v[88:91]
	v_mfma_f32_16x16x32_bf16 v[92:95], v[168:171], v[202:205], v[92:95]
	v_mfma_f32_16x16x32_bf16 v[84:87], v[168:171], v[210:213], v[84:87]
	v_mfma_f32_16x16x32_bf16 v[76:79], v[168:171], v[218:221], v[76:79]
	v_mfma_f32_16x16x32_bf16 v[68:71], v[168:171], v[226:229], v[68:71]
	v_mfma_f32_16x16x32_bf16 v[64:67], v[176:179], v[226:229], v[64:67]
	v_mfma_f32_16x16x32_bf16 v[72:75], v[176:179], v[218:221], v[72:75]
	v_mfma_f32_16x16x32_bf16 v[80:83], v[176:179], v[210:213], v[80:83]
	v_mfma_f32_16x16x32_bf16 v[88:91], v[176:179], v[202:205], v[88:91]
	s_setprio 0
	s_setprio 1
	v_mfma_f32_16x16x32_bf16 v[28:31], v[180:183], v[198:201], v[28:31]
	v_mfma_f32_16x16x32_bf16 v[20:23], v[180:183], v[206:209], v[20:23]
	v_mfma_f32_16x16x32_bf16 v[12:15], v[180:183], v[214:217], v[12:15]
	v_mfma_f32_16x16x32_bf16 v[4:7], v[180:183], v[222:225], v[4:7]
	v_mfma_f32_16x16x32_bf16 v[0:3], v[188:191], v[222:225], v[0:3]
	v_mfma_f32_16x16x32_bf16 v[8:11], v[188:191], v[214:217], v[8:11]
	v_mfma_f32_16x16x32_bf16 v[16:19], v[188:191], v[206:209], v[16:19]
	v_mfma_f32_16x16x32_bf16 v[24:27], v[188:191], v[198:201], v[24:27]
	v_mfma_f32_16x16x32_bf16 v[28:31], v[184:187], v[202:205], v[28:31]
	v_mfma_f32_16x16x32_bf16 v[20:23], v[184:187], v[210:213], v[20:23]
	v_mfma_f32_16x16x32_bf16 v[12:15], v[184:187], v[218:221], v[12:15]
	v_mfma_f32_16x16x32_bf16 v[4:7], v[184:187], v[226:229], v[4:7]
	v_mfma_f32_16x16x32_bf16 v[0:3], v[192:195], v[226:229], v[0:3]
	v_mfma_f32_16x16x32_bf16 v[8:11], v[192:195], v[218:221], v[8:11]
	v_mfma_f32_16x16x32_bf16 v[16:19], v[192:195], v[210:213], v[16:19]
	v_mfma_f32_16x16x32_bf16 v[24:27], v[192:195], v[202:205], v[24:27]
	s_setprio 0
	s_barrier
	s_add_u32 s24, s24, 0x100
	s_addc_u32 s25, s25, 0
	s_add_u32 s52, s52, 0x100
	s_addc_u32 s53, s53, 0
	s_cmp_ge_i32 s54, s41
	s_mov_b32 s26, s54
	s_cbranch_scc0 .LBB0_706

; #define PG8_STAGE(bufoff, gbase, voff) do { _Pragma("unroll") for (int _i = 0; _i < 2; ++_i) \
;         __builtin_amdgcn_global_load_lds((const unsigned*)((const char*)(gbase) + (voff)[_i]), (PG8_LAS unsigned*)(lds + (bufoff) + ldsw + _i * 8192), 16, 0, 0); } while (0)
; #define PG8_LDA(dst, b, h) do { _Pragma("unroll") for (int m = 0; m < 4; ++m) _Pragma("unroll") for (int k = 0; k < 2; ++k) dst[m][k] = *(const PG8_LAS bf16x8*)(lds + PG8_SA(b, h) + aoff + m * 2048 + k * 1024); } while (0)
; #define PG8_LDB(dst, b, h) do { _Pragma("unroll") for (int n = 0; n < 2; ++n) _Pragma("unroll") for (int k = 0; k < 2; ++k) dst[n][k] = *(const PG8_LAS bf16x8*)(lds + PG8_SB(b, h) + boff + n * 2048 + k * 1024); } while (0)
; #define PG8_MMA(ai, bj, At, Bt) do { __builtin_amdgcn_s_setprio(1); _Pragma("unroll") for (int m = 0; m < 4; ++m) _Pragma("unroll") for (int n = 0; n < 2; ++n) _Pragma("unroll") for (int k = 0; k < 2; ++k) \
;         acc[ai][bj][m][n] = __builtin_amdgcn_mfma_f32_16x16x32_bf16(Bt[n][k], At[m][k], acc[ai][bj][m][n], 0, 0, 0); __builtin_amdgcn_s_setprio(0); } while (0)
; #define PG8_WAIT_V(n) asm volatile("s_waitcnt vmcnt(" #n ")" ::: "memory")
; #define PG8_BAR __builtin_amdgcn_s_barrier()
; template <class Epi, class Sched, bool ALIGN_EPI = false, bool SP2 = false>
; __device__ __forceinline__ void gemm_phase(PG8_LAS unsigned char* lds, const Gemm g, const Sched& S, const Epi& E) {
;     ...
;         for (int t = 0; t < nt; t += 2) {
;             const bool last = (t == nt - 2);
;             const char* a1 = cA + (size_t)(t + 1) * kstep;
;             const char* a2 = last ? nA : cA + (size_t)(t + 2) * kstep; const char* b2 = last ? nB : cB + (size_t)(t + 2) * kstep;
;             const char* a3 = a2 + kstep; const char* b3 = b2 + kstep;
;             if (last && has_next) S.a_ready(nxt);
;             if constexpr (SP2) {
;             PG8_LDB(B0, 0, 0); PG8_LDB(B1, 0, 1); PG8_SCHED; PG8_LDA(At, 0, 0); PG8_STAGE(PG8_SA(1, 1), a1 + hstep, voffA);
;             PG8_WAIT_V(8); PG8_WAIT_L(0); PG8_BAR; PG8_MMA(0, 0, At, B0); PG8_MMA(0, 1, At, B1); PG8_BAR; PG8_SCHED;
;             PG8_LDA(At, 0, 1); PG8_STAGE(PG8_SB(0, 0), b2, voffB); PG8_STAGE(PG8_SB(0, 1), b2 + hstep, voffB); PG8_STAGE(PG8_SA(0, 0), a2, voffA);
;             PG8_WAIT_V(8); PG8_WAIT_L(0); PG8_BAR; PG8_MMA(1, 0, At, B0); PG8_MMA(1, 1, At, B1); PG8_BAR; PG8_SCHED;
.LBB0_731:
	ds_read_b128 v[166:169], v162
	ds_read_b128 v[170:173], v162 offset:1024
	ds_read_b128 v[174:177], v162 offset:2048
	ds_read_b128 v[178:181], v162 offset:3072
	ds_read_b128 v[182:185], v163
	ds_read_b128 v[186:189], v163 offset:1024
	ds_read_b128 v[190:193], v163 offset:2048
	ds_read_b128 v[198:201], v163 offset:3072
	s_add_i32 s50, s24, 2
	s_add_u32 s51, s22, 0x80
	s_addc_u32 s25, s23, 0
	s_cmp_eq_u32 s40, s24
	s_cselect_b32 s24, s4, s51
	s_cselect_b32 s25, s5, s25
	s_cselect_b32 s53, s21, s49
	s_cselect_b32 s52, s20, s48
	v_lshl_add_u64 v[194:195], s[22:23], 0, v[138:139]
	s_add_i32 m0, s27, 0xc000
	ds_read_b128 v[202:205], v164
	ds_read_b128 v[206:209], v164 offset:1024
	ds_read_b128 v[210:213], v164 offset:2048
	ds_read_b128 v[214:217], v164 offset:3072
	ds_read_b128 v[218:221], v164 offset:4096
	ds_read_b128 v[222:225], v164 offset:5120
	ds_read_b128 v[226:229], v164 offset:6144
	ds_read_b128 v[230:233], v164 offset:7168
	global_load_lds_dwordx4 v[194:195], off
	v_lshl_add_u64 v[194:195], s[22:23], 0, v[140:141]
	s_add_i32 m0, s27, 0xe000
	s_nop 0
	global_load_lds_dwordx4 v[194:195], off
	s_waitcnt vmcnt(8)
	s_waitcnt lgkmcnt(0)
	s_barrier
	s_setprio 1
	s_waitcnt lgkmcnt(0)
	v_mfma_f32_16x16x32_bf16 v[124:127], v[166:169], v[202:205], v[124:127]
	v_mfma_f32_16x16x32_bf16 v[116:119], v[166:169], v[210:213], v[116:119]
	v_mfma_f32_16x16x32_bf16 v[108:111], v[166:169], v[218:221], v[108:111]
	v_mfma_f32_16x16x32_bf16 v[100:103], v[166:169], v[226:229], v[100:103]
	v_mfma_f32_16x16x32_bf16 v[96:99], v[174:177], v[226:229], v[96:99]
	v_mfma_f32_16x16x32_bf16 v[104:107], v[174:177], v[218:221], v[104:107]
	v_mfma_f32_16x16x32_bf16 v[112:115], v[174:177], v[210:213], v[112:115]
	v_mfma_f32_16x16x32_bf16 v[120:123], v[174:177], v[202:205], v[120:123]
	v_mfma_f32_16x16x32_bf16 v[124:127], v[170:173], v[206:209], v[124:127]
	v_mfma_f32_16x16x32_bf16 v[116:119], v[170:173], v[214:217], v[116:119]
	v_mfma_f32_16x16x32_bf16 v[108:111], v[170:173], v[222:225], v[108:111]
	v_mfma_f32_16x16x32_bf16 v[100:103], v[170:173], v[230:233], v[100:103]
	v_mfma_f32_16x16x32_bf16 v[96:99], v[178:181], v[230:233], v[96:99]
	v_mfma_f32_16x16x32_bf16 v[104:107], v[178:181], v[222:225], v[104:107]
	v_mfma_f32_16x16x32_bf16 v[112:115], v[178:181], v[214:217], v[112:115]
	v_mfma_f32_16x16x32_bf16 v[120:123], v[178:181], v[206:209], v[120:123]
	s_setprio 0
	s_setprio 1
	v_mfma_f32_16x16x32_bf16 v[60:63], v[182:185], v[202:205], v[60:63]
	v_mfma_f32_16x16x32_bf16 v[52:55], v[182:185], v[210:213], v[52:55]
	v_mfma_f32_16x16x32_bf16 v[44:47], v[182:185], v[218:221], v[44:47]
	v_mfma_f32_16x16x32_bf16 v[36:39], v[182:185], v[226:229], v[36:39]
	v_mfma_f32_16x16x32_bf16 v[32:35], v[190:193], v[226:229], v[32:35]
	v_mfma_f32_16x16x32_bf16 v[40:43], v[190:193], v[218:221], v[40:43]
	v_mfma_f32_16x16x32_bf16 v[48:51], v[190:193], v[210:213], v[48:51]
	v_mfma_f32_16x16x32_bf16 v[56:59], v[190:193], v[202:205], v[56:59]
	v_mfma_f32_16x16x32_bf16 v[60:63], v[186:189], v[206:209], v[60:63]
	v_mfma_f32_16x16x32_bf16 v[52:55], v[186:189], v[214:217], v[52:55]
	v_mfma_f32_16x16x32_bf16 v[44:47], v[186:189], v[222:225], v[44:47]
	v_mfma_f32_16x16x32_bf16 v[36:39], v[186:189], v[230:233], v[36:39]
	v_mfma_f32_16x16x32_bf16 v[32:35], v[198:201], v[230:233], v[32:35]
	v_mfma_f32_16x16x32_bf16 v[40:43], v[198:201], v[222:225], v[40:43]
	v_mfma_f32_16x16x32_bf16 v[48:51], v[198:201], v[214:217], v[48:51]
	v_mfma_f32_16x16x32_bf16 v[56:59], v[198:201], v[206:209], v[56:59]
	s_setprio 0
	s_barrier
	s_add_i32 s51, s41, s26
	v_lshl_add_u64 v[194:195], s[52:53], 0, v[132:133]
	s_mov_b32 m0, s51
	ds_read_b128 v[202:205], v164 offset:16384
	ds_read_b128 v[206:209], v164 offset:17408
	ds_read_b128 v[210:213], v164 offset:18432
	ds_read_b128 v[214:217], v164 offset:19456
	ds_read_b128 v[218:221], v164 offset:20480
	ds_read_b128 v[222:225], v164 offset:21504
	ds_read_b128 v[226:229], v164 offset:22528
	ds_read_b128 v[230:233], v164 offset:23552
	global_load_lds_dwordx4 v[194:195], off
	s_add_i32 m0, s51, 0x2000
	v_lshl_add_u64 v[234:235], s[52:53], 0, v[128:129]
	s_add_u32 s52, s52, s10
	s_addc_u32 s53, s53, s11
	s_add_i32 s51, s42, s26
	global_load_lds_dwordx4 v[234:235], off
	v_lshl_add_u64 v[236:237], s[52:53], 0, v[132:133]
	s_mov_b32 m0, s51
	v_lshl_add_u64 v[238:239], s[52:53], 0, v[128:129]
	global_load_lds_dwordx4 v[236:237], off
	s_add_i32 m0, s51, 0x2000
	v_lshl_add_u64 v[240:241], s[24:25], 0, v[134:135]
	global_load_lds_dwordx4 v[238:239], off
	s_mov_b32 m0, s27
	v_lshl_add_u64 v[242:243], s[24:25], 0, v[130:131]
	global_load_lds_dwordx4 v[240:241], off
	s_mov_b32 m0, s30
	s_nop 0
	global_load_lds_dwordx4 v[242:243], off
	s_waitcnt vmcnt(8)
	s_waitcnt lgkmcnt(0)
	s_barrier
; #define PG8_STAGE(bufoff, gbase, voff) do { _Pragma("unroll") for (int _i = 0; _i < 2; ++_i) \
;         __builtin_amdgcn_global_load_lds((const unsigned*)((const char*)(gbase) + (voff)[_i]), (PG8_LAS unsigned*)(lds + (bufoff) + ldsw + _i * 8192), 16, 0, 0); } while (0)
; #define PG8_LDA(dst, b, h) do { _Pragma("unroll") for (int m = 0; m < 4; ++m) _Pragma("unroll") for (int k = 0; k < 2; ++k) dst[m][k] = *(const PG8_LAS bf16x8*)(lds + PG8_SA(b, h) + aoff + m * 2048 + k * 1024); } while (0)
; #define PG8_LDB(dst, b, h) do { _Pragma("unroll") for (int n = 0; n < 2; ++n) _Pragma("unroll") for (int k = 0; k < 2; ++k) dst[n][k] = *(const PG8_LAS bf16x8*)(lds + PG8_SB(b, h) + boff + n * 2048 + k * 1024); } while (0)
; #define PG8_MMA(ai, bj, At, Bt) do { __builtin_amdgcn_s_setprio(1); _Pragma("unroll") for (int m = 0; m < 4; ++m) _Pragma("unroll") for (int n = 0; n < 2; ++n) _Pragma("unroll") for (int k = 0; k < 2; ++k) \
;         acc[ai][bj][m][n] = __builtin_amdgcn_mfma_f32_16x16x32_bf16(Bt[n][k], At[m][k], acc[ai][bj][m][n], 0, 0, 0); __builtin_amdgcn_s_setprio(0); } while (0)
; #define PG8_WAIT_V(n) asm volatile("s_waitcnt vmcnt(" #n ")" ::: "memory")
; #define PG8_WAIT_L(n) asm volatile("s_waitcnt lgkmcnt(" #n ")" ::: "memory")
; #define PG8_BAR __builtin_amdgcn_s_barrier()
; #define PG8_SCHED __builtin_amdgcn_sched_barrier(0)
; template <class Epi, class Sched, bool ALIGN_EPI = false, bool SP2 = false>
; __device__ __forceinline__ void gemm_phase(PG8_LAS unsigned char* lds, const Gemm g, const Sched& S, const Epi& E) {
;     ...
;             PG8_WAIT_V(8); PG8_WAIT_L(0); PG8_BAR; PG8_MMA(1, 0, At, B0); PG8_MMA(1, 1, At, B1); PG8_BAR; PG8_SCHED;
;             PG8_LDB(B0, 1, 0); PG8_LDB(B1, 1, 1); PG8_SCHED; PG8_LDA(At, 1, 0); PG8_STAGE(PG8_SA(0, 1), a2 + hstep, voffA);
;             PG8_WAIT_V(8); PG8_WAIT_L(0); PG8_BAR; PG8_MMA(0, 0, At, B0); PG8_MMA(0, 1, At, B1); PG8_BAR; PG8_SCHED;
	s_setprio 1
	s_waitcnt lgkmcnt(0)
	v_mfma_f32_16x16x32_bf16 v[92:95], v[166:169], v[202:205], v[92:95]
	v_mfma_f32_16x16x32_bf16 v[84:87], v[166:169], v[210:213], v[84:87]
	v_mfma_f32_16x16x32_bf16 v[76:79], v[166:169], v[218:221], v[76:79]
	v_mfma_f32_16x16x32_bf16 v[68:71], v[166:169], v[226:229], v[68:71]
	v_mfma_f32_16x16x32_bf16 v[64:67], v[174:177], v[226:229], v[64:67]
	v_mfma_f32_16x16x32_bf16 v[72:75], v[174:177], v[218:221], v[72:75]
	v_mfma_f32_16x16x32_bf16 v[80:83], v[174:177], v[210:213], v[80:83]
	v_mfma_f32_16x16x32_bf16 v[88:91], v[174:177], v[202:205], v[88:91]
	v_mfma_f32_16x16x32_bf16 v[92:95], v[170:173], v[206:209], v[92:95]
	v_mfma_f32_16x16x32_bf16 v[84:87], v[170:173], v[214:217], v[84:87]
	v_mfma_f32_16x16x32_bf16 v[76:79], v[170:173], v[222:225], v[76:79]
	v_mfma_f32_16x16x32_bf16 v[68:71], v[170:173], v[230:233], v[68:71]
	v_mfma_f32_16x16x32_bf16 v[64:67], v[178:181], v[230:233], v[64:67]
	v_mfma_f32_16x16x32_bf16 v[72:75], v[178:181], v[222:225], v[72:75]
	v_mfma_f32_16x16x32_bf16 v[80:83], v[178:181], v[214:217], v[80:83]
	v_mfma_f32_16x16x32_bf16 v[88:91], v[178:181], v[206:209], v[88:91]
	s_setprio 0
	s_setprio 1
	v_mfma_f32_16x16x32_bf16 v[28:31], v[182:185], v[202:205], v[28:31]
	v_mfma_f32_16x16x32_bf16 v[20:23], v[182:185], v[210:213], v[20:23]
	v_mfma_f32_16x16x32_bf16 v[12:15], v[182:185], v[218:221], v[12:15]
	v_mfma_f32_16x16x32_bf16 v[4:7], v[182:185], v[226:229], v[4:7]
	v_mfma_f32_16x16x32_bf16 v[0:3], v[190:193], v[226:229], v[0:3]
	v_mfma_f32_16x16x32_bf16 v[8:11], v[190:193], v[218:221], v[8:11]
	v_mfma_f32_16x16x32_bf16 v[16:19], v[190:193], v[210:213], v[16:19]
	v_mfma_f32_16x16x32_bf16 v[24:27], v[190:193], v[202:205], v[24:27]
	v_mfma_f32_16x16x32_bf16 v[28:31], v[186:189], v[206:209], v[28:31]
	v_mfma_f32_16x16x32_bf16 v[20:23], v[186:189], v[214:217], v[20:23]
	v_mfma_f32_16x16x32_bf16 v[12:15], v[186:189], v[222:225], v[12:15]
	v_mfma_f32_16x16x32_bf16 v[4:7], v[186:189], v[230:233], v[4:7]
	v_mfma_f32_16x16x32_bf16 v[0:3], v[198:201], v[230:233], v[0:3]
	v_mfma_f32_16x16x32_bf16 v[8:11], v[198:201], v[222:225], v[8:11]
	v_mfma_f32_16x16x32_bf16 v[16:19], v[198:201], v[214:217], v[16:19]
	v_mfma_f32_16x16x32_bf16 v[24:27], v[198:201], v[206:209], v[24:27]
	s_setprio 0
	s_barrier
	s_add_i32 s51, 0, 0x18000
	v_add_u32_e32 v165, s51, v161
	s_add_i32 s52, 0, 0x1c000
	ds_read_b128 v[166:169], v165
	ds_read_b128 v[170:173], v165 offset:1024
	ds_read_b128 v[174:177], v165 offset:2048
	ds_read_b128 v[178:181], v165 offset:3072
	v_add_u32_e32 v165, s52, v161
	ds_read_b128 v[182:185], v165
	ds_read_b128 v[186:189], v165 offset:1024
	ds_read_b128 v[190:193], v165 offset:2048
	ds_read_b128 v[198:201], v165 offset:3072
	s_add_u32 s24, s24, s10
	s_addc_u32 s25, s25, s11
	s_mov_b32 m0, s31
	v_lshl_add_u64 v[244:245], s[24:25], 0, v[134:135]
	ds_read_b128 v[202:205], v164 offset:32768
	ds_read_b128 v[206:209], v164 offset:33792
	ds_read_b128 v[210:213], v164 offset:34816
	ds_read_b128 v[214:217], v164 offset:35840
	ds_read_b128 v[218:221], v164 offset:36864
	ds_read_b128 v[222:225], v164 offset:37888
	ds_read_b128 v[226:229], v164 offset:38912
	ds_read_b128 v[230:233], v164 offset:39936
	global_load_lds_dwordx4 v[244:245], off
	v_lshl_add_u64 v[244:245], s[24:25], 0, v[130:131]
	s_mov_b32 m0, s34
	s_nop 0
	global_load_lds_dwordx4 v[244:245], off
	s_waitcnt vmcnt(8)
	s_waitcnt lgkmcnt(0)
	s_barrier
	s_setprio 1
	s_waitcnt lgkmcnt(0)
	v_mfma_f32_16x16x32_bf16 v[124:127], v[166:169], v[202:205], v[124:127]
	v_mfma_f32_16x16x32_bf16 v[116:119], v[166:169], v[210:213], v[116:119]
	v_mfma_f32_16x16x32_bf16 v[108:111], v[166:169], v[218:221], v[108:111]
	v_mfma_f32_16x16x32_bf16 v[100:103], v[166:169], v[226:229], v[100:103]
	v_mfma_f32_16x16x32_bf16 v[96:99], v[174:177], v[226:229], v[96:99]
	v_mfma_f32_16x16x32_bf16 v[104:107], v[174:177], v[218:221], v[104:107]
	v_mfma_f32_16x16x32_bf16 v[112:115], v[174:177], v[210:213], v[112:115]
	v_mfma_f32_16x16x32_bf16 v[120:123], v[174:177], v[202:205], v[120:123]
	v_mfma_f32_16x16x32_bf16 v[124:127], v[170:173], v[206:209], v[124:127]
	v_mfma_f32_16x16x32_bf16 v[116:119], v[170:173], v[214:217], v[116:119]
	v_mfma_f32_16x16x32_bf16 v[108:111], v[170:173], v[222:225], v[108:111]
	v_mfma_f32_16x16x32_bf16 v[100:103], v[170:173], v[230:233], v[100:103]
	v_mfma_f32_16x16x32_bf16 v[96:99], v[178:181], v[230:233], v[96:99]
	v_mfma_f32_16x16x32_bf16 v[104:107], v[178:181], v[222:225], v[104:107]
	v_mfma_f32_16x16x32_bf16 v[112:115], v[178:181], v[214:217], v[112:115]
	v_mfma_f32_16x16x32_bf16 v[120:123], v[178:181], v[206:209], v[120:123]
	s_setprio 0
	s_setprio 1
	v_mfma_f32_16x16x32_bf16 v[60:63], v[182:185], v[202:205], v[60:63]
	v_mfma_f32_16x16x32_bf16 v[52:55], v[182:185], v[210:213], v[52:55]
	v_mfma_f32_16x16x32_bf16 v[44:47], v[182:185], v[218:221], v[44:47]
	v_mfma_f32_16x16x32_bf16 v[36:39], v[182:185], v[226:229], v[36:39]
	v_mfma_f32_16x16x32_bf16 v[32:35], v[190:193], v[226:229], v[32:35]
	v_mfma_f32_16x16x32_bf16 v[40:43], v[190:193], v[218:221], v[40:43]
	v_mfma_f32_16x16x32_bf16 v[48:51], v[190:193], v[210:213], v[48:51]
	v_mfma_f32_16x16x32_bf16 v[56:59], v[190:193], v[202:205], v[56:59]
	v_mfma_f32_16x16x32_bf16 v[60:63], v[186:189], v[206:209], v[60:63]
	v_mfma_f32_16x16x32_bf16 v[52:55], v[186:189], v[214:217], v[52:55]
	v_mfma_f32_16x16x32_bf16 v[44:47], v[186:189], v[222:225], v[44:47]
	v_mfma_f32_16x16x32_bf16 v[36:39], v[186:189], v[230:233], v[36:39]
	v_mfma_f32_16x16x32_bf16 v[32:35], v[198:201], v[230:233], v[32:35]
	v_mfma_f32_16x16x32_bf16 v[40:43], v[198:201], v[222:225], v[40:43]
	v_mfma_f32_16x16x32_bf16 v[48:51], v[198:201], v[214:217], v[48:51]
	v_mfma_f32_16x16x32_bf16 v[56:59], v[198:201], v[206:209], v[56:59]
	s_setprio 0
	s_barrier
; #define PG8_STAGE(bufoff, gbase, voff) do { _Pragma("unroll") for (int _i = 0; _i < 2; ++_i) \
;         __builtin_amdgcn_global_load_lds((const unsigned*)((const char*)(gbase) + (voff)[_i]), (PG8_LAS unsigned*)(lds + (bufoff) + ldsw + _i * 8192), 16, 0, 0); } while (0)
; #define PG8_LDA(dst, b, h) do { _Pragma("unroll") for (int m = 0; m < 4; ++m) _Pragma("unroll") for (int k = 0; k < 2; ++k) dst[m][k] = *(const PG8_LAS bf16x8*)(lds + PG8_SA(b, h) + aoff + m * 2048 + k * 1024); } while (0)
; #define PG8_MMA(ai, bj, At, Bt) do { __builtin_amdgcn_s_setprio(1); _Pragma("unroll") for (int m = 0; m < 4; ++m) _Pragma("unroll") for (int n = 0; n < 2; ++n) _Pragma("unroll") for (int k = 0; k < 2; ++k) \
;         acc[ai][bj][m][n] = __builtin_amdgcn_mfma_f32_16x16x32_bf16(Bt[n][k], At[m][k], acc[ai][bj][m][n], 0, 0, 0); __builtin_amdgcn_s_setprio(0); } while (0)
; #define PG8_WAIT_V(n) asm volatile("s_waitcnt vmcnt(" #n ")" ::: "memory")
; #define PG8_WAIT_L(n) asm volatile("s_waitcnt lgkmcnt(" #n ")" ::: "memory")
; #define PG8_BAR __builtin_amdgcn_s_barrier()
; #define PG8_SCHED __builtin_amdgcn_sched_barrier(0)
; template <class Epi, class Sched, bool ALIGN_EPI = false, bool SP2 = false>
; __device__ __forceinline__ void gemm_phase(PG8_LAS unsigned char* lds, const Gemm g, const Sched& S, const Epi& E) {
;     ...
;             PG8_LDA(At, 1, 1); PG8_STAGE(PG8_SB(1, 0), b3, voffB); PG8_STAGE(PG8_SB(1, 1), b3 + hstep, voffB); PG8_STAGE(PG8_SA(1, 0), a3, voffA);
;             PG8_WAIT_V(8); PG8_WAIT_L(0); PG8_BAR; PG8_MMA(1, 0, At, B0); PG8_MMA(1, 1, At, B1); PG8_BAR; PG8_SCHED;
	s_add_i32 s24, s51, s26
	v_lshl_add_u64 v[194:195], v[194:195], 0, s[16:17]
	s_mov_b32 m0, s24
	ds_read_b128 v[202:205], v164 offset:49152
	ds_read_b128 v[206:209], v164 offset:50176
	ds_read_b128 v[210:213], v164 offset:51200
	ds_read_b128 v[214:217], v164 offset:52224
	ds_read_b128 v[218:221], v164 offset:53248
	ds_read_b128 v[222:225], v164 offset:54272
	ds_read_b128 v[226:229], v164 offset:55296
	ds_read_b128 v[230:233], v164 offset:56320
	global_load_lds_dwordx4 v[194:195], off
	v_lshl_add_u64 v[194:195], v[234:235], 0, s[16:17]
	s_add_i32 m0, s24, 0x2000
	s_add_i32 s24, s52, s26
	global_load_lds_dwordx4 v[194:195], off
	v_lshl_add_u64 v[194:195], v[236:237], 0, s[16:17]
	s_mov_b32 m0, s24
	s_nop 0
	global_load_lds_dwordx4 v[194:195], off
	v_lshl_add_u64 v[194:195], v[238:239], 0, s[16:17]
	s_add_i32 m0, s24, 0x2000
	s_nop 0
	global_load_lds_dwordx4 v[194:195], off
	v_lshl_add_u64 v[194:195], v[240:241], 0, s[16:17]
	s_mov_b32 m0, s36
	s_nop 0
	global_load_lds_dwordx4 v[194:195], off
	v_lshl_add_u64 v[194:195], v[242:243], 0, s[16:17]
	s_mov_b32 m0, s37
	s_nop 0
	global_load_lds_dwordx4 v[194:195], off
	s_waitcnt vmcnt(8)
	s_waitcnt lgkmcnt(0)
	s_barrier
	s_setprio 1
	s_waitcnt lgkmcnt(0)
	v_mfma_f32_16x16x32_bf16 v[92:95], v[166:169], v[202:205], v[92:95]
	v_mfma_f32_16x16x32_bf16 v[84:87], v[166:169], v[210:213], v[84:87]
	v_mfma_f32_16x16x32_bf16 v[76:79], v[166:169], v[218:221], v[76:79]
	v_mfma_f32_16x16x32_bf16 v[68:71], v[166:169], v[226:229], v[68:71]
	v_mfma_f32_16x16x32_bf16 v[64:67], v[174:177], v[226:229], v[64:67]
	v_mfma_f32_16x16x32_bf16 v[72:75], v[174:177], v[218:221], v[72:75]
	v_mfma_f32_16x16x32_bf16 v[80:83], v[174:177], v[210:213], v[80:83]
	v_mfma_f32_16x16x32_bf16 v[88:91], v[174:177], v[202:205], v[88:91]
	v_mfma_f32_16x16x32_bf16 v[92:95], v[170:173], v[206:209], v[92:95]
	v_mfma_f32_16x16x32_bf16 v[84:87], v[170:173], v[214:217], v[84:87]
	v_mfma_f32_16x16x32_bf16 v[76:79], v[170:173], v[222:225], v[76:79]
	v_mfma_f32_16x16x32_bf16 v[68:71], v[170:173], v[230:233], v[68:71]
	v_mfma_f32_16x16x32_bf16 v[64:67], v[178:181], v[230:233], v[64:67]
	v_mfma_f32_16x16x32_bf16 v[72:75], v[178:181], v[222:225], v[72:75]
	v_mfma_f32_16x16x32_bf16 v[80:83], v[178:181], v[214:217], v[80:83]
	v_mfma_f32_16x16x32_bf16 v[88:91], v[178:181], v[206:209], v[88:91]
	s_setprio 0
	s_setprio 1
	v_mfma_f32_16x16x32_bf16 v[28:31], v[182:185], v[202:205], v[28:31]
	v_mfma_f32_16x16x32_bf16 v[20:23], v[182:185], v[210:213], v[20:23]
	v_mfma_f32_16x16x32_bf16 v[12:15], v[182:185], v[218:221], v[12:15]
	v_mfma_f32_16x16x32_bf16 v[4:7], v[182:185], v[226:229], v[4:7]
	v_mfma_f32_16x16x32_bf16 v[0:3], v[190:193], v[226:229], v[0:3]
	v_mfma_f32_16x16x32_bf16 v[8:11], v[190:193], v[218:221], v[8:11]
	v_mfma_f32_16x16x32_bf16 v[16:19], v[190:193], v[210:213], v[16:19]
	v_mfma_f32_16x16x32_bf16 v[24:27], v[190:193], v[202:205], v[24:27]
	v_mfma_f32_16x16x32_bf16 v[28:31], v[186:189], v[206:209], v[28:31]
	v_mfma_f32_16x16x32_bf16 v[20:23], v[186:189], v[214:217], v[20:23]
	v_mfma_f32_16x16x32_bf16 v[12:15], v[186:189], v[222:225], v[12:15]
	v_mfma_f32_16x16x32_bf16 v[4:7], v[186:189], v[230:233], v[4:7]
	v_mfma_f32_16x16x32_bf16 v[0:3], v[198:201], v[230:233], v[0:3]
	v_mfma_f32_16x16x32_bf16 v[8:11], v[198:201], v[222:225], v[8:11]
	v_mfma_f32_16x16x32_bf16 v[16:19], v[198:201], v[214:217], v[16:19]
	v_mfma_f32_16x16x32_bf16 v[24:27], v[198:201], v[206:209], v[24:27]
	s_setprio 0
	s_barrier
	s_add_u32 s22, s22, 0x100
	s_addc_u32 s23, s23, 0
	s_add_u32 s48, s48, 0x100
	s_addc_u32 s49, s49, 0
	s_cmp_ge_i32 s50, s38
	s_mov_b32 s24, s50
	s_cbranch_scc0 .LBB0_731

; #define PG8_STAGE(bufoff, gbase, voff) do { _Pragma("unroll") for (int _i = 0; _i < 2; ++_i) \
;         __builtin_amdgcn_global_load_lds((const unsigned*)((const char*)(gbase) + (voff)[_i]), (PG8_LAS unsigned*)(lds + (bufoff) + ldsw + _i * 8192), 16, 0, 0); } while (0)
; #define PG8_LDA(dst, b, h) do { _Pragma("unroll") for (int m = 0; m < 4; ++m) _Pragma("unroll") for (int k = 0; k < 2; ++k) dst[m][k] = *(const PG8_LAS bf16x8*)(lds + PG8_SA(b, h) + aoff + m * 2048 + k * 1024); } while (0)
; #define PG8_LDB(dst, b, h) do { _Pragma("unroll") for (int n = 0; n < 2; ++n) _Pragma("unroll") for (int k = 0; k < 2; ++k) dst[n][k] = *(const PG8_LAS bf16x8*)(lds + PG8_SB(b, h) + boff + n * 2048 + k * 1024); } while (0)
; #define PG8_MMA(ai, bj, At, Bt) do { __builtin_amdgcn_s_setprio(1); _Pragma("unroll") for (int m = 0; m < 4; ++m) _Pragma("unroll") for (int n = 0; n < 2; ++n) _Pragma("unroll") for (int k = 0; k < 2; ++k) \
;         acc[ai][bj][m][n] = __builtin_amdgcn_mfma_f32_16x16x32_bf16(Bt[n][k], At[m][k], acc[ai][bj][m][n], 0, 0, 0); __builtin_amdgcn_s_setprio(0); } while (0)
; #define PG8_WAIT_V(n) asm volatile("s_waitcnt vmcnt(" #n ")" ::: "memory")
; #define PG8_BAR __builtin_amdgcn_s_barrier()
; template <class Epi, class Sched, bool ALIGN_EPI = false, bool SP2 = false>
; __device__ __forceinline__ void gemm_phase(PG8_LAS unsigned char* lds, const Gemm g, const Sched& S, const Epi& E) {
;     ...
;         for (int t = 0; t < nt; t += 2) {
;             const bool last = (t == nt - 2);
;             const char* a1 = cA + (size_t)(t + 1) * kstep;
;             const char* a2 = last ? nA : cA + (size_t)(t + 2) * kstep; const char* b2 = last ? nB : cB + (size_t)(t + 2) * kstep;
;             const char* a3 = a2 + kstep; const char* b3 = b2 + kstep;
;             if (last && has_next) S.a_ready(nxt);
;             if constexpr (SP2) {
;             PG8_LDB(B0, 0, 0); PG8_LDB(B1, 0, 1); PG8_SCHED; PG8_LDA(At, 0, 0); PG8_STAGE(PG8_SA(1, 1), a1 + hstep, voffA);
;             PG8_WAIT_V(8); PG8_WAIT_L(0); PG8_BAR; PG8_MMA(0, 0, At, B0); PG8_MMA(0, 1, At, B1); PG8_BAR; PG8_SCHED;
;             PG8_LDA(At, 0, 1); PG8_STAGE(PG8_SB(0, 0), b2, voffB); PG8_STAGE(PG8_SB(0, 1), b2 + hstep, voffB); PG8_STAGE(PG8_SA(0, 0), a2, voffA);
;             PG8_WAIT_V(8); PG8_WAIT_L(0); PG8_BAR; PG8_MMA(1, 0, At, B0); PG8_MMA(1, 1, At, B1); PG8_BAR; PG8_SCHED;
.LBB0_757:
	ds_read_b128 v[150:153], v146
	ds_read_b128 v[154:157], v146 offset:1024
	ds_read_b128 v[158:161], v146 offset:2048
	ds_read_b128 v[162:165], v146 offset:3072
	ds_read_b128 v[166:169], v147
	ds_read_b128 v[170:173], v147 offset:1024
	ds_read_b128 v[174:177], v147 offset:2048
	ds_read_b128 v[178:181], v147 offset:3072
	s_add_i32 s53, s24, 2
	s_add_u32 s54, s22, 0x80
	s_addc_u32 s25, s23, 0
	s_cmp_eq_u32 s43, s24
	s_cselect_b32 s24, s2, s54
	s_cselect_b32 s25, s3, s25
	s_cselect_b32 s55, s21, s52
	s_cselect_b32 s54, s20, s51
	v_lshl_add_u64 v[194:195], s[22:23], 0, v[136:137]
	s_add_i32 m0, s31, 0xc000
	ds_read_b128 v[182:185], v148
	ds_read_b128 v[186:189], v148 offset:1024
	ds_read_b128 v[190:193], v148 offset:2048
	ds_read_b128 v[198:201], v148 offset:3072
	ds_read_b128 v[202:205], v148 offset:4096
	ds_read_b128 v[206:209], v148 offset:5120
	ds_read_b128 v[210:213], v148 offset:6144
	ds_read_b128 v[214:217], v148 offset:7168
	global_load_lds_dwordx4 v[194:195], off
	v_lshl_add_u64 v[194:195], s[22:23], 0, v[138:139]
	s_add_i32 m0, s31, 0xe000
	s_nop 0
	global_load_lds_dwordx4 v[194:195], off
	s_waitcnt vmcnt(8)
	s_waitcnt lgkmcnt(0)
	s_barrier
	s_setprio 1
	s_waitcnt lgkmcnt(0)
	v_mfma_f32_16x16x32_bf16 v[120:123], v[150:153], v[182:185], v[120:123]
	v_mfma_f32_16x16x32_bf16 v[116:119], v[150:153], v[190:193], v[116:119]
	v_mfma_f32_16x16x32_bf16 v[108:111], v[150:153], v[202:205], v[108:111]
	v_mfma_f32_16x16x32_bf16 v[100:103], v[150:153], v[210:213], v[100:103]
	v_mfma_f32_16x16x32_bf16 v[96:99], v[158:161], v[210:213], v[96:99]
	v_mfma_f32_16x16x32_bf16 v[104:107], v[158:161], v[202:205], v[104:107]
	v_mfma_f32_16x16x32_bf16 v[112:115], v[158:161], v[190:193], v[112:115]
	v_mfma_f32_16x16x32_bf16 v[124:127], v[158:161], v[182:185], v[124:127]
	v_mfma_f32_16x16x32_bf16 v[120:123], v[154:157], v[186:189], v[120:123]
	v_mfma_f32_16x16x32_bf16 v[116:119], v[154:157], v[198:201], v[116:119]
	v_mfma_f32_16x16x32_bf16 v[108:111], v[154:157], v[206:209], v[108:111]
	v_mfma_f32_16x16x32_bf16 v[100:103], v[154:157], v[214:217], v[100:103]
	v_mfma_f32_16x16x32_bf16 v[96:99], v[162:165], v[214:217], v[96:99]
	v_mfma_f32_16x16x32_bf16 v[104:107], v[162:165], v[206:209], v[104:107]
	v_mfma_f32_16x16x32_bf16 v[112:115], v[162:165], v[198:201], v[112:115]
	v_mfma_f32_16x16x32_bf16 v[124:127], v[162:165], v[186:189], v[124:127]
	s_setprio 0
	s_setprio 1
	v_mfma_f32_16x16x32_bf16 v[60:63], v[166:169], v[182:185], v[60:63]
	v_mfma_f32_16x16x32_bf16 v[52:55], v[166:169], v[190:193], v[52:55]
	v_mfma_f32_16x16x32_bf16 v[44:47], v[166:169], v[202:205], v[44:47]
	v_mfma_f32_16x16x32_bf16 v[36:39], v[166:169], v[210:213], v[36:39]
	v_mfma_f32_16x16x32_bf16 v[32:35], v[174:177], v[210:213], v[32:35]
	v_mfma_f32_16x16x32_bf16 v[40:43], v[174:177], v[202:205], v[40:43]
	v_mfma_f32_16x16x32_bf16 v[48:51], v[174:177], v[190:193], v[48:51]
	v_mfma_f32_16x16x32_bf16 v[56:59], v[174:177], v[182:185], v[56:59]
	v_mfma_f32_16x16x32_bf16 v[60:63], v[170:173], v[186:189], v[60:63]
	v_mfma_f32_16x16x32_bf16 v[52:55], v[170:173], v[198:201], v[52:55]
	v_mfma_f32_16x16x32_bf16 v[44:47], v[170:173], v[206:209], v[44:47]
	v_mfma_f32_16x16x32_bf16 v[36:39], v[170:173], v[214:217], v[36:39]
	v_mfma_f32_16x16x32_bf16 v[32:35], v[178:181], v[214:217], v[32:35]
	v_mfma_f32_16x16x32_bf16 v[40:43], v[178:181], v[206:209], v[40:43]
	v_mfma_f32_16x16x32_bf16 v[48:51], v[178:181], v[198:201], v[48:51]
	v_mfma_f32_16x16x32_bf16 v[56:59], v[178:181], v[186:189], v[56:59]
	s_setprio 0
	s_barrier
	s_add_i32 s56, s44, s27
	v_lshl_add_u64 v[194:195], s[54:55], 0, v[132:133]
	s_mov_b32 m0, s56
	ds_read_b128 v[182:185], v148 offset:16384
	ds_read_b128 v[186:189], v148 offset:17408
	ds_read_b128 v[190:193], v148 offset:18432
	ds_read_b128 v[198:201], v148 offset:19456
	ds_read_b128 v[202:205], v148 offset:20480
	ds_read_b128 v[206:209], v148 offset:21504
	ds_read_b128 v[210:213], v148 offset:22528
	ds_read_b128 v[214:217], v148 offset:23552
	global_load_lds_dwordx4 v[194:195], off
	s_add_i32 m0, s56, 0x2000
	v_lshl_add_u64 v[218:219], s[54:55], 0, v[128:129]
	s_add_u32 s54, s54, s4
	s_addc_u32 s55, s55, s5
	s_add_i32 s56, s45, s27
	global_load_lds_dwordx4 v[218:219], off
	v_lshl_add_u64 v[220:221], s[54:55], 0, v[132:133]
	s_mov_b32 m0, s56
	v_lshl_add_u64 v[222:223], s[54:55], 0, v[128:129]
	global_load_lds_dwordx4 v[220:221], off
	s_add_i32 m0, s56, 0x2000
	v_lshl_add_u64 v[224:225], s[24:25], 0, v[134:135]
	global_load_lds_dwordx4 v[222:223], off
	s_mov_b32 m0, s31
	v_lshl_add_u64 v[226:227], s[24:25], 0, v[130:131]
	global_load_lds_dwordx4 v[224:225], off
	s_mov_b32 m0, s34
	s_nop 0
	global_load_lds_dwordx4 v[226:227], off
	s_waitcnt vmcnt(8)
	s_waitcnt lgkmcnt(0)
	s_barrier
; #define PG8_STAGE(bufoff, gbase, voff) do { _Pragma("unroll") for (int _i = 0; _i < 2; ++_i) \
;         __builtin_amdgcn_global_load_lds((const unsigned*)((const char*)(gbase) + (voff)[_i]), (PG8_LAS unsigned*)(lds + (bufoff) + ldsw + _i * 8192), 16, 0, 0); } while (0)
; #define PG8_LDA(dst, b, h) do { _Pragma("unroll") for (int m = 0; m < 4; ++m) _Pragma("unroll") for (int k = 0; k < 2; ++k) dst[m][k] = *(const PG8_LAS bf16x8*)(lds + PG8_SA(b, h) + aoff + m * 2048 + k * 1024); } while (0)
; #define PG8_LDB(dst, b, h) do { _Pragma("unroll") for (int n = 0; n < 2; ++n) _Pragma("unroll") for (int k = 0; k < 2; ++k) dst[n][k] = *(const PG8_LAS bf16x8*)(lds + PG8_SB(b, h) + boff + n * 2048 + k * 1024); } while (0)
; #define PG8_MMA(ai, bj, At, Bt) do { __builtin_amdgcn_s_setprio(1); _Pragma("unroll") for (int m = 0; m < 4; ++m) _Pragma("unroll") for (int n = 0; n < 2; ++n) _Pragma("unroll") for (int k = 0; k < 2; ++k) \
;         acc[ai][bj][m][n] = __builtin_amdgcn_mfma_f32_16x16x32_bf16(Bt[n][k], At[m][k], acc[ai][bj][m][n], 0, 0, 0); __builtin_amdgcn_s_setprio(0); } while (0)
; #define PG8_WAIT_V(n) asm volatile("s_waitcnt vmcnt(" #n ")" ::: "memory")
; #define PG8_WAIT_L(n) asm volatile("s_waitcnt lgkmcnt(" #n ")" ::: "memory")
; #define PG8_BAR __builtin_amdgcn_s_barrier()
; #define PG8_SCHED __builtin_amdgcn_sched_barrier(0)
; template <class Epi, class Sched, bool ALIGN_EPI = false, bool SP2 = false>
; __device__ __forceinline__ void gemm_phase(PG8_LAS unsigned char* lds, const Gemm g, const Sched& S, const Epi& E) {
;     ...
;             PG8_WAIT_V(8); PG8_WAIT_L(0); PG8_BAR; PG8_MMA(1, 0, At, B0); PG8_MMA(1, 1, At, B1); PG8_BAR; PG8_SCHED;
;             PG8_LDB(B0, 1, 0); PG8_LDB(B1, 1, 1); PG8_SCHED; PG8_LDA(At, 1, 0); PG8_STAGE(PG8_SA(0, 1), a2 + hstep, voffA);
;             PG8_WAIT_V(8); PG8_WAIT_L(0); PG8_BAR; PG8_MMA(0, 0, At, B0); PG8_MMA(0, 1, At, B1); PG8_BAR; PG8_SCHED;
	s_setprio 1
	s_waitcnt lgkmcnt(0)
	v_mfma_f32_16x16x32_bf16 v[92:95], v[150:153], v[182:185], v[92:95]
	v_mfma_f32_16x16x32_bf16 v[84:87], v[150:153], v[190:193], v[84:87]
	v_mfma_f32_16x16x32_bf16 v[76:79], v[150:153], v[202:205], v[76:79]
	v_mfma_f32_16x16x32_bf16 v[68:71], v[150:153], v[210:213], v[68:71]
	v_mfma_f32_16x16x32_bf16 v[64:67], v[158:161], v[210:213], v[64:67]
	v_mfma_f32_16x16x32_bf16 v[72:75], v[158:161], v[202:205], v[72:75]
	v_mfma_f32_16x16x32_bf16 v[80:83], v[158:161], v[190:193], v[80:83]
	v_mfma_f32_16x16x32_bf16 v[88:91], v[158:161], v[182:185], v[88:91]
	v_mfma_f32_16x16x32_bf16 v[92:95], v[154:157], v[186:189], v[92:95]
	v_mfma_f32_16x16x32_bf16 v[84:87], v[154:157], v[198:201], v[84:87]
	v_mfma_f32_16x16x32_bf16 v[76:79], v[154:157], v[206:209], v[76:79]
	v_mfma_f32_16x16x32_bf16 v[68:71], v[154:157], v[214:217], v[68:71]
	v_mfma_f32_16x16x32_bf16 v[64:67], v[162:165], v[214:217], v[64:67]
	v_mfma_f32_16x16x32_bf16 v[72:75], v[162:165], v[206:209], v[72:75]
	v_mfma_f32_16x16x32_bf16 v[80:83], v[162:165], v[198:201], v[80:83]
	v_mfma_f32_16x16x32_bf16 v[88:91], v[162:165], v[186:189], v[88:91]
	s_setprio 0
	s_setprio 1
	v_mfma_f32_16x16x32_bf16 v[28:31], v[166:169], v[182:185], v[28:31]
	v_mfma_f32_16x16x32_bf16 v[20:23], v[166:169], v[190:193], v[20:23]
	v_mfma_f32_16x16x32_bf16 v[12:15], v[166:169], v[202:205], v[12:15]
	v_mfma_f32_16x16x32_bf16 v[4:7], v[166:169], v[210:213], v[4:7]
	v_mfma_f32_16x16x32_bf16 v[0:3], v[174:177], v[210:213], v[0:3]
	v_mfma_f32_16x16x32_bf16 v[8:11], v[174:177], v[202:205], v[8:11]
	v_mfma_f32_16x16x32_bf16 v[16:19], v[174:177], v[190:193], v[16:19]
	v_mfma_f32_16x16x32_bf16 v[24:27], v[174:177], v[182:185], v[24:27]
	v_mfma_f32_16x16x32_bf16 v[28:31], v[170:173], v[186:189], v[28:31]
	v_mfma_f32_16x16x32_bf16 v[20:23], v[170:173], v[198:201], v[20:23]
	v_mfma_f32_16x16x32_bf16 v[12:15], v[170:173], v[206:209], v[12:15]
	v_mfma_f32_16x16x32_bf16 v[4:7], v[170:173], v[214:217], v[4:7]
	v_mfma_f32_16x16x32_bf16 v[0:3], v[178:181], v[214:217], v[0:3]
	v_mfma_f32_16x16x32_bf16 v[8:11], v[178:181], v[206:209], v[8:11]
	v_mfma_f32_16x16x32_bf16 v[16:19], v[178:181], v[198:201], v[16:19]
	v_mfma_f32_16x16x32_bf16 v[24:27], v[178:181], v[186:189], v[24:27]
	s_setprio 0
	s_barrier
	s_add_i32 s54, 0, 0x18000
	s_add_i32 s55, 0, 0x1c000
	v_add_u32_e32 v162, s54, v145
	v_add_u32_e32 v178, s55, v145
	ds_read_b128 v[150:153], v162
	ds_read_b128 v[154:157], v162 offset:1024
	ds_read_b128 v[158:161], v162 offset:2048
	ds_read_b128 v[162:165], v162 offset:3072
	ds_read_b128 v[166:169], v178
	ds_read_b128 v[170:173], v178 offset:1024
	ds_read_b128 v[174:177], v178 offset:2048
	ds_read_b128 v[178:181], v178 offset:3072
	s_add_u32 s24, s24, s4
	s_addc_u32 s25, s25, s5
	s_mov_b32 m0, s35
	v_lshl_add_u64 v[228:229], s[24:25], 0, v[134:135]
	ds_read_b128 v[182:185], v148 offset:32768
	ds_read_b128 v[186:189], v148 offset:33792
	ds_read_b128 v[190:193], v148 offset:34816
	ds_read_b128 v[198:201], v148 offset:35840
	ds_read_b128 v[202:205], v148 offset:36864
	ds_read_b128 v[206:209], v148 offset:37888
	ds_read_b128 v[210:213], v148 offset:38912
	ds_read_b128 v[214:217], v148 offset:39936
	global_load_lds_dwordx4 v[228:229], off
	v_lshl_add_u64 v[228:229], s[24:25], 0, v[130:131]
	s_mov_b32 m0, s36
	s_nop 0
	global_load_lds_dwordx4 v[228:229], off
	s_waitcnt vmcnt(8)
	s_waitcnt lgkmcnt(0)
	s_barrier
	s_setprio 1
	s_waitcnt lgkmcnt(0)
	v_mfma_f32_16x16x32_bf16 v[120:123], v[150:153], v[182:185], v[120:123]
	v_mfma_f32_16x16x32_bf16 v[116:119], v[150:153], v[190:193], v[116:119]
	v_mfma_f32_16x16x32_bf16 v[108:111], v[150:153], v[202:205], v[108:111]
	v_mfma_f32_16x16x32_bf16 v[100:103], v[150:153], v[210:213], v[100:103]
	v_mfma_f32_16x16x32_bf16 v[96:99], v[158:161], v[210:213], v[96:99]
	v_mfma_f32_16x16x32_bf16 v[104:107], v[158:161], v[202:205], v[104:107]
	v_mfma_f32_16x16x32_bf16 v[112:115], v[158:161], v[190:193], v[112:115]
	v_mfma_f32_16x16x32_bf16 v[124:127], v[158:161], v[182:185], v[124:127]
	v_mfma_f32_16x16x32_bf16 v[120:123], v[154:157], v[186:189], v[120:123]
	v_mfma_f32_16x16x32_bf16 v[116:119], v[154:157], v[198:201], v[116:119]
	v_mfma_f32_16x16x32_bf16 v[108:111], v[154:157], v[206:209], v[108:111]
	v_mfma_f32_16x16x32_bf16 v[100:103], v[154:157], v[214:217], v[100:103]
	v_mfma_f32_16x16x32_bf16 v[96:99], v[162:165], v[214:217], v[96:99]
	v_mfma_f32_16x16x32_bf16 v[104:107], v[162:165], v[206:209], v[104:107]
	v_mfma_f32_16x16x32_bf16 v[112:115], v[162:165], v[198:201], v[112:115]
	v_mfma_f32_16x16x32_bf16 v[124:127], v[162:165], v[186:189], v[124:127]
	s_setprio 0
	s_setprio 1
	v_mfma_f32_16x16x32_bf16 v[60:63], v[166:169], v[182:185], v[60:63]
	v_mfma_f32_16x16x32_bf16 v[52:55], v[166:169], v[190:193], v[52:55]
	v_mfma_f32_16x16x32_bf16 v[44:47], v[166:169], v[202:205], v[44:47]
	v_mfma_f32_16x16x32_bf16 v[36:39], v[166:169], v[210:213], v[36:39]
	v_mfma_f32_16x16x32_bf16 v[32:35], v[174:177], v[210:213], v[32:35]
	v_mfma_f32_16x16x32_bf16 v[40:43], v[174:177], v[202:205], v[40:43]
	v_mfma_f32_16x16x32_bf16 v[48:51], v[174:177], v[190:193], v[48:51]
	v_mfma_f32_16x16x32_bf16 v[56:59], v[174:177], v[182:185], v[56:59]
	v_mfma_f32_16x16x32_bf16 v[60:63], v[170:173], v[186:189], v[60:63]
	v_mfma_f32_16x16x32_bf16 v[52:55], v[170:173], v[198:201], v[52:55]
	v_mfma_f32_16x16x32_bf16 v[44:47], v[170:173], v[206:209], v[44:47]
	v_mfma_f32_16x16x32_bf16 v[36:39], v[170:173], v[214:217], v[36:39]
	v_mfma_f32_16x16x32_bf16 v[32:35], v[178:181], v[214:217], v[32:35]
	v_mfma_f32_16x16x32_bf16 v[40:43], v[178:181], v[206:209], v[40:43]
	v_mfma_f32_16x16x32_bf16 v[48:51], v[178:181], v[198:201], v[48:51]
	v_mfma_f32_16x16x32_bf16 v[56:59], v[178:181], v[186:189], v[56:59]
	s_setprio 0
	s_barrier
; #define PG8_STAGE(bufoff, gbase, voff) do { _Pragma("unroll") for (int _i = 0; _i < 2; ++_i) \
;         __builtin_amdgcn_global_load_lds((const unsigned*)((const char*)(gbase) + (voff)[_i]), (PG8_LAS unsigned*)(lds + (bufoff) + ldsw + _i * 8192), 16, 0, 0); } while (0)
; #define PG8_LDA(dst, b, h) do { _Pragma("unroll") for (int m = 0; m < 4; ++m) _Pragma("unroll") for (int k = 0; k < 2; ++k) dst[m][k] = *(const PG8_LAS bf16x8*)(lds + PG8_SA(b, h) + aoff + m * 2048 + k * 1024); } while (0)
; #define PG8_MMA(ai, bj, At, Bt) do { __builtin_amdgcn_s_setprio(1); _Pragma("unroll") for (int m = 0; m < 4; ++m) _Pragma("unroll") for (int n = 0; n < 2; ++n) _Pragma("unroll") for (int k = 0; k < 2; ++k) \
;         acc[ai][bj][m][n] = __builtin_amdgcn_mfma_f32_16x16x32_bf16(Bt[n][k], At[m][k], acc[ai][bj][m][n], 0, 0, 0); __builtin_amdgcn_s_setprio(0); } while (0)
; #define PG8_WAIT_V(n) asm volatile("s_waitcnt vmcnt(" #n ")" ::: "memory")
; #define PG8_WAIT_L(n) asm volatile("s_waitcnt lgkmcnt(" #n ")" ::: "memory")
; #define PG8_BAR __builtin_amdgcn_s_barrier()
; #define PG8_SCHED __builtin_amdgcn_sched_barrier(0)
; template <class Epi, class Sched, bool ALIGN_EPI = false, bool SP2 = false>
; __device__ __forceinline__ void gemm_phase(PG8_LAS unsigned char* lds, const Gemm g, const Sched& S, const Epi& E) {
;     ...
;             PG8_LDA(At, 1, 1); PG8_STAGE(PG8_SB(1, 0), b3, voffB); PG8_STAGE(PG8_SB(1, 1), b3 + hstep, voffB); PG8_STAGE(PG8_SA(1, 0), a3, voffA);
;             PG8_WAIT_V(8); PG8_WAIT_L(0); PG8_BAR; PG8_MMA(1, 0, At, B0); PG8_MMA(1, 1, At, B1); PG8_BAR; PG8_SCHED;
	s_add_i32 s24, s54, s27
	v_lshl_add_u64 v[194:195], v[194:195], 0, s[14:15]
	s_mov_b32 m0, s24
	ds_read_b128 v[182:185], v148 offset:49152
	ds_read_b128 v[186:189], v148 offset:50176
	ds_read_b128 v[190:193], v148 offset:51200
	ds_read_b128 v[198:201], v148 offset:52224
	ds_read_b128 v[202:205], v148 offset:53248
	ds_read_b128 v[206:209], v148 offset:54272
	ds_read_b128 v[210:213], v148 offset:55296
	ds_read_b128 v[214:217], v148 offset:56320
	global_load_lds_dwordx4 v[194:195], off
	v_lshl_add_u64 v[194:195], v[218:219], 0, s[14:15]
	s_add_i32 m0, s24, 0x2000
	s_add_i32 s24, s55, s27
	global_load_lds_dwordx4 v[194:195], off
	v_lshl_add_u64 v[194:195], v[220:221], 0, s[14:15]
	s_mov_b32 m0, s24
	s_nop 0
	global_load_lds_dwordx4 v[194:195], off
	v_lshl_add_u64 v[194:195], v[222:223], 0, s[14:15]
	s_add_i32 m0, s24, 0x2000
	s_nop 0
	global_load_lds_dwordx4 v[194:195], off
	v_lshl_add_u64 v[194:195], v[224:225], 0, s[14:15]
	s_mov_b32 m0, s40
	s_nop 0
	global_load_lds_dwordx4 v[194:195], off
	v_lshl_add_u64 v[194:195], v[226:227], 0, s[14:15]
	s_mov_b32 m0, s41
	s_nop 0
	global_load_lds_dwordx4 v[194:195], off
	s_waitcnt vmcnt(8)
	s_waitcnt lgkmcnt(0)
	s_barrier
	s_setprio 1
	s_waitcnt lgkmcnt(0)
	v_mfma_f32_16x16x32_bf16 v[92:95], v[150:153], v[182:185], v[92:95]
	v_mfma_f32_16x16x32_bf16 v[84:87], v[150:153], v[190:193], v[84:87]
	v_mfma_f32_16x16x32_bf16 v[76:79], v[150:153], v[202:205], v[76:79]
	v_mfma_f32_16x16x32_bf16 v[68:71], v[150:153], v[210:213], v[68:71]
	v_mfma_f32_16x16x32_bf16 v[64:67], v[158:161], v[210:213], v[64:67]
	v_mfma_f32_16x16x32_bf16 v[72:75], v[158:161], v[202:205], v[72:75]
	v_mfma_f32_16x16x32_bf16 v[80:83], v[158:161], v[190:193], v[80:83]
	v_mfma_f32_16x16x32_bf16 v[88:91], v[158:161], v[182:185], v[88:91]
	v_mfma_f32_16x16x32_bf16 v[92:95], v[154:157], v[186:189], v[92:95]
	v_mfma_f32_16x16x32_bf16 v[84:87], v[154:157], v[198:201], v[84:87]
	v_mfma_f32_16x16x32_bf16 v[76:79], v[154:157], v[206:209], v[76:79]
	v_mfma_f32_16x16x32_bf16 v[68:71], v[154:157], v[214:217], v[68:71]
	v_mfma_f32_16x16x32_bf16 v[64:67], v[162:165], v[214:217], v[64:67]
	v_mfma_f32_16x16x32_bf16 v[72:75], v[162:165], v[206:209], v[72:75]
	v_mfma_f32_16x16x32_bf16 v[80:83], v[162:165], v[198:201], v[80:83]
	v_mfma_f32_16x16x32_bf16 v[88:91], v[162:165], v[186:189], v[88:91]
	s_setprio 0
	s_setprio 1
	v_mfma_f32_16x16x32_bf16 v[28:31], v[166:169], v[182:185], v[28:31]
	v_mfma_f32_16x16x32_bf16 v[20:23], v[166:169], v[190:193], v[20:23]
	v_mfma_f32_16x16x32_bf16 v[12:15], v[166:169], v[202:205], v[12:15]
	v_mfma_f32_16x16x32_bf16 v[4:7], v[166:169], v[210:213], v[4:7]
	v_mfma_f32_16x16x32_bf16 v[0:3], v[174:177], v[210:213], v[0:3]
	v_mfma_f32_16x16x32_bf16 v[8:11], v[174:177], v[202:205], v[8:11]
	v_mfma_f32_16x16x32_bf16 v[16:19], v[174:177], v[190:193], v[16:19]
	v_mfma_f32_16x16x32_bf16 v[24:27], v[174:177], v[182:185], v[24:27]
	v_mfma_f32_16x16x32_bf16 v[28:31], v[170:173], v[186:189], v[28:31]
	v_mfma_f32_16x16x32_bf16 v[20:23], v[170:173], v[198:201], v[20:23]
	v_mfma_f32_16x16x32_bf16 v[12:15], v[170:173], v[206:209], v[12:15]
	v_mfma_f32_16x16x32_bf16 v[4:7], v[170:173], v[214:217], v[4:7]
	v_mfma_f32_16x16x32_bf16 v[0:3], v[178:181], v[214:217], v[0:3]
	v_mfma_f32_16x16x32_bf16 v[8:11], v[178:181], v[206:209], v[8:11]
	v_mfma_f32_16x16x32_bf16 v[16:19], v[178:181], v[198:201], v[16:19]
	v_mfma_f32_16x16x32_bf16 v[24:27], v[178:181], v[186:189], v[24:27]
	s_setprio 0
	s_barrier
	s_add_u32 s22, s22, 0x100
	s_addc_u32 s23, s23, 0
	s_add_u32 s51, s51, 0x100
	s_addc_u32 s52, s52, 0
	s_cmp_ge_i32 s53, s38
	s_mov_b32 s24, s53
	s_cbranch_scc0 .LBB0_757

; #define PG8_STAGE(bufoff, gbase, voff) do { _Pragma("unroll") for (int _i = 0; _i < 2; ++_i) \
;         __builtin_amdgcn_global_load_lds((const unsigned*)((const char*)(gbase) + (voff)[_i]), (PG8_LAS unsigned*)(lds + (bufoff) + ldsw + _i * 8192), 16, 0, 0); } while (0)
; #define PG8_LDA(dst, b, h) do { _Pragma("unroll") for (int m = 0; m < 4; ++m) _Pragma("unroll") for (int k = 0; k < 2; ++k) dst[m][k] = *(const PG8_LAS bf16x8*)(lds + PG8_SA(b, h) + aoff + m * 2048 + k * 1024); } while (0)
; #define PG8_LDB(dst, b, h) do { _Pragma("unroll") for (int n = 0; n < 2; ++n) _Pragma("unroll") for (int k = 0; k < 2; ++k) dst[n][k] = *(const PG8_LAS bf16x8*)(lds + PG8_SB(b, h) + boff + n * 2048 + k * 1024); } while (0)
; #define PG8_MMA(ai, bj, At, Bt) do { __builtin_amdgcn_s_setprio(1); _Pragma("unroll") for (int m = 0; m < 4; ++m) _Pragma("unroll") for (int n = 0; n < 2; ++n) _Pragma("unroll") for (int k = 0; k < 2; ++k) \
;         acc[ai][bj][m][n] = __builtin_amdgcn_mfma_f32_16x16x32_bf16(Bt[n][k], At[m][k], acc[ai][bj][m][n], 0, 0, 0); __builtin_amdgcn_s_setprio(0); } while (0)
; #define PG8_WAIT_V(n) asm volatile("s_waitcnt vmcnt(" #n ")" ::: "memory")
; #define PG8_BAR __builtin_amdgcn_s_barrier()
; template <class Epi, class Sched, bool ALIGN_EPI = false, bool SP2 = false>
; __device__ __forceinline__ void gemm_phase(PG8_LAS unsigned char* lds, const Gemm g, const Sched& S, const Epi& E) {
;     ...
;         for (int t = 0; t < nt; t += 2) {
;             const bool last = (t == nt - 2);
;             const char* a1 = cA + (size_t)(t + 1) * kstep;
;             const char* a2 = last ? nA : cA + (size_t)(t + 2) * kstep; const char* b2 = last ? nB : cB + (size_t)(t + 2) * kstep;
;             const char* a3 = a2 + kstep; const char* b3 = b2 + kstep;
;             if (last && has_next) S.a_ready(nxt);
;             if constexpr (SP2) {
;             PG8_LDB(B0, 0, 0); PG8_LDB(B1, 0, 1); PG8_SCHED; PG8_LDA(At, 0, 0); PG8_STAGE(PG8_SA(1, 1), a1 + hstep, voffA);
;             PG8_WAIT_V(8); PG8_WAIT_L(0); PG8_BAR; PG8_MMA(0, 0, At, B0); PG8_MMA(0, 1, At, B1); PG8_BAR; PG8_SCHED;
;             PG8_LDA(At, 0, 1); PG8_STAGE(PG8_SB(0, 0), b2, voffB); PG8_STAGE(PG8_SB(0, 1), b2 + hstep, voffB); PG8_STAGE(PG8_SA(0, 0), a2, voffA);
;             PG8_WAIT_V(8); PG8_WAIT_L(0); PG8_BAR; PG8_MMA(1, 0, At, B0); PG8_MMA(1, 1, At, B1); PG8_BAR; PG8_SCHED;
.Lp9h_b:
	ds_read_b128 v[144:147], v151
	ds_read_b128 v[156:159], v151 offset:1024
	ds_read_b128 v[160:163], v151 offset:2048
	ds_read_b128 v[164:167], v151 offset:3072
	ds_read_b128 v[168:171], v152
	ds_read_b128 v[172:175], v152 offset:1024
	ds_read_b128 v[176:179], v152 offset:2048
	ds_read_b128 v[180:183], v152 offset:3072
	s_add_u32 s26, s24, 0xfffc0080
	s_addc_u32 s27, s25, -1
	s_cmp_eq_u32 s48, 12
	s_cselect_b32 s29, s17, s27
	s_cselect_b32 s28, s23, s26
	s_cselect_b32 s27, s15, s47
	s_cselect_b32 s26, s45, s46
	v_lshl_add_u64 v[218:219], s[24:25], 0, v[136:137]
	s_add_i32 m0, s31, 0xc000
	ds_read_b128 v[184:187], v153
	ds_read_b128 v[188:191], v153 offset:1024
	ds_read_b128 v[192:195], v153 offset:2048
	ds_read_b128 v[198:201], v153 offset:3072
	ds_read_b128 v[202:205], v153 offset:4096
	ds_read_b128 v[206:209], v153 offset:5120
	ds_read_b128 v[210:213], v153 offset:6144
	ds_read_b128 v[214:217], v153 offset:7168
	global_load_lds_dwordx4 v[218:219], off
	v_lshl_add_u64 v[218:219], s[24:25], 0, v[138:139]
	s_add_i32 m0, s31, 0xe000
	s_nop 0
	global_load_lds_dwordx4 v[218:219], off
	s_waitcnt vmcnt(8)
	s_waitcnt lgkmcnt(0)
	s_barrier
	s_setprio 1
	s_waitcnt lgkmcnt(0)
	v_mfma_f32_16x16x32_bf16 v[124:127], v[144:147], v[184:187], v[124:127]
	v_mfma_f32_16x16x32_bf16 v[108:111], v[144:147], v[192:195], v[108:111]
	v_mfma_f32_16x16x32_bf16 v[92:95], v[144:147], v[202:205], v[92:95]
	v_mfma_f32_16x16x32_bf16 v[76:79], v[144:147], v[210:213], v[76:79]
	v_mfma_f32_16x16x32_bf16 v[72:75], v[160:163], v[210:213], v[72:75]
	v_mfma_f32_16x16x32_bf16 v[88:91], v[160:163], v[202:205], v[88:91]
	v_mfma_f32_16x16x32_bf16 v[104:107], v[160:163], v[192:195], v[104:107]
	v_mfma_f32_16x16x32_bf16 v[120:123], v[160:163], v[184:187], v[120:123]
	v_mfma_f32_16x16x32_bf16 v[124:127], v[156:159], v[188:191], v[124:127]
	v_mfma_f32_16x16x32_bf16 v[108:111], v[156:159], v[198:201], v[108:111]
	v_mfma_f32_16x16x32_bf16 v[92:95], v[156:159], v[206:209], v[92:95]
	v_mfma_f32_16x16x32_bf16 v[76:79], v[156:159], v[214:217], v[76:79]
	v_mfma_f32_16x16x32_bf16 v[72:75], v[164:167], v[214:217], v[72:75]
	v_mfma_f32_16x16x32_bf16 v[88:91], v[164:167], v[206:209], v[88:91]
	v_mfma_f32_16x16x32_bf16 v[104:107], v[164:167], v[198:201], v[104:107]
	v_mfma_f32_16x16x32_bf16 v[120:123], v[164:167], v[188:191], v[120:123]
	s_setprio 0
	s_setprio 1
	v_mfma_f32_16x16x32_bf16 v[116:119], v[168:171], v[184:187], v[116:119]
	v_mfma_f32_16x16x32_bf16 v[100:103], v[168:171], v[192:195], v[100:103]
	v_mfma_f32_16x16x32_bf16 v[84:87], v[168:171], v[202:205], v[84:87]
	v_mfma_f32_16x16x32_bf16 v[68:71], v[168:171], v[210:213], v[68:71]
	v_mfma_f32_16x16x32_bf16 v[64:67], v[176:179], v[210:213], v[64:67]
	v_mfma_f32_16x16x32_bf16 v[80:83], v[176:179], v[202:205], v[80:83]
	v_mfma_f32_16x16x32_bf16 v[96:99], v[176:179], v[192:195], v[96:99]
	v_mfma_f32_16x16x32_bf16 v[112:115], v[176:179], v[184:187], v[112:115]
	v_mfma_f32_16x16x32_bf16 v[116:119], v[172:175], v[188:191], v[116:119]
	v_mfma_f32_16x16x32_bf16 v[100:103], v[172:175], v[198:201], v[100:103]
	v_mfma_f32_16x16x32_bf16 v[84:87], v[172:175], v[206:209], v[84:87]
	v_mfma_f32_16x16x32_bf16 v[68:71], v[172:175], v[214:217], v[68:71]
	v_mfma_f32_16x16x32_bf16 v[64:67], v[180:183], v[214:217], v[64:67]
	v_mfma_f32_16x16x32_bf16 v[80:83], v[180:183], v[206:209], v[80:83]
	v_mfma_f32_16x16x32_bf16 v[96:99], v[180:183], v[198:201], v[96:99]
	v_mfma_f32_16x16x32_bf16 v[112:115], v[180:183], v[188:191], v[112:115]
	s_setprio 0
	s_barrier
	s_add_i32 s49, s42, s30
	v_lshl_add_u64 v[218:219], s[26:27], 0, v[130:131]
	s_mov_b32 m0, s49
	ds_read_b128 v[184:187], v153 offset:16384
	ds_read_b128 v[188:191], v153 offset:17408
	ds_read_b128 v[192:195], v153 offset:18432
	ds_read_b128 v[198:201], v153 offset:19456
	ds_read_b128 v[202:205], v153 offset:20480
	ds_read_b128 v[206:209], v153 offset:21504
	ds_read_b128 v[210:213], v153 offset:22528
	ds_read_b128 v[214:217], v153 offset:23552
	global_load_lds_dwordx4 v[218:219], off
	s_add_i32 m0, s49, 0x2000
	s_add_u32 s50, s26, 0x40000
	v_lshl_add_u64 v[220:221], s[26:27], 0, v[134:135]
	s_addc_u32 s51, s27, 0
	s_add_i32 s49, s43, s30
	global_load_lds_dwordx4 v[220:221], off
	v_lshl_add_u64 v[222:223], s[50:51], 0, v[130:131]
	s_mov_b32 m0, s49
	v_lshl_add_u64 v[224:225], s[28:29], 0, v[132:133]
	global_load_lds_dwordx4 v[222:223], off
	v_lshl_add_u64 v[222:223], s[50:51], 0, v[134:135]
	s_add_i32 m0, s49, 0x2000
	s_nop 0
	global_load_lds_dwordx4 v[222:223], off
	v_lshl_add_u64 v[222:223], s[28:29], 0, v[128:129]
	s_mov_b32 m0, s31
	s_nop 0
	global_load_lds_dwordx4 v[222:223], off
	s_mov_b32 m0, s33
	s_nop 0
	global_load_lds_dwordx4 v[224:225], off
	s_waitcnt vmcnt(8)
	s_waitcnt lgkmcnt(0)
	s_barrier
; #define PG8_STAGE(bufoff, gbase, voff) do { _Pragma("unroll") for (int _i = 0; _i < 2; ++_i) \
;         __builtin_amdgcn_global_load_lds((const unsigned*)((const char*)(gbase) + (voff)[_i]), (PG8_LAS unsigned*)(lds + (bufoff) + ldsw + _i * 8192), 16, 0, 0); } while (0)
; #define PG8_LDA(dst, b, h) do { _Pragma("unroll") for (int m = 0; m < 4; ++m) _Pragma("unroll") for (int k = 0; k < 2; ++k) dst[m][k] = *(const PG8_LAS bf16x8*)(lds + PG8_SA(b, h) + aoff + m * 2048 + k * 1024); } while (0)
; #define PG8_LDB(dst, b, h) do { _Pragma("unroll") for (int n = 0; n < 2; ++n) _Pragma("unroll") for (int k = 0; k < 2; ++k) dst[n][k] = *(const PG8_LAS bf16x8*)(lds + PG8_SB(b, h) + boff + n * 2048 + k * 1024); } while (0)
; #define PG8_MMA(ai, bj, At, Bt) do { __builtin_amdgcn_s_setprio(1); _Pragma("unroll") for (int m = 0; m < 4; ++m) _Pragma("unroll") for (int n = 0; n < 2; ++n) _Pragma("unroll") for (int k = 0; k < 2; ++k) \
;         acc[ai][bj][m][n] = __builtin_amdgcn_mfma_f32_16x16x32_bf16(Bt[n][k], At[m][k], acc[ai][bj][m][n], 0, 0, 0); __builtin_amdgcn_s_setprio(0); } while (0)
; #define PG8_WAIT_V(n) asm volatile("s_waitcnt vmcnt(" #n ")" ::: "memory")
; #define PG8_WAIT_L(n) asm volatile("s_waitcnt lgkmcnt(" #n ")" ::: "memory")
; #define PG8_BAR __builtin_amdgcn_s_barrier()
; #define PG8_SCHED __builtin_amdgcn_sched_barrier(0)
; template <class Epi, class Sched, bool ALIGN_EPI = false, bool SP2 = false>
; __device__ __forceinline__ void gemm_phase(PG8_LAS unsigned char* lds, const Gemm g, const Sched& S, const Epi& E) {
;     ...
;             PG8_WAIT_V(8); PG8_WAIT_L(0); PG8_BAR; PG8_MMA(1, 0, At, B0); PG8_MMA(1, 1, At, B1); PG8_BAR; PG8_SCHED;
;             PG8_LDB(B0, 1, 0); PG8_LDB(B1, 1, 1); PG8_SCHED; PG8_LDA(At, 1, 0); PG8_STAGE(PG8_SA(0, 1), a2 + hstep, voffA);
;             PG8_WAIT_V(8); PG8_WAIT_L(0); PG8_BAR; PG8_MMA(0, 0, At, B0); PG8_MMA(0, 1, At, B1); PG8_BAR; PG8_SCHED;
	s_setprio 1
	s_waitcnt lgkmcnt(0)
	v_mfma_f32_16x16x32_bf16 v[60:63], v[144:147], v[184:187], v[60:63]
	v_mfma_f32_16x16x32_bf16 v[44:47], v[144:147], v[192:195], v[44:47]
	v_mfma_f32_16x16x32_bf16 v[28:31], v[144:147], v[202:205], v[28:31]
	v_mfma_f32_16x16x32_bf16 v[12:15], v[144:147], v[210:213], v[12:15]
	v_mfma_f32_16x16x32_bf16 v[8:11], v[160:163], v[210:213], v[8:11]
	v_mfma_f32_16x16x32_bf16 v[24:27], v[160:163], v[202:205], v[24:27]
	v_mfma_f32_16x16x32_bf16 v[40:43], v[160:163], v[192:195], v[40:43]
	v_mfma_f32_16x16x32_bf16 v[56:59], v[160:163], v[184:187], v[56:59]
	v_mfma_f32_16x16x32_bf16 v[60:63], v[156:159], v[188:191], v[60:63]
	v_mfma_f32_16x16x32_bf16 v[44:47], v[156:159], v[198:201], v[44:47]
	v_mfma_f32_16x16x32_bf16 v[28:31], v[156:159], v[206:209], v[28:31]
	v_mfma_f32_16x16x32_bf16 v[12:15], v[156:159], v[214:217], v[12:15]
	v_mfma_f32_16x16x32_bf16 v[8:11], v[164:167], v[214:217], v[8:11]
	v_mfma_f32_16x16x32_bf16 v[24:27], v[164:167], v[206:209], v[24:27]
	v_mfma_f32_16x16x32_bf16 v[40:43], v[164:167], v[198:201], v[40:43]
	v_mfma_f32_16x16x32_bf16 v[56:59], v[164:167], v[188:191], v[56:59]
	s_setprio 0
	s_setprio 1
	v_mfma_f32_16x16x32_bf16 v[52:55], v[168:171], v[184:187], v[52:55]
	v_mfma_f32_16x16x32_bf16 v[36:39], v[168:171], v[192:195], v[36:39]
	v_mfma_f32_16x16x32_bf16 v[20:23], v[168:171], v[202:205], v[20:23]
	v_mfma_f32_16x16x32_bf16 v[4:7], v[168:171], v[210:213], v[4:7]
	v_mfma_f32_16x16x32_bf16 v[0:3], v[176:179], v[210:213], v[0:3]
	v_mfma_f32_16x16x32_bf16 v[16:19], v[176:179], v[202:205], v[16:19]
	v_mfma_f32_16x16x32_bf16 v[32:35], v[176:179], v[192:195], v[32:35]
	v_mfma_f32_16x16x32_bf16 v[48:51], v[176:179], v[184:187], v[48:51]
	v_mfma_f32_16x16x32_bf16 v[52:55], v[172:175], v[188:191], v[52:55]
	v_mfma_f32_16x16x32_bf16 v[36:39], v[172:175], v[198:201], v[36:39]
	v_mfma_f32_16x16x32_bf16 v[20:23], v[172:175], v[206:209], v[20:23]
	v_mfma_f32_16x16x32_bf16 v[4:7], v[172:175], v[214:217], v[4:7]
	v_mfma_f32_16x16x32_bf16 v[0:3], v[180:183], v[214:217], v[0:3]
	v_mfma_f32_16x16x32_bf16 v[16:19], v[180:183], v[206:209], v[16:19]
	v_mfma_f32_16x16x32_bf16 v[32:35], v[180:183], v[198:201], v[32:35]
	v_mfma_f32_16x16x32_bf16 v[48:51], v[180:183], v[188:191], v[48:51]
	s_setprio 0
	s_barrier
	s_add_i32 s49, 0, 0x18000
	v_add_u32_e32 v155, s49, v149
	s_add_i32 s50, 0, 0x1c000
	ds_read_b128 v[144:147], v155
	ds_read_b128 v[156:159], v155 offset:1024
	ds_read_b128 v[160:163], v155 offset:2048
	ds_read_b128 v[164:167], v155 offset:3072
	v_add_u32_e32 v155, s50, v149
	ds_read_b128 v[168:171], v155
	ds_read_b128 v[172:175], v155 offset:1024
	ds_read_b128 v[176:179], v155 offset:2048
	ds_read_b128 v[180:183], v155 offset:3072
	s_add_u32 s28, s28, 0x40000
	s_addc_u32 s29, s29, 0
	s_mov_b32 m0, s34
	v_lshl_add_u64 v[226:227], s[28:29], 0, v[128:129]
	ds_read_b128 v[184:187], v153 offset:32768
	ds_read_b128 v[188:191], v153 offset:33792
	ds_read_b128 v[192:195], v153 offset:34816
	ds_read_b128 v[198:201], v153 offset:35840
	ds_read_b128 v[202:205], v153 offset:36864
	ds_read_b128 v[206:209], v153 offset:37888
	ds_read_b128 v[210:213], v153 offset:38912
	ds_read_b128 v[214:217], v153 offset:39936
	global_load_lds_dwordx4 v[226:227], off
	v_lshl_add_u64 v[226:227], s[28:29], 0, v[132:133]
	s_mov_b32 m0, s35
	s_nop 0
	global_load_lds_dwordx4 v[226:227], off
	s_waitcnt vmcnt(8)
	s_waitcnt lgkmcnt(0)
	s_barrier
	s_setprio 1
	s_waitcnt lgkmcnt(0)
	v_mfma_f32_16x16x32_bf16 v[124:127], v[144:147], v[184:187], v[124:127]
	v_mfma_f32_16x16x32_bf16 v[108:111], v[144:147], v[192:195], v[108:111]
	v_mfma_f32_16x16x32_bf16 v[92:95], v[144:147], v[202:205], v[92:95]
	v_mfma_f32_16x16x32_bf16 v[76:79], v[144:147], v[210:213], v[76:79]
	v_mfma_f32_16x16x32_bf16 v[72:75], v[160:163], v[210:213], v[72:75]
	v_mfma_f32_16x16x32_bf16 v[88:91], v[160:163], v[202:205], v[88:91]
	v_mfma_f32_16x16x32_bf16 v[104:107], v[160:163], v[192:195], v[104:107]
	v_mfma_f32_16x16x32_bf16 v[120:123], v[160:163], v[184:187], v[120:123]
	v_mfma_f32_16x16x32_bf16 v[124:127], v[156:159], v[188:191], v[124:127]
	v_mfma_f32_16x16x32_bf16 v[108:111], v[156:159], v[198:201], v[108:111]
	v_mfma_f32_16x16x32_bf16 v[92:95], v[156:159], v[206:209], v[92:95]
	v_mfma_f32_16x16x32_bf16 v[76:79], v[156:159], v[214:217], v[76:79]
	v_mfma_f32_16x16x32_bf16 v[72:75], v[164:167], v[214:217], v[72:75]
	v_mfma_f32_16x16x32_bf16 v[88:91], v[164:167], v[206:209], v[88:91]
	v_mfma_f32_16x16x32_bf16 v[104:107], v[164:167], v[198:201], v[104:107]
	v_mfma_f32_16x16x32_bf16 v[120:123], v[164:167], v[188:191], v[120:123]
	s_setprio 0
	s_setprio 1
	v_mfma_f32_16x16x32_bf16 v[116:119], v[168:171], v[184:187], v[116:119]
	v_mfma_f32_16x16x32_bf16 v[100:103], v[168:171], v[192:195], v[100:103]
	v_mfma_f32_16x16x32_bf16 v[84:87], v[168:171], v[202:205], v[84:87]
	v_mfma_f32_16x16x32_bf16 v[68:71], v[168:171], v[210:213], v[68:71]
	v_mfma_f32_16x16x32_bf16 v[64:67], v[176:179], v[210:213], v[64:67]
	v_mfma_f32_16x16x32_bf16 v[80:83], v[176:179], v[202:205], v[80:83]
	v_mfma_f32_16x16x32_bf16 v[96:99], v[176:179], v[192:195], v[96:99]
	v_mfma_f32_16x16x32_bf16 v[112:115], v[176:179], v[184:187], v[112:115]
	v_mfma_f32_16x16x32_bf16 v[116:119], v[172:175], v[188:191], v[116:119]
	v_mfma_f32_16x16x32_bf16 v[100:103], v[172:175], v[198:201], v[100:103]
	v_mfma_f32_16x16x32_bf16 v[84:87], v[172:175], v[206:209], v[84:87]
	v_mfma_f32_16x16x32_bf16 v[68:71], v[172:175], v[214:217], v[68:71]
	v_mfma_f32_16x16x32_bf16 v[64:67], v[180:183], v[214:217], v[64:67]
	v_mfma_f32_16x16x32_bf16 v[80:83], v[180:183], v[206:209], v[80:83]
	v_mfma_f32_16x16x32_bf16 v[96:99], v[180:183], v[198:201], v[96:99]
	v_mfma_f32_16x16x32_bf16 v[112:115], v[180:183], v[188:191], v[112:115]
	s_setprio 0
	s_barrier
; #define PG8_STAGE(bufoff, gbase, voff) do { _Pragma("unroll") for (int _i = 0; _i < 2; ++_i) \
;         __builtin_amdgcn_global_load_lds((const unsigned*)((const char*)(gbase) + (voff)[_i]), (PG8_LAS unsigned*)(lds + (bufoff) + ldsw + _i * 8192), 16, 0, 0); } while (0)
; #define PG8_LDA(dst, b, h) do { _Pragma("unroll") for (int m = 0; m < 4; ++m) _Pragma("unroll") for (int k = 0; k < 2; ++k) dst[m][k] = *(const PG8_LAS bf16x8*)(lds + PG8_SA(b, h) + aoff + m * 2048 + k * 1024); } while (0)
; #define PG8_MMA(ai, bj, At, Bt) do { __builtin_amdgcn_s_setprio(1); _Pragma("unroll") for (int m = 0; m < 4; ++m) _Pragma("unroll") for (int n = 0; n < 2; ++n) _Pragma("unroll") for (int k = 0; k < 2; ++k) \
;         acc[ai][bj][m][n] = __builtin_amdgcn_mfma_f32_16x16x32_bf16(Bt[n][k], At[m][k], acc[ai][bj][m][n], 0, 0, 0); __builtin_amdgcn_s_setprio(0); } while (0)
; #define PG8_WAIT_V(n) asm volatile("s_waitcnt vmcnt(" #n ")" ::: "memory")
; #define PG8_WAIT_L(n) asm volatile("s_waitcnt lgkmcnt(" #n ")" ::: "memory")
; #define PG8_BAR __builtin_amdgcn_s_barrier()
; #define PG8_SCHED __builtin_amdgcn_sched_barrier(0)
; template <class Epi, class Sched, bool ALIGN_EPI = false, bool SP2 = false>
; __device__ __forceinline__ void gemm_phase(PG8_LAS unsigned char* lds, const Gemm g, const Sched& S, const Epi& E) {
;     ...
;             PG8_LDA(At, 1, 1); PG8_STAGE(PG8_SB(1, 0), b3, voffB); PG8_STAGE(PG8_SB(1, 1), b3 + hstep, voffB); PG8_STAGE(PG8_SA(1, 0), a3, voffA);
;             PG8_WAIT_V(8); PG8_WAIT_L(0); PG8_BAR; PG8_MMA(1, 0, At, B0); PG8_MMA(1, 1, At, B1); PG8_BAR; PG8_SCHED;
	s_add_i32 s28, s49, s30
	v_lshl_add_u64 v[218:219], v[218:219], 0, s[10:11]
	s_mov_b32 m0, s28
	ds_read_b128 v[184:187], v153 offset:49152
	ds_read_b128 v[188:191], v153 offset:50176
	ds_read_b128 v[192:195], v153 offset:51200
	ds_read_b128 v[198:201], v153 offset:52224
	ds_read_b128 v[202:205], v153 offset:53248
	ds_read_b128 v[206:209], v153 offset:54272
	ds_read_b128 v[210:213], v153 offset:55296
	ds_read_b128 v[214:217], v153 offset:56320
	global_load_lds_dwordx4 v[218:219], off
	s_add_i32 m0, s28, 0x2000
	s_add_u32 s26, s26, 0x40080
	v_lshl_add_u64 v[218:219], v[220:221], 0, s[10:11]
	s_addc_u32 s27, s27, 0
	s_add_i32 s28, s50, s30
	global_load_lds_dwordx4 v[218:219], off
	v_lshl_add_u64 v[218:219], s[26:27], 0, v[130:131]
	s_mov_b32 m0, s28
	s_nop 0
	global_load_lds_dwordx4 v[218:219], off
	v_lshl_add_u64 v[218:219], s[26:27], 0, v[134:135]
	s_add_i32 m0, s28, 0x2000
	s_nop 0
	global_load_lds_dwordx4 v[218:219], off
	v_lshl_add_u64 v[218:219], v[222:223], 0, s[10:11]
	s_mov_b32 m0, s39
	s_nop 0
	global_load_lds_dwordx4 v[218:219], off
	v_lshl_add_u64 v[218:219], v[224:225], 0, s[10:11]
	s_mov_b32 m0, s40
	s_nop 0
	global_load_lds_dwordx4 v[218:219], off
	s_waitcnt vmcnt(8)
	s_waitcnt lgkmcnt(0)
	s_barrier
	s_setprio 1
	s_waitcnt lgkmcnt(0)
	v_mfma_f32_16x16x32_bf16 v[60:63], v[144:147], v[184:187], v[60:63]
	v_mfma_f32_16x16x32_bf16 v[44:47], v[144:147], v[192:195], v[44:47]
	v_mfma_f32_16x16x32_bf16 v[28:31], v[144:147], v[202:205], v[28:31]
	v_mfma_f32_16x16x32_bf16 v[12:15], v[144:147], v[210:213], v[12:15]
	v_mfma_f32_16x16x32_bf16 v[8:11], v[160:163], v[210:213], v[8:11]
	v_mfma_f32_16x16x32_bf16 v[24:27], v[160:163], v[202:205], v[24:27]
	v_mfma_f32_16x16x32_bf16 v[40:43], v[160:163], v[192:195], v[40:43]
	v_mfma_f32_16x16x32_bf16 v[56:59], v[160:163], v[184:187], v[56:59]
	v_mfma_f32_16x16x32_bf16 v[60:63], v[156:159], v[188:191], v[60:63]
	v_mfma_f32_16x16x32_bf16 v[44:47], v[156:159], v[198:201], v[44:47]
	v_mfma_f32_16x16x32_bf16 v[28:31], v[156:159], v[206:209], v[28:31]
	v_mfma_f32_16x16x32_bf16 v[12:15], v[156:159], v[214:217], v[12:15]
	v_mfma_f32_16x16x32_bf16 v[8:11], v[164:167], v[214:217], v[8:11]
	v_mfma_f32_16x16x32_bf16 v[24:27], v[164:167], v[206:209], v[24:27]
	v_mfma_f32_16x16x32_bf16 v[40:43], v[164:167], v[198:201], v[40:43]
	v_mfma_f32_16x16x32_bf16 v[56:59], v[164:167], v[188:191], v[56:59]
	s_setprio 0
	s_setprio 1
	v_mfma_f32_16x16x32_bf16 v[52:55], v[168:171], v[184:187], v[52:55]
	v_mfma_f32_16x16x32_bf16 v[36:39], v[168:171], v[192:195], v[36:39]
	v_mfma_f32_16x16x32_bf16 v[20:23], v[168:171], v[202:205], v[20:23]
	v_mfma_f32_16x16x32_bf16 v[4:7], v[168:171], v[210:213], v[4:7]
	v_mfma_f32_16x16x32_bf16 v[0:3], v[176:179], v[210:213], v[0:3]
	v_mfma_f32_16x16x32_bf16 v[16:19], v[176:179], v[202:205], v[16:19]
	v_mfma_f32_16x16x32_bf16 v[32:35], v[176:179], v[192:195], v[32:35]
	v_mfma_f32_16x16x32_bf16 v[48:51], v[176:179], v[184:187], v[48:51]
	v_mfma_f32_16x16x32_bf16 v[52:55], v[172:175], v[188:191], v[52:55]
	v_mfma_f32_16x16x32_bf16 v[36:39], v[172:175], v[198:201], v[36:39]
	v_mfma_f32_16x16x32_bf16 v[20:23], v[172:175], v[206:209], v[20:23]
	v_mfma_f32_16x16x32_bf16 v[4:7], v[172:175], v[214:217], v[4:7]
	v_mfma_f32_16x16x32_bf16 v[0:3], v[180:183], v[214:217], v[0:3]
	v_mfma_f32_16x16x32_bf16 v[16:19], v[180:183], v[206:209], v[16:19]
	v_mfma_f32_16x16x32_bf16 v[32:35], v[180:183], v[198:201], v[32:35]
	v_mfma_f32_16x16x32_bf16 v[48:51], v[180:183], v[188:191], v[48:51]
	s_setprio 0
	s_barrier
	s_add_i32 s48, s48, 2
	s_add_u32 s24, s24, 0x100
	s_addc_u32 s25, s25, 0
	s_add_u32 s46, s46, 0x100
	s_addc_u32 s47, s47, 0
	s_cmp_gt_u32 s48, 13
	s_cbranch_scc0 .LBB0_991
	s_and_b64 vcc, exec, s[12:13]
	s_cbranch_vccz .LBB0_994
	s_barrier

; #define PG8_STAGE(bufoff, gbase, voff) do { _Pragma("unroll") for (int _i = 0; _i < 2; ++_i) \
;         __builtin_amdgcn_global_load_lds((const unsigned*)((const char*)(gbase) + (voff)[_i]), (PG8_LAS unsigned*)(lds + (bufoff) + ldsw + _i * 8192), 16, 0, 0); } while (0)
; #define PG8_LDA(dst, b, h) do { _Pragma("unroll") for (int m = 0; m < 4; ++m) _Pragma("unroll") for (int k = 0; k < 2; ++k) dst[m][k] = *(const PG8_LAS bf16x8*)(lds + PG8_SA(b, h) + aoff + m * 2048 + k * 1024); } while (0)
; #define PG8_LDB(dst, b, h) do { _Pragma("unroll") for (int n = 0; n < 2; ++n) _Pragma("unroll") for (int k = 0; k < 2; ++k) dst[n][k] = *(const PG8_LAS bf16x8*)(lds + PG8_SB(b, h) + boff + n * 2048 + k * 1024); } while (0)
; #define PG8_MMA(ai, bj, At, Bt) do { __builtin_amdgcn_s_setprio(1); _Pragma("unroll") for (int m = 0; m < 4; ++m) _Pragma("unroll") for (int n = 0; n < 2; ++n) _Pragma("unroll") for (int k = 0; k < 2; ++k) \
;         acc[ai][bj][m][n] = __builtin_amdgcn_mfma_f32_16x16x32_bf16(Bt[n][k], At[m][k], acc[ai][bj][m][n], 0, 0, 0); __builtin_amdgcn_s_setprio(0); } while (0)
; #define PG8_WAIT_V(n) asm volatile("s_waitcnt vmcnt(" #n ")" ::: "memory")
; #define PG8_WAIT_L(n) asm volatile("s_waitcnt lgkmcnt(" #n ")" ::: "memory")
; #define PG8_BAR __builtin_amdgcn_s_barrier()
; #define PG8_SCHED __builtin_amdgcn_sched_barrier(0)
; template <class Epi, class Sched, bool ALIGN_EPI = false, bool SP2 = false>
; __device__ __forceinline__ void gemm_phase(PG8_LAS unsigned char* lds, const Gemm g, const Sched& S, const Epi& E) {
;     ...
;             PG8_LDB(B0, 0, 0); PG8_LDB(B1, 0, 1); PG8_SCHED; PG8_LDA(At, 0, 0); PG8_STAGE(PG8_SA(1, 1), a1 + hstep, voffA);
;             PG8_WAIT_V(8); PG8_WAIT_L(0); PG8_BAR; PG8_MMA(0, 0, At, B0); PG8_MMA(0, 1, At, B1); PG8_BAR; PG8_SCHED;
;             PG8_LDA(At, 0, 1); PG8_STAGE(PG8_SB(0, 0), b2, voffB); PG8_STAGE(PG8_SB(0, 1), b2 + hstep, voffB); PG8_STAGE(PG8_SA(0, 0), a2, voffA);
;             PG8_WAIT_V(8); PG8_WAIT_L(0); PG8_BAR; PG8_MMA(1, 0, At, B0); PG8_MMA(1, 1, At, B1); PG8_BAR; PG8_SCHED;
.Lrw2_b0:
	s_waitcnt lgkmcnt(0)
	s_barrier
	s_setprio 1
	s_waitcnt lgkmcnt(0)
	v_mfma_f32_16x16x32_bf16 v[124:127], v[144:147], v[184:187], v[124:127]
	v_mfma_f32_16x16x32_bf16 v[108:111], v[144:147], v[192:195], v[108:111]
	v_mfma_f32_16x16x32_bf16 v[92:95], v[144:147], v[202:205], v[92:95]
	v_mfma_f32_16x16x32_bf16 v[76:79], v[144:147], v[210:213], v[76:79]
	v_mfma_f32_16x16x32_bf16 v[68:71], v[160:163], v[210:213], v[68:71]
	v_mfma_f32_16x16x32_bf16 v[84:87], v[160:163], v[202:205], v[84:87]
	v_mfma_f32_16x16x32_bf16 v[100:103], v[160:163], v[192:195], v[100:103]
	v_mfma_f32_16x16x32_bf16 v[116:119], v[160:163], v[184:187], v[116:119]
	v_mfma_f32_16x16x32_bf16 v[124:127], v[156:159], v[188:191], v[124:127]
	v_mfma_f32_16x16x32_bf16 v[108:111], v[156:159], v[198:201], v[108:111]
	v_mfma_f32_16x16x32_bf16 v[92:95], v[156:159], v[206:209], v[92:95]
	v_mfma_f32_16x16x32_bf16 v[76:79], v[156:159], v[214:217], v[76:79]
	v_mfma_f32_16x16x32_bf16 v[68:71], v[164:167], v[214:217], v[68:71]
	v_mfma_f32_16x16x32_bf16 v[84:87], v[164:167], v[206:209], v[84:87]
	v_mfma_f32_16x16x32_bf16 v[100:103], v[164:167], v[198:201], v[100:103]
	v_mfma_f32_16x16x32_bf16 v[116:119], v[164:167], v[188:191], v[116:119]
	s_setprio 0
	s_setprio 1
	v_mfma_f32_16x16x32_bf16 v[120:123], v[168:171], v[184:187], v[120:123]
	v_mfma_f32_16x16x32_bf16 v[104:107], v[168:171], v[192:195], v[104:107]
	v_mfma_f32_16x16x32_bf16 v[88:91], v[168:171], v[202:205], v[88:91]
	v_mfma_f32_16x16x32_bf16 v[72:75], v[168:171], v[210:213], v[72:75]
	v_mfma_f32_16x16x32_bf16 v[64:67], v[176:179], v[210:213], v[64:67]
	v_mfma_f32_16x16x32_bf16 v[80:83], v[176:179], v[202:205], v[80:83]
	v_mfma_f32_16x16x32_bf16 v[96:99], v[176:179], v[192:195], v[96:99]
	v_mfma_f32_16x16x32_bf16 v[112:115], v[176:179], v[184:187], v[112:115]
	v_mfma_f32_16x16x32_bf16 v[120:123], v[172:175], v[188:191], v[120:123]
	v_mfma_f32_16x16x32_bf16 v[104:107], v[172:175], v[198:201], v[104:107]
	v_mfma_f32_16x16x32_bf16 v[88:91], v[172:175], v[206:209], v[88:91]
	v_mfma_f32_16x16x32_bf16 v[72:75], v[172:175], v[214:217], v[72:75]
	v_mfma_f32_16x16x32_bf16 v[64:67], v[180:183], v[214:217], v[64:67]
	v_mfma_f32_16x16x32_bf16 v[80:83], v[180:183], v[206:209], v[80:83]
	v_mfma_f32_16x16x32_bf16 v[96:99], v[180:183], v[198:201], v[96:99]
	v_mfma_f32_16x16x32_bf16 v[112:115], v[180:183], v[188:191], v[112:115]
	s_setprio 0
	s_barrier
	s_add_i32 s51, s44, s33
	v_lshl_add_u64 v[218:219], s[28:29], 0, v[130:131]
	s_mov_b32 m0, s51
	ds_read_b128 v[184:187], v155 offset:16384
	ds_read_b128 v[188:191], v155 offset:17408
	ds_read_b128 v[192:195], v155 offset:18432
	ds_read_b128 v[198:201], v155 offset:19456
	ds_read_b128 v[202:205], v155 offset:20480
	ds_read_b128 v[206:209], v155 offset:21504
	ds_read_b128 v[210:213], v155 offset:22528
	ds_read_b128 v[214:217], v155 offset:23552
	global_load_lds_dwordx4 v[218:219], off
	s_add_i32 m0, s51, 0x2000
	s_add_u32 s52, s28, 0x40000
	v_lshl_add_u64 v[220:221], s[28:29], 0, v[134:135]
	s_addc_u32 s53, s29, 0
	s_add_i32 s51, s45, s33
	global_load_lds_dwordx4 v[220:221], off
	v_lshl_add_u64 v[222:223], s[52:53], 0, v[130:131]
	s_mov_b32 m0, s51
	v_lshl_add_u64 v[224:225], s[30:31], 0, v[132:133]
	global_load_lds_dwordx4 v[222:223], off
	v_lshl_add_u64 v[222:223], s[52:53], 0, v[134:135]
	s_add_i32 m0, s51, 0x2000
	s_nop 0
	global_load_lds_dwordx4 v[222:223], off
	v_lshl_add_u64 v[222:223], s[30:31], 0, v[128:129]
	s_mov_b32 m0, s25
	s_nop 0
	global_load_lds_dwordx4 v[222:223], off
	s_mov_b32 m0, s34
	s_nop 0
	global_load_lds_dwordx4 v[224:225], off
	s_cmp_eq_u32 s50, s101
	s_cbranch_scc1 .Lrw2_r1
	s_waitcnt vmcnt(8)
.Lrw2_b1:
	s_waitcnt lgkmcnt(0)
	s_barrier
	s_setprio 1
	s_waitcnt lgkmcnt(0)
	v_mfma_f32_16x16x32_bf16 v[60:63], v[144:147], v[184:187], v[60:63]
	v_mfma_f32_16x16x32_bf16 v[44:47], v[144:147], v[192:195], v[44:47]
	v_mfma_f32_16x16x32_bf16 v[28:31], v[144:147], v[202:205], v[28:31]
	v_mfma_f32_16x16x32_bf16 v[12:15], v[144:147], v[210:213], v[12:15]
	v_mfma_f32_16x16x32_bf16 v[4:7], v[160:163], v[210:213], v[4:7]
	v_mfma_f32_16x16x32_bf16 v[20:23], v[160:163], v[202:205], v[20:23]
	v_mfma_f32_16x16x32_bf16 v[36:39], v[160:163], v[192:195], v[36:39]
	v_mfma_f32_16x16x32_bf16 v[52:55], v[160:163], v[184:187], v[52:55]
	v_mfma_f32_16x16x32_bf16 v[60:63], v[156:159], v[188:191], v[60:63]
	v_mfma_f32_16x16x32_bf16 v[44:47], v[156:159], v[198:201], v[44:47]
	v_mfma_f32_16x16x32_bf16 v[28:31], v[156:159], v[206:209], v[28:31]
	v_mfma_f32_16x16x32_bf16 v[12:15], v[156:159], v[214:217], v[12:15]
	v_mfma_f32_16x16x32_bf16 v[4:7], v[164:167], v[214:217], v[4:7]
	v_mfma_f32_16x16x32_bf16 v[20:23], v[164:167], v[206:209], v[20:23]
	v_mfma_f32_16x16x32_bf16 v[36:39], v[164:167], v[198:201], v[36:39]
	v_mfma_f32_16x16x32_bf16 v[52:55], v[164:167], v[188:191], v[52:55]
	s_setprio 0
	s_setprio 1
	v_mfma_f32_16x16x32_bf16 v[56:59], v[168:171], v[184:187], v[56:59]
	v_mfma_f32_16x16x32_bf16 v[40:43], v[168:171], v[192:195], v[40:43]
	v_mfma_f32_16x16x32_bf16 v[24:27], v[168:171], v[202:205], v[24:27]
	v_mfma_f32_16x16x32_bf16 v[8:11], v[168:171], v[210:213], v[8:11]
	v_mfma_f32_16x16x32_bf16 v[0:3], v[176:179], v[210:213], v[0:3]
	v_mfma_f32_16x16x32_bf16 v[16:19], v[176:179], v[202:205], v[16:19]
	v_mfma_f32_16x16x32_bf16 v[32:35], v[176:179], v[192:195], v[32:35]
	v_mfma_f32_16x16x32_bf16 v[48:51], v[176:179], v[184:187], v[48:51]
	v_mfma_f32_16x16x32_bf16 v[56:59], v[172:175], v[188:191], v[56:59]
	v_mfma_f32_16x16x32_bf16 v[40:43], v[172:175], v[198:201], v[40:43]
	v_mfma_f32_16x16x32_bf16 v[24:27], v[172:175], v[206:209], v[24:27]
	v_mfma_f32_16x16x32_bf16 v[8:11], v[172:175], v[214:217], v[8:11]
	v_mfma_f32_16x16x32_bf16 v[0:3], v[180:183], v[214:217], v[0:3]
	v_mfma_f32_16x16x32_bf16 v[16:19], v[180:183], v[206:209], v[16:19]
	v_mfma_f32_16x16x32_bf16 v[32:35], v[180:183], v[198:201], v[32:35]
	v_mfma_f32_16x16x32_bf16 v[48:51], v[180:183], v[188:191], v[48:51]
	s_setprio 0
	s_barrier
; #define PG8_STAGE(bufoff, gbase, voff) do { _Pragma("unroll") for (int _i = 0; _i < 2; ++_i) \
;         __builtin_amdgcn_global_load_lds((const unsigned*)((const char*)(gbase) + (voff)[_i]), (PG8_LAS unsigned*)(lds + (bufoff) + ldsw + _i * 8192), 16, 0, 0); } while (0)
; #define PG8_LDA(dst, b, h) do { _Pragma("unroll") for (int m = 0; m < 4; ++m) _Pragma("unroll") for (int k = 0; k < 2; ++k) dst[m][k] = *(const PG8_LAS bf16x8*)(lds + PG8_SA(b, h) + aoff + m * 2048 + k * 1024); } while (0)
; #define PG8_LDB(dst, b, h) do { _Pragma("unroll") for (int n = 0; n < 2; ++n) _Pragma("unroll") for (int k = 0; k < 2; ++k) dst[n][k] = *(const PG8_LAS bf16x8*)(lds + PG8_SB(b, h) + boff + n * 2048 + k * 1024); } while (0)
; #define PG8_MMA(ai, bj, At, Bt) do { __builtin_amdgcn_s_setprio(1); _Pragma("unroll") for (int m = 0; m < 4; ++m) _Pragma("unroll") for (int n = 0; n < 2; ++n) _Pragma("unroll") for (int k = 0; k < 2; ++k) \
;         acc[ai][bj][m][n] = __builtin_amdgcn_mfma_f32_16x16x32_bf16(Bt[n][k], At[m][k], acc[ai][bj][m][n], 0, 0, 0); __builtin_amdgcn_s_setprio(0); } while (0)
; #define PG8_WAIT_V(n) asm volatile("s_waitcnt vmcnt(" #n ")" ::: "memory")
; #define PG8_WAIT_L(n) asm volatile("s_waitcnt lgkmcnt(" #n ")" ::: "memory")
; #define PG8_BAR __builtin_amdgcn_s_barrier()
; #define PG8_SCHED __builtin_amdgcn_sched_barrier(0)
; template <class Epi, class Sched, bool ALIGN_EPI = false, bool SP2 = false>
; __device__ __forceinline__ void gemm_phase(PG8_LAS unsigned char* lds, const Gemm g, const Sched& S, const Epi& E) {
;     ...
;             PG8_LDB(B0, 1, 0); PG8_LDB(B1, 1, 1); PG8_SCHED; PG8_LDA(At, 1, 0); PG8_STAGE(PG8_SA(0, 1), a2 + hstep, voffA);
;             PG8_WAIT_V(8); PG8_WAIT_L(0); PG8_BAR; PG8_MMA(0, 0, At, B0); PG8_MMA(0, 1, At, B1); PG8_BAR; PG8_SCHED;
	s_add_i32 s51, 0, 0x18000
	v_add_u32_e32 v148, s51, v151
	s_add_i32 s52, 0, 0x1c000
	ds_read_b128 v[144:147], v148
	ds_read_b128 v[156:159], v148 offset:1024
	ds_read_b128 v[160:163], v148 offset:2048
	ds_read_b128 v[164:167], v148 offset:3072
	v_add_u32_e32 v148, s52, v151
	ds_read_b128 v[168:171], v148
	ds_read_b128 v[172:175], v148 offset:1024
	ds_read_b128 v[176:179], v148 offset:2048
	ds_read_b128 v[180:183], v148 offset:3072
	s_add_u32 s30, s30, 0x40000
	s_addc_u32 s31, s31, 0
	s_mov_b32 m0, s35
	v_lshl_add_u64 v[226:227], s[30:31], 0, v[128:129]
	ds_read_b128 v[184:187], v155 offset:32768
	ds_read_b128 v[188:191], v155 offset:33792
	ds_read_b128 v[192:195], v155 offset:34816
	ds_read_b128 v[198:201], v155 offset:35840
	ds_read_b128 v[202:205], v155 offset:36864
	ds_read_b128 v[206:209], v155 offset:37888
	ds_read_b128 v[210:213], v155 offset:38912
	ds_read_b128 v[214:217], v155 offset:39936
	global_load_lds_dwordx4 v[226:227], off
	v_lshl_add_u64 v[226:227], s[30:31], 0, v[132:133]
	s_mov_b32 m0, s36
	s_nop 0
	global_load_lds_dwordx4 v[226:227], off
	s_waitcnt vmcnt(8)
	s_waitcnt lgkmcnt(0)
	s_barrier
	s_setprio 1
	s_waitcnt lgkmcnt(0)
	v_mfma_f32_16x16x32_bf16 v[124:127], v[144:147], v[184:187], v[124:127]
	v_mfma_f32_16x16x32_bf16 v[108:111], v[144:147], v[192:195], v[108:111]
	v_mfma_f32_16x16x32_bf16 v[92:95], v[144:147], v[202:205], v[92:95]
	v_mfma_f32_16x16x32_bf16 v[76:79], v[144:147], v[210:213], v[76:79]
	v_mfma_f32_16x16x32_bf16 v[68:71], v[160:163], v[210:213], v[68:71]
	v_mfma_f32_16x16x32_bf16 v[84:87], v[160:163], v[202:205], v[84:87]
	v_mfma_f32_16x16x32_bf16 v[100:103], v[160:163], v[192:195], v[100:103]
	v_mfma_f32_16x16x32_bf16 v[116:119], v[160:163], v[184:187], v[116:119]
	v_mfma_f32_16x16x32_bf16 v[124:127], v[156:159], v[188:191], v[124:127]
	v_mfma_f32_16x16x32_bf16 v[108:111], v[156:159], v[198:201], v[108:111]
	v_mfma_f32_16x16x32_bf16 v[92:95], v[156:159], v[206:209], v[92:95]
	v_mfma_f32_16x16x32_bf16 v[76:79], v[156:159], v[214:217], v[76:79]
	v_mfma_f32_16x16x32_bf16 v[68:71], v[164:167], v[214:217], v[68:71]
	v_mfma_f32_16x16x32_bf16 v[84:87], v[164:167], v[206:209], v[84:87]
	v_mfma_f32_16x16x32_bf16 v[100:103], v[164:167], v[198:201], v[100:103]
	v_mfma_f32_16x16x32_bf16 v[116:119], v[164:167], v[188:191], v[116:119]
	s_setprio 0
	s_setprio 1
	v_mfma_f32_16x16x32_bf16 v[120:123], v[168:171], v[184:187], v[120:123]
	v_mfma_f32_16x16x32_bf16 v[104:107], v[168:171], v[192:195], v[104:107]
	v_mfma_f32_16x16x32_bf16 v[88:91], v[168:171], v[202:205], v[88:91]
	v_mfma_f32_16x16x32_bf16 v[72:75], v[168:171], v[210:213], v[72:75]
	v_mfma_f32_16x16x32_bf16 v[64:67], v[176:179], v[210:213], v[64:67]
	v_mfma_f32_16x16x32_bf16 v[80:83], v[176:179], v[202:205], v[80:83]
	v_mfma_f32_16x16x32_bf16 v[96:99], v[176:179], v[192:195], v[96:99]
	v_mfma_f32_16x16x32_bf16 v[112:115], v[176:179], v[184:187], v[112:115]
	v_mfma_f32_16x16x32_bf16 v[120:123], v[172:175], v[188:191], v[120:123]
	v_mfma_f32_16x16x32_bf16 v[104:107], v[172:175], v[198:201], v[104:107]
	v_mfma_f32_16x16x32_bf16 v[88:91], v[172:175], v[206:209], v[88:91]
	v_mfma_f32_16x16x32_bf16 v[72:75], v[172:175], v[214:217], v[72:75]
	v_mfma_f32_16x16x32_bf16 v[64:67], v[180:183], v[214:217], v[64:67]
	v_mfma_f32_16x16x32_bf16 v[80:83], v[180:183], v[206:209], v[80:83]
	v_mfma_f32_16x16x32_bf16 v[96:99], v[180:183], v[198:201], v[96:99]
	v_mfma_f32_16x16x32_bf16 v[112:115], v[180:183], v[188:191], v[112:115]
	s_setprio 0
	s_barrier
; #define PG8_STAGE(bufoff, gbase, voff) do { _Pragma("unroll") for (int _i = 0; _i < 2; ++_i) \
;         __builtin_amdgcn_global_load_lds((const unsigned*)((const char*)(gbase) + (voff)[_i]), (PG8_LAS unsigned*)(lds + (bufoff) + ldsw + _i * 8192), 16, 0, 0); } while (0)
; #define PG8_LDA(dst, b, h) do { _Pragma("unroll") for (int m = 0; m < 4; ++m) _Pragma("unroll") for (int k = 0; k < 2; ++k) dst[m][k] = *(const PG8_LAS bf16x8*)(lds + PG8_SA(b, h) + aoff + m * 2048 + k * 1024); } while (0)
; #define PG8_MMA(ai, bj, At, Bt) do { __builtin_amdgcn_s_setprio(1); _Pragma("unroll") for (int m = 0; m < 4; ++m) _Pragma("unroll") for (int n = 0; n < 2; ++n) _Pragma("unroll") for (int k = 0; k < 2; ++k) \
;         acc[ai][bj][m][n] = __builtin_amdgcn_mfma_f32_16x16x32_bf16(Bt[n][k], At[m][k], acc[ai][bj][m][n], 0, 0, 0); __builtin_amdgcn_s_setprio(0); } while (0)
; #define PG8_WAIT_V(n) asm volatile("s_waitcnt vmcnt(" #n ")" ::: "memory")
; #define PG8_WAIT_L(n) asm volatile("s_waitcnt lgkmcnt(" #n ")" ::: "memory")
; #define PG8_BAR __builtin_amdgcn_s_barrier()
; #define PG8_SCHED __builtin_amdgcn_sched_barrier(0)
; template <class Epi, class Sched, bool ALIGN_EPI = false, bool SP2 = false>
; __device__ __forceinline__ void gemm_phase(PG8_LAS unsigned char* lds, const Gemm g, const Sched& S, const Epi& E) {
;     ...
;         for (int t = 0; t < nt; t += 2) {
;             const bool last = (t == nt - 2);
;             const char* a1 = cA + (size_t)(t + 1) * kstep;
;             const char* a2 = last ? nA : cA + (size_t)(t + 2) * kstep; const char* b2 = last ? nB : cB + (size_t)(t + 2) * kstep;
;             const char* a3 = a2 + kstep; const char* b3 = b2 + kstep;
;     ...
;             PG8_LDA(At, 1, 1); PG8_STAGE(PG8_SB(1, 0), b3, voffB); PG8_STAGE(PG8_SB(1, 1), b3 + hstep, voffB); PG8_STAGE(PG8_SA(1, 0), a3, voffA);
;             PG8_WAIT_V(8); PG8_WAIT_L(0); PG8_BAR; PG8_MMA(1, 0, At, B0); PG8_MMA(1, 1, At, B1); PG8_BAR; PG8_SCHED;
	s_add_i32 s30, s51, s33
	v_lshl_add_u64 v[218:219], v[218:219], 0, s[12:13]
	s_mov_b32 m0, s30
	ds_read_b128 v[184:187], v155 offset:49152
	ds_read_b128 v[188:191], v155 offset:50176
	ds_read_b128 v[192:195], v155 offset:51200
	ds_read_b128 v[198:201], v155 offset:52224
	ds_read_b128 v[202:205], v155 offset:53248
	ds_read_b128 v[206:209], v155 offset:54272
	ds_read_b128 v[210:213], v155 offset:55296
	ds_read_b128 v[214:217], v155 offset:56320
	global_load_lds_dwordx4 v[218:219], off
	s_add_i32 m0, s30, 0x2000
	s_add_u32 s28, s28, 0x40080
	v_lshl_add_u64 v[218:219], v[220:221], 0, s[12:13]
	s_addc_u32 s29, s29, 0
	s_add_i32 s30, s52, s33
	global_load_lds_dwordx4 v[218:219], off
	v_lshl_add_u64 v[218:219], s[28:29], 0, v[130:131]
	s_mov_b32 m0, s30
	s_nop 0
	global_load_lds_dwordx4 v[218:219], off
	v_lshl_add_u64 v[218:219], s[28:29], 0, v[134:135]
	s_add_i32 m0, s30, 0x2000
	s_nop 0
	global_load_lds_dwordx4 v[218:219], off
	v_lshl_add_u64 v[218:219], v[222:223], 0, s[12:13]
	s_mov_b32 m0, s40
	s_nop 0
	global_load_lds_dwordx4 v[218:219], off
	v_lshl_add_u64 v[218:219], v[224:225], 0, s[12:13]
	s_mov_b32 m0, s41
	s_nop 0
	global_load_lds_dwordx4 v[218:219], off
	s_waitcnt vmcnt(8)
	s_waitcnt lgkmcnt(0)
	s_barrier
	s_setprio 1
	s_waitcnt lgkmcnt(0)
	v_mfma_f32_16x16x32_bf16 v[60:63], v[144:147], v[184:187], v[60:63]
	v_mfma_f32_16x16x32_bf16 v[44:47], v[144:147], v[192:195], v[44:47]
	v_mfma_f32_16x16x32_bf16 v[28:31], v[144:147], v[202:205], v[28:31]
	v_mfma_f32_16x16x32_bf16 v[12:15], v[144:147], v[210:213], v[12:15]
	v_mfma_f32_16x16x32_bf16 v[4:7], v[160:163], v[210:213], v[4:7]
	v_mfma_f32_16x16x32_bf16 v[20:23], v[160:163], v[202:205], v[20:23]
	v_mfma_f32_16x16x32_bf16 v[36:39], v[160:163], v[192:195], v[36:39]
	v_mfma_f32_16x16x32_bf16 v[52:55], v[160:163], v[184:187], v[52:55]
	v_mfma_f32_16x16x32_bf16 v[60:63], v[156:159], v[188:191], v[60:63]
	v_mfma_f32_16x16x32_bf16 v[44:47], v[156:159], v[198:201], v[44:47]
	v_mfma_f32_16x16x32_bf16 v[28:31], v[156:159], v[206:209], v[28:31]
	v_mfma_f32_16x16x32_bf16 v[12:15], v[156:159], v[214:217], v[12:15]
	v_mfma_f32_16x16x32_bf16 v[4:7], v[164:167], v[214:217], v[4:7]
	v_mfma_f32_16x16x32_bf16 v[20:23], v[164:167], v[206:209], v[20:23]
	v_mfma_f32_16x16x32_bf16 v[36:39], v[164:167], v[198:201], v[36:39]
	v_mfma_f32_16x16x32_bf16 v[52:55], v[164:167], v[188:191], v[52:55]
	s_setprio 0
	s_setprio 1
	v_mfma_f32_16x16x32_bf16 v[56:59], v[168:171], v[184:187], v[56:59]
	v_mfma_f32_16x16x32_bf16 v[40:43], v[168:171], v[192:195], v[40:43]
	v_mfma_f32_16x16x32_bf16 v[24:27], v[168:171], v[202:205], v[24:27]
	v_mfma_f32_16x16x32_bf16 v[8:11], v[168:171], v[210:213], v[8:11]
	v_mfma_f32_16x16x32_bf16 v[0:3], v[176:179], v[210:213], v[0:3]
	v_mfma_f32_16x16x32_bf16 v[16:19], v[176:179], v[202:205], v[16:19]
	v_mfma_f32_16x16x32_bf16 v[32:35], v[176:179], v[192:195], v[32:35]
	v_mfma_f32_16x16x32_bf16 v[48:51], v[176:179], v[184:187], v[48:51]
	v_mfma_f32_16x16x32_bf16 v[56:59], v[172:175], v[188:191], v[56:59]
	v_mfma_f32_16x16x32_bf16 v[40:43], v[172:175], v[198:201], v[40:43]
	v_mfma_f32_16x16x32_bf16 v[24:27], v[172:175], v[206:209], v[24:27]
	v_mfma_f32_16x16x32_bf16 v[8:11], v[172:175], v[214:217], v[8:11]
	v_mfma_f32_16x16x32_bf16 v[0:3], v[180:183], v[214:217], v[0:3]
	v_mfma_f32_16x16x32_bf16 v[16:19], v[180:183], v[206:209], v[16:19]
	v_mfma_f32_16x16x32_bf16 v[32:35], v[180:183], v[198:201], v[32:35]
	v_mfma_f32_16x16x32_bf16 v[48:51], v[180:183], v[188:191], v[48:51]
	s_setprio 0
	s_barrier
	s_add_i32 s50, s50, 2
	s_add_u32 s26, s26, 0x100
	s_addc_u32 s27, s27, 0
	s_add_u32 s48, s48, 0x100
	s_addc_u32 s49, s49, 0
	s_cmp_gt_u32 s50, 13
	s_cbranch_scc0 .LBB0_1146
	s_branch .Lrw2_x

; #define PG8_STAGE(bufoff, gbase, voff) do { _Pragma("unroll") for (int _i = 0; _i < 2; ++_i) \
;         __builtin_amdgcn_global_load_lds((const unsigned*)((const char*)(gbase) + (voff)[_i]), (PG8_LAS unsigned*)(lds + (bufoff) + ldsw + _i * 8192), 16, 0, 0); } while (0)
; #define PG8_LDA(dst, b, h) do { _Pragma("unroll") for (int m = 0; m < 4; ++m) _Pragma("unroll") for (int k = 0; k < 2; ++k) dst[m][k] = *(const PG8_LAS bf16x8*)(lds + PG8_SA(b, h) + aoff + m * 2048 + k * 1024); } while (0)
; #define PG8_LDB(dst, b, h) do { _Pragma("unroll") for (int n = 0; n < 2; ++n) _Pragma("unroll") for (int k = 0; k < 2; ++k) dst[n][k] = *(const PG8_LAS bf16x8*)(lds + PG8_SB(b, h) + boff + n * 2048 + k * 1024); } while (0)
; #define PG8_MMA(ai, bj, At, Bt) do { __builtin_amdgcn_s_setprio(1); _Pragma("unroll") for (int m = 0; m < 4; ++m) _Pragma("unroll") for (int n = 0; n < 2; ++n) _Pragma("unroll") for (int k = 0; k < 2; ++k) \
;         acc[ai][bj][m][n] = __builtin_amdgcn_mfma_f32_16x16x32_bf16(Bt[n][k], At[m][k], acc[ai][bj][m][n], 0, 0, 0); __builtin_amdgcn_s_setprio(0); } while (0)
; #define PG8_WAIT_V(n) asm volatile("s_waitcnt vmcnt(" #n ")" ::: "memory")
; #define PG8_WAIT_L(n) asm volatile("s_waitcnt lgkmcnt(" #n ")" ::: "memory")
; #define PG8_BAR __builtin_amdgcn_s_barrier()
; #define PG8_SCHED __builtin_amdgcn_sched_barrier(0)
; template <class Epi, class Sched, bool ALIGN_EPI = false, bool SP2 = false>
; __device__ __forceinline__ void gemm_phase(PG8_LAS unsigned char* lds, const Gemm g, const Sched& S, const Epi& E) {
;     ...
;             PG8_LDB(B0, 0, 0); PG8_LDB(B1, 0, 1); PG8_SCHED; PG8_LDA(At, 0, 0); PG8_STAGE(PG8_SA(1, 1), a1 + hstep, voffA);
;             PG8_WAIT_V(8); PG8_WAIT_L(0); PG8_BAR; PG8_MMA(0, 0, At, B0); PG8_MMA(0, 1, At, B1); PG8_BAR; PG8_SCHED;
;             PG8_LDA(At, 0, 1); PG8_STAGE(PG8_SB(0, 0), b2, voffB); PG8_STAGE(PG8_SB(0, 1), b2 + hstep, voffB); PG8_STAGE(PG8_SA(0, 0), a2, voffA);
;             PG8_WAIT_V(8); PG8_WAIT_L(0); PG8_BAR; PG8_MMA(1, 0, At, B0); PG8_MMA(1, 1, At, B1); PG8_BAR; PG8_SCHED;
.Lrw4_b0:
	s_waitcnt lgkmcnt(0)
	s_barrier
	s_setprio 1
	s_waitcnt lgkmcnt(0)
	v_mfma_f32_16x16x32_bf16 v[124:127], v[144:147], v[184:187], v[124:127]
	v_mfma_f32_16x16x32_bf16 v[108:111], v[144:147], v[192:195], v[108:111]
	v_mfma_f32_16x16x32_bf16 v[92:95], v[144:147], v[202:205], v[92:95]
	v_mfma_f32_16x16x32_bf16 v[76:79], v[144:147], v[210:213], v[76:79]
	v_mfma_f32_16x16x32_bf16 v[72:75], v[160:163], v[210:213], v[72:75]
	v_mfma_f32_16x16x32_bf16 v[88:91], v[160:163], v[202:205], v[88:91]
	v_mfma_f32_16x16x32_bf16 v[104:107], v[160:163], v[192:195], v[104:107]
	v_mfma_f32_16x16x32_bf16 v[120:123], v[160:163], v[184:187], v[120:123]
	v_mfma_f32_16x16x32_bf16 v[124:127], v[156:159], v[188:191], v[124:127]
	v_mfma_f32_16x16x32_bf16 v[108:111], v[156:159], v[198:201], v[108:111]
	v_mfma_f32_16x16x32_bf16 v[92:95], v[156:159], v[206:209], v[92:95]
	v_mfma_f32_16x16x32_bf16 v[76:79], v[156:159], v[214:217], v[76:79]
	v_mfma_f32_16x16x32_bf16 v[72:75], v[164:167], v[214:217], v[72:75]
	v_mfma_f32_16x16x32_bf16 v[88:91], v[164:167], v[206:209], v[88:91]
	v_mfma_f32_16x16x32_bf16 v[104:107], v[164:167], v[198:201], v[104:107]
	v_mfma_f32_16x16x32_bf16 v[120:123], v[164:167], v[188:191], v[120:123]
	s_setprio 0
	s_setprio 1
	v_mfma_f32_16x16x32_bf16 v[116:119], v[168:171], v[184:187], v[116:119]
	v_mfma_f32_16x16x32_bf16 v[100:103], v[168:171], v[192:195], v[100:103]
	v_mfma_f32_16x16x32_bf16 v[84:87], v[168:171], v[202:205], v[84:87]
	v_mfma_f32_16x16x32_bf16 v[68:71], v[168:171], v[210:213], v[68:71]
	v_mfma_f32_16x16x32_bf16 v[64:67], v[176:179], v[210:213], v[64:67]
	v_mfma_f32_16x16x32_bf16 v[80:83], v[176:179], v[202:205], v[80:83]
	v_mfma_f32_16x16x32_bf16 v[96:99], v[176:179], v[192:195], v[96:99]
	v_mfma_f32_16x16x32_bf16 v[112:115], v[176:179], v[184:187], v[112:115]
	v_mfma_f32_16x16x32_bf16 v[116:119], v[172:175], v[188:191], v[116:119]
	v_mfma_f32_16x16x32_bf16 v[100:103], v[172:175], v[198:201], v[100:103]
	v_mfma_f32_16x16x32_bf16 v[84:87], v[172:175], v[206:209], v[84:87]
	v_mfma_f32_16x16x32_bf16 v[68:71], v[172:175], v[214:217], v[68:71]
	v_mfma_f32_16x16x32_bf16 v[64:67], v[180:183], v[214:217], v[64:67]
	v_mfma_f32_16x16x32_bf16 v[80:83], v[180:183], v[206:209], v[80:83]
	v_mfma_f32_16x16x32_bf16 v[96:99], v[180:183], v[198:201], v[96:99]
	v_mfma_f32_16x16x32_bf16 v[112:115], v[180:183], v[188:191], v[112:115]
	s_setprio 0
	s_barrier
	s_add_i32 s45, s36, s24
	v_lshl_add_u64 v[218:219], s[20:21], 0, v[130:131]
	s_mov_b32 m0, s45
	ds_read_b128 v[184:187], v153 offset:16384
	ds_read_b128 v[188:191], v153 offset:17408
	ds_read_b128 v[192:195], v153 offset:18432
	ds_read_b128 v[198:201], v153 offset:19456
	ds_read_b128 v[202:205], v153 offset:20480
	ds_read_b128 v[206:209], v153 offset:21504
	ds_read_b128 v[210:213], v153 offset:22528
	ds_read_b128 v[214:217], v153 offset:23552
	global_load_lds_dwordx4 v[218:219], off
	s_add_i32 m0, s45, 0x2000
	s_add_u32 s46, s20, 0xb0000
	v_lshl_add_u64 v[220:221], s[20:21], 0, v[134:135]
	s_addc_u32 s47, s21, 0
	s_add_i32 s45, s37, s24
	global_load_lds_dwordx4 v[220:221], off
	v_lshl_add_u64 v[222:223], s[46:47], 0, v[130:131]
	s_mov_b32 m0, s45
	v_lshl_add_u64 v[224:225], s[22:23], 0, v[132:133]
	global_load_lds_dwordx4 v[222:223], off
	v_lshl_add_u64 v[222:223], s[46:47], 0, v[134:135]
	s_add_i32 m0, s45, 0x2000
	s_nop 0
	global_load_lds_dwordx4 v[222:223], off
	v_lshl_add_u64 v[222:223], s[22:23], 0, v[128:129]
	s_mov_b32 m0, s25
	s_nop 0
	global_load_lds_dwordx4 v[222:223], off
	s_mov_b32 m0, s26
	s_nop 0
	global_load_lds_dwordx4 v[224:225], off
	s_cmp_eq_u32 s44, s101
	s_cbranch_scc1 .Lrw4_r1
	s_waitcnt vmcnt(8)
.Lrw4_b1:
	s_waitcnt lgkmcnt(0)
	s_barrier
	s_setprio 1
	s_waitcnt lgkmcnt(0)
	v_mfma_f32_16x16x32_bf16 v[60:63], v[144:147], v[184:187], v[60:63]
	v_mfma_f32_16x16x32_bf16 v[44:47], v[144:147], v[192:195], v[44:47]
	v_mfma_f32_16x16x32_bf16 v[28:31], v[144:147], v[202:205], v[28:31]
	v_mfma_f32_16x16x32_bf16 v[12:15], v[144:147], v[210:213], v[12:15]
	v_mfma_f32_16x16x32_bf16 v[8:11], v[160:163], v[210:213], v[8:11]
	v_mfma_f32_16x16x32_bf16 v[24:27], v[160:163], v[202:205], v[24:27]
	v_mfma_f32_16x16x32_bf16 v[40:43], v[160:163], v[192:195], v[40:43]
	v_mfma_f32_16x16x32_bf16 v[56:59], v[160:163], v[184:187], v[56:59]
	v_mfma_f32_16x16x32_bf16 v[60:63], v[156:159], v[188:191], v[60:63]
	v_mfma_f32_16x16x32_bf16 v[44:47], v[156:159], v[198:201], v[44:47]
	v_mfma_f32_16x16x32_bf16 v[28:31], v[156:159], v[206:209], v[28:31]
	v_mfma_f32_16x16x32_bf16 v[12:15], v[156:159], v[214:217], v[12:15]
	v_mfma_f32_16x16x32_bf16 v[8:11], v[164:167], v[214:217], v[8:11]
	v_mfma_f32_16x16x32_bf16 v[24:27], v[164:167], v[206:209], v[24:27]
	v_mfma_f32_16x16x32_bf16 v[40:43], v[164:167], v[198:201], v[40:43]
	v_mfma_f32_16x16x32_bf16 v[56:59], v[164:167], v[188:191], v[56:59]
	s_setprio 0
	s_setprio 1
	v_mfma_f32_16x16x32_bf16 v[52:55], v[168:171], v[184:187], v[52:55]
	v_mfma_f32_16x16x32_bf16 v[36:39], v[168:171], v[192:195], v[36:39]
	v_mfma_f32_16x16x32_bf16 v[20:23], v[168:171], v[202:205], v[20:23]
	v_mfma_f32_16x16x32_bf16 v[4:7], v[168:171], v[210:213], v[4:7]
	v_mfma_f32_16x16x32_bf16 v[0:3], v[176:179], v[210:213], v[0:3]
	v_mfma_f32_16x16x32_bf16 v[16:19], v[176:179], v[202:205], v[16:19]
	v_mfma_f32_16x16x32_bf16 v[32:35], v[176:179], v[192:195], v[32:35]
	v_mfma_f32_16x16x32_bf16 v[48:51], v[176:179], v[184:187], v[48:51]
	v_mfma_f32_16x16x32_bf16 v[52:55], v[172:175], v[188:191], v[52:55]
	v_mfma_f32_16x16x32_bf16 v[36:39], v[172:175], v[198:201], v[36:39]
	v_mfma_f32_16x16x32_bf16 v[20:23], v[172:175], v[206:209], v[20:23]
	v_mfma_f32_16x16x32_bf16 v[4:7], v[172:175], v[214:217], v[4:7]
	v_mfma_f32_16x16x32_bf16 v[0:3], v[180:183], v[214:217], v[0:3]
	v_mfma_f32_16x16x32_bf16 v[16:19], v[180:183], v[206:209], v[16:19]
	v_mfma_f32_16x16x32_bf16 v[32:35], v[180:183], v[198:201], v[32:35]
	v_mfma_f32_16x16x32_bf16 v[48:51], v[180:183], v[188:191], v[48:51]
	s_setprio 0
	s_barrier
; #define PG8_STAGE(bufoff, gbase, voff) do { _Pragma("unroll") for (int _i = 0; _i < 2; ++_i) \
;         __builtin_amdgcn_global_load_lds((const unsigned*)((const char*)(gbase) + (voff)[_i]), (PG8_LAS unsigned*)(lds + (bufoff) + ldsw + _i * 8192), 16, 0, 0); } while (0)
; #define PG8_LDA(dst, b, h) do { _Pragma("unroll") for (int m = 0; m < 4; ++m) _Pragma("unroll") for (int k = 0; k < 2; ++k) dst[m][k] = *(const PG8_LAS bf16x8*)(lds + PG8_SA(b, h) + aoff + m * 2048 + k * 1024); } while (0)
; #define PG8_LDB(dst, b, h) do { _Pragma("unroll") for (int n = 0; n < 2; ++n) _Pragma("unroll") for (int k = 0; k < 2; ++k) dst[n][k] = *(const PG8_LAS bf16x8*)(lds + PG8_SB(b, h) + boff + n * 2048 + k * 1024); } while (0)
; #define PG8_MMA(ai, bj, At, Bt) do { __builtin_amdgcn_s_setprio(1); _Pragma("unroll") for (int m = 0; m < 4; ++m) _Pragma("unroll") for (int n = 0; n < 2; ++n) _Pragma("unroll") for (int k = 0; k < 2; ++k) \
;         acc[ai][bj][m][n] = __builtin_amdgcn_mfma_f32_16x16x32_bf16(Bt[n][k], At[m][k], acc[ai][bj][m][n], 0, 0, 0); __builtin_amdgcn_s_setprio(0); } while (0)
; #define PG8_WAIT_V(n) asm volatile("s_waitcnt vmcnt(" #n ")" ::: "memory")
; #define PG8_WAIT_L(n) asm volatile("s_waitcnt lgkmcnt(" #n ")" ::: "memory")
; #define PG8_BAR __builtin_amdgcn_s_barrier()
; #define PG8_SCHED __builtin_amdgcn_sched_barrier(0)
; template <class Epi, class Sched, bool ALIGN_EPI = false, bool SP2 = false>
; __device__ __forceinline__ void gemm_phase(PG8_LAS unsigned char* lds, const Gemm g, const Sched& S, const Epi& E) {
;     ...
;             PG8_LDB(B0, 1, 0); PG8_LDB(B1, 1, 1); PG8_SCHED; PG8_LDA(At, 1, 0); PG8_STAGE(PG8_SA(0, 1), a2 + hstep, voffA);
;             PG8_WAIT_V(8); PG8_WAIT_L(0); PG8_BAR; PG8_MMA(0, 0, At, B0); PG8_MMA(0, 1, At, B1); PG8_BAR; PG8_SCHED;
	s_add_i32 s45, 0, 0x18000
	v_add_u32_e32 v155, s45, v149
	s_add_i32 s46, 0, 0x1c000
	ds_read_b128 v[144:147], v155
	ds_read_b128 v[156:159], v155 offset:1024
	ds_read_b128 v[160:163], v155 offset:2048
	ds_read_b128 v[164:167], v155 offset:3072
	v_add_u32_e32 v155, s46, v149
	ds_read_b128 v[168:171], v155
	ds_read_b128 v[172:175], v155 offset:1024
	ds_read_b128 v[176:179], v155 offset:2048
	ds_read_b128 v[180:183], v155 offset:3072
	s_add_u32 s22, s22, 0xb0000
	s_addc_u32 s23, s23, 0
	s_mov_b32 m0, s27
	v_lshl_add_u64 v[226:227], s[22:23], 0, v[128:129]
	ds_read_b128 v[184:187], v153 offset:32768
	ds_read_b128 v[188:191], v153 offset:33792
	ds_read_b128 v[192:195], v153 offset:34816
	ds_read_b128 v[198:201], v153 offset:35840
	ds_read_b128 v[202:205], v153 offset:36864
	ds_read_b128 v[206:209], v153 offset:37888
	ds_read_b128 v[210:213], v153 offset:38912
	ds_read_b128 v[214:217], v153 offset:39936
	global_load_lds_dwordx4 v[226:227], off
	v_lshl_add_u64 v[226:227], s[22:23], 0, v[132:133]
	s_mov_b32 m0, s28
	s_nop 0
	global_load_lds_dwordx4 v[226:227], off
	s_waitcnt vmcnt(8)
	s_waitcnt lgkmcnt(0)
	s_barrier
	s_setprio 1
	s_waitcnt lgkmcnt(0)
	v_mfma_f32_16x16x32_bf16 v[124:127], v[144:147], v[184:187], v[124:127]
	v_mfma_f32_16x16x32_bf16 v[108:111], v[144:147], v[192:195], v[108:111]
	v_mfma_f32_16x16x32_bf16 v[92:95], v[144:147], v[202:205], v[92:95]
	v_mfma_f32_16x16x32_bf16 v[76:79], v[144:147], v[210:213], v[76:79]
	v_mfma_f32_16x16x32_bf16 v[72:75], v[160:163], v[210:213], v[72:75]
	v_mfma_f32_16x16x32_bf16 v[88:91], v[160:163], v[202:205], v[88:91]
	v_mfma_f32_16x16x32_bf16 v[104:107], v[160:163], v[192:195], v[104:107]
	v_mfma_f32_16x16x32_bf16 v[120:123], v[160:163], v[184:187], v[120:123]
	v_mfma_f32_16x16x32_bf16 v[124:127], v[156:159], v[188:191], v[124:127]
	v_mfma_f32_16x16x32_bf16 v[108:111], v[156:159], v[198:201], v[108:111]
	v_mfma_f32_16x16x32_bf16 v[92:95], v[156:159], v[206:209], v[92:95]
	v_mfma_f32_16x16x32_bf16 v[76:79], v[156:159], v[214:217], v[76:79]
	v_mfma_f32_16x16x32_bf16 v[72:75], v[164:167], v[214:217], v[72:75]
	v_mfma_f32_16x16x32_bf16 v[88:91], v[164:167], v[206:209], v[88:91]
	v_mfma_f32_16x16x32_bf16 v[104:107], v[164:167], v[198:201], v[104:107]
	v_mfma_f32_16x16x32_bf16 v[120:123], v[164:167], v[188:191], v[120:123]
	s_setprio 0
	s_setprio 1
	v_mfma_f32_16x16x32_bf16 v[116:119], v[168:171], v[184:187], v[116:119]
	v_mfma_f32_16x16x32_bf16 v[100:103], v[168:171], v[192:195], v[100:103]
	v_mfma_f32_16x16x32_bf16 v[84:87], v[168:171], v[202:205], v[84:87]
	v_mfma_f32_16x16x32_bf16 v[68:71], v[168:171], v[210:213], v[68:71]
	v_mfma_f32_16x16x32_bf16 v[64:67], v[176:179], v[210:213], v[64:67]
	v_mfma_f32_16x16x32_bf16 v[80:83], v[176:179], v[202:205], v[80:83]
	v_mfma_f32_16x16x32_bf16 v[96:99], v[176:179], v[192:195], v[96:99]
	v_mfma_f32_16x16x32_bf16 v[112:115], v[176:179], v[184:187], v[112:115]
	v_mfma_f32_16x16x32_bf16 v[116:119], v[172:175], v[188:191], v[116:119]
	v_mfma_f32_16x16x32_bf16 v[100:103], v[172:175], v[198:201], v[100:103]
	v_mfma_f32_16x16x32_bf16 v[84:87], v[172:175], v[206:209], v[84:87]
	v_mfma_f32_16x16x32_bf16 v[68:71], v[172:175], v[214:217], v[68:71]
	v_mfma_f32_16x16x32_bf16 v[64:67], v[180:183], v[214:217], v[64:67]
	v_mfma_f32_16x16x32_bf16 v[80:83], v[180:183], v[206:209], v[80:83]
	v_mfma_f32_16x16x32_bf16 v[96:99], v[180:183], v[198:201], v[96:99]
	v_mfma_f32_16x16x32_bf16 v[112:115], v[180:183], v[188:191], v[112:115]
	s_setprio 0
	s_barrier
; #define PG8_STAGE(bufoff, gbase, voff) do { _Pragma("unroll") for (int _i = 0; _i < 2; ++_i) \
;         __builtin_amdgcn_global_load_lds((const unsigned*)((const char*)(gbase) + (voff)[_i]), (PG8_LAS unsigned*)(lds + (bufoff) + ldsw + _i * 8192), 16, 0, 0); } while (0)
; #define PG8_LDA(dst, b, h) do { _Pragma("unroll") for (int m = 0; m < 4; ++m) _Pragma("unroll") for (int k = 0; k < 2; ++k) dst[m][k] = *(const PG8_LAS bf16x8*)(lds + PG8_SA(b, h) + aoff + m * 2048 + k * 1024); } while (0)
; #define PG8_MMA(ai, bj, At, Bt) do { __builtin_amdgcn_s_setprio(1); _Pragma("unroll") for (int m = 0; m < 4; ++m) _Pragma("unroll") for (int n = 0; n < 2; ++n) _Pragma("unroll") for (int k = 0; k < 2; ++k) \
;         acc[ai][bj][m][n] = __builtin_amdgcn_mfma_f32_16x16x32_bf16(Bt[n][k], At[m][k], acc[ai][bj][m][n], 0, 0, 0); __builtin_amdgcn_s_setprio(0); } while (0)
; #define PG8_WAIT_V(n) asm volatile("s_waitcnt vmcnt(" #n ")" ::: "memory")
; #define PG8_WAIT_L(n) asm volatile("s_waitcnt lgkmcnt(" #n ")" ::: "memory")
; #define PG8_BAR __builtin_amdgcn_s_barrier()
; #define PG8_SCHED __builtin_amdgcn_sched_barrier(0)
; template <class Epi, class Sched, bool ALIGN_EPI = false, bool SP2 = false>
; __device__ __forceinline__ void gemm_phase(PG8_LAS unsigned char* lds, const Gemm g, const Sched& S, const Epi& E) {
;     ...
;         for (int t = 0; t < nt; t += 2) {
;             const bool last = (t == nt - 2);
;             const char* a1 = cA + (size_t)(t + 1) * kstep;
;             const char* a2 = last ? nA : cA + (size_t)(t + 2) * kstep; const char* b2 = last ? nB : cB + (size_t)(t + 2) * kstep;
;             const char* a3 = a2 + kstep; const char* b3 = b2 + kstep;
;     ...
;             PG8_LDA(At, 1, 1); PG8_STAGE(PG8_SB(1, 0), b3, voffB); PG8_STAGE(PG8_SB(1, 1), b3 + hstep, voffB); PG8_STAGE(PG8_SA(1, 0), a3, voffA);
;             PG8_WAIT_V(8); PG8_WAIT_L(0); PG8_BAR; PG8_MMA(1, 0, At, B0); PG8_MMA(1, 1, At, B1); PG8_BAR; PG8_SCHED;
	s_add_i32 s22, s45, s24
	v_lshl_add_u64 v[218:219], v[218:219], 0, s[12:13]
	s_mov_b32 m0, s22
	ds_read_b128 v[184:187], v153 offset:49152
	ds_read_b128 v[188:191], v153 offset:50176
	ds_read_b128 v[192:195], v153 offset:51200
	ds_read_b128 v[198:201], v153 offset:52224
	ds_read_b128 v[202:205], v153 offset:53248
	ds_read_b128 v[206:209], v153 offset:54272
	ds_read_b128 v[210:213], v153 offset:55296
	ds_read_b128 v[214:217], v153 offset:56320
	global_load_lds_dwordx4 v[218:219], off
	s_add_i32 m0, s22, 0x2000
	s_add_u32 s20, s20, 0xb0080
	v_lshl_add_u64 v[218:219], v[220:221], 0, s[12:13]
	s_addc_u32 s21, s21, 0
	s_add_i32 s22, s46, s24
	global_load_lds_dwordx4 v[218:219], off
	v_lshl_add_u64 v[218:219], s[20:21], 0, v[130:131]
	s_mov_b32 m0, s22
	s_nop 0
	global_load_lds_dwordx4 v[218:219], off
	v_lshl_add_u64 v[218:219], s[20:21], 0, v[134:135]
	s_add_i32 m0, s22, 0x2000
	s_nop 0
	global_load_lds_dwordx4 v[218:219], off
	v_lshl_add_u64 v[218:219], v[222:223], 0, s[12:13]
	s_mov_b32 m0, s33
	s_nop 0
	global_load_lds_dwordx4 v[218:219], off
	v_lshl_add_u64 v[218:219], v[224:225], 0, s[12:13]
	s_mov_b32 m0, s34
	s_nop 0
	global_load_lds_dwordx4 v[218:219], off
	s_waitcnt vmcnt(8)
	s_waitcnt lgkmcnt(0)
	s_barrier
	s_setprio 1
	s_waitcnt lgkmcnt(0)
	v_mfma_f32_16x16x32_bf16 v[60:63], v[144:147], v[184:187], v[60:63]
	v_mfma_f32_16x16x32_bf16 v[44:47], v[144:147], v[192:195], v[44:47]
	v_mfma_f32_16x16x32_bf16 v[28:31], v[144:147], v[202:205], v[28:31]
	v_mfma_f32_16x16x32_bf16 v[12:15], v[144:147], v[210:213], v[12:15]
	v_mfma_f32_16x16x32_bf16 v[8:11], v[160:163], v[210:213], v[8:11]
	v_mfma_f32_16x16x32_bf16 v[24:27], v[160:163], v[202:205], v[24:27]
	v_mfma_f32_16x16x32_bf16 v[40:43], v[160:163], v[192:195], v[40:43]
	v_mfma_f32_16x16x32_bf16 v[56:59], v[160:163], v[184:187], v[56:59]
	v_mfma_f32_16x16x32_bf16 v[60:63], v[156:159], v[188:191], v[60:63]
	v_mfma_f32_16x16x32_bf16 v[44:47], v[156:159], v[198:201], v[44:47]
	v_mfma_f32_16x16x32_bf16 v[28:31], v[156:159], v[206:209], v[28:31]
	v_mfma_f32_16x16x32_bf16 v[12:15], v[156:159], v[214:217], v[12:15]
	v_mfma_f32_16x16x32_bf16 v[8:11], v[164:167], v[214:217], v[8:11]
	v_mfma_f32_16x16x32_bf16 v[24:27], v[164:167], v[206:209], v[24:27]
	v_mfma_f32_16x16x32_bf16 v[40:43], v[164:167], v[198:201], v[40:43]
	v_mfma_f32_16x16x32_bf16 v[56:59], v[164:167], v[188:191], v[56:59]
	s_setprio 0
	s_setprio 1
	v_mfma_f32_16x16x32_bf16 v[52:55], v[168:171], v[184:187], v[52:55]
	v_mfma_f32_16x16x32_bf16 v[36:39], v[168:171], v[192:195], v[36:39]
	v_mfma_f32_16x16x32_bf16 v[20:23], v[168:171], v[202:205], v[20:23]
	v_mfma_f32_16x16x32_bf16 v[4:7], v[168:171], v[210:213], v[4:7]
	v_mfma_f32_16x16x32_bf16 v[0:3], v[176:179], v[210:213], v[0:3]
	v_mfma_f32_16x16x32_bf16 v[16:19], v[176:179], v[202:205], v[16:19]
	v_mfma_f32_16x16x32_bf16 v[32:35], v[176:179], v[192:195], v[32:35]
	v_mfma_f32_16x16x32_bf16 v[48:51], v[176:179], v[184:187], v[48:51]
	v_mfma_f32_16x16x32_bf16 v[52:55], v[172:175], v[188:191], v[52:55]
	v_mfma_f32_16x16x32_bf16 v[36:39], v[172:175], v[198:201], v[36:39]
	v_mfma_f32_16x16x32_bf16 v[20:23], v[172:175], v[206:209], v[20:23]
	v_mfma_f32_16x16x32_bf16 v[4:7], v[172:175], v[214:217], v[4:7]
	v_mfma_f32_16x16x32_bf16 v[0:3], v[180:183], v[214:217], v[0:3]
	v_mfma_f32_16x16x32_bf16 v[16:19], v[180:183], v[206:209], v[16:19]
	v_mfma_f32_16x16x32_bf16 v[32:35], v[180:183], v[198:201], v[32:35]
	v_mfma_f32_16x16x32_bf16 v[48:51], v[180:183], v[188:191], v[48:51]
	s_setprio 0
	s_barrier
	s_add_i32 s44, s44, 2
	s_add_u32 s18, s18, 0x100
	s_addc_u32 s19, s19, 0
	s_add_u32 s42, s42, 0x100
	s_addc_u32 s43, s43, 0
	s_cmp_gt_u32 s44, 41
	s_cbranch_scc0 .LBB0_1239
	s_branch .Lrw4_x
